# GEMM mainloops: LDS-DMA loads with scalar base + 32-bit lane offset use the saddr form of global_load_lds; 42 64-bit VALU address adds removed from the load parts
# speedup vs baseline: 1.0090x; 1.0049x over previous
; #define PG8_STAGE(bufoff, gbase, voff) do { _Pragma("unroll") for (int _i = 0; _i < 2; ++_i) \
;         __builtin_amdgcn_global_load_lds((const unsigned*)((const char*)(gbase) + (voff)[_i]), (LAS unsigned*)(lds + (bufoff) + ldsw + _i * 8192), 16, 0, 0); } while (0)
; #define PG8_LDA(dst, b, h) do { _Pragma("unroll") for (int m = 0; m < 4; ++m) _Pragma("unroll") for (int k = 0; k < 2; ++k) dst[m][k] = *(const LAS bf16x8*)(lds + PG8_SA(b, h) + aoff + m * 2048 + k * 1024); } while (0)
; #define PG8_LDB(dst, b, h) do { _Pragma("unroll") for (int n = 0; n < 2; ++n) _Pragma("unroll") for (int k = 0; k < 2; ++k) dst[n][k] = *(const LAS bf16x8*)(lds + PG8_SB(b, h) + boff + n * 2048 + k * 1024); } while (0)
; #define PG8_MMA(ai, bj, At, Bt) do { __builtin_amdgcn_s_setprio(1); _Pragma("unroll") for (int m = 0; m < 4; ++m) _Pragma("unroll") for (int n = 0; n < 2; ++n) _Pragma("unroll") for (int k = 0; k < 2; ++k) \
;         acc[ai][bj][m][n] = __builtin_amdgcn_mfma_f32_16x16x32_bf16(Bt[n][k], At[m][k], acc[ai][bj][m][n], 0, 0, 0); __builtin_amdgcn_s_setprio(0); } while (0)
; #define PG8_WAIT_V(n) asm volatile("s_waitcnt vmcnt(" #n ")" ::: "memory")
; #define PG8_WAIT_L(n) asm volatile("s_waitcnt lgkmcnt(" #n ")" ::: "memory")
; #define PG8_BAR __builtin_amdgcn_s_barrier()
; template <class Epi>
; __device__ __forceinline__ void gemm_phase(LAS unsigned char* lds, const Gemm g, const StaticOrder& S, const Epi& E, const int tid) {
;     ...
;             const bool last = (t == nt - 2);
;             const char* a1 = cA + (size_t)(t + 1) * kstep;
;             const char* a2 = last ? nA : cA + (size_t)(t + 2) * kstep; const char* b2 = last ? nB : cB + (size_t)(t + 2) * kstep;
;             const char* a3 = a2 + kstep; const char* b3 = b2 + kstep;
;             PG8_LDB(B0, 0, 0); PG8_SCHED; PG8_LDA(At, 0, 0); PG8_STAGE(PG8_SA(1, 1), a1 + hstep, voffA);
;             PG8_WAIT_L(8); PG8_BAR; PG8_WAIT_L(0); PG8_MMA(0, 0, At, B0); PG8_BAR; PG8_SCHED;
;             PG8_LDB(B1, 0, 1); PG8_STAGE(PG8_SB(0, 0), b2, voffB);
;             PG8_BAR; PG8_WAIT_L(0); PG8_MMA(0, 1, At, B1); PG8_BAR;
;             PG8_LDA(At, 0, 1); PG8_STAGE(PG8_SA(0, 0), a2, voffA);
;             PG8_BAR; PG8_WAIT_L(0); PG8_MMA(1, 0, At, B0); PG8_BAR; PG8_SCHED;
;             PG8_STAGE(PG8_SB(0, 1), b2 + hstep, voffB);
;             PG8_WAIT_V(6); PG8_BAR; PG8_MMA(1, 1, At, B1); PG8_BAR;
.Lgprio0:
.LBB0_40:
	s_add_u32 s20, s18, 0xffe00080
	s_addc_u32 s21, s19, -1
	s_add_i32 s50, 0, 0x10000
	v_add_u32_e32 v70, s50, v173
	ds_read_b128 v[50:53], v70
	ds_read_b128 v[54:57], v70 offset:1024
	ds_read_b128 v[66:69], v70 offset:2048
	ds_read_b128 v[70:73], v70 offset:3072
	s_cmpk_eq_i32 s49, 0x7c
	s_cselect_b32 s23, s13, s21
	s_cselect_b32 s22, s44, s20
	s_cselect_b32 s21, s11, s48
	s_cselect_b32 s20, s45, s47
	s_add_i32 m0, s3, 0xc000
	ds_read_b128 v[176:179], v174
	ds_read_b128 v[180:183], v174 offset:1024
	ds_read_b128 v[184:187], v174 offset:2048
	ds_read_b128 v[188:191], v174 offset:3072
	ds_read_b128 v[192:195], v174 offset:4096
	ds_read_b128 v[196:199], v174 offset:5120
	ds_read_b128 v[210:213], v174 offset:6144
	ds_read_b128 v[214:217], v174 offset:7168
	global_load_lds_dwordx4 v168, s[18:19]
	v_lshl_add_u64 v[170:171], s[18:19], 0, v[166:167]
	s_add_i32 m0, s3, 0xe000
	s_nop 0
	global_load_lds_dwordx4 v[170:171], off
	s_waitcnt lgkmcnt(8)
	s_barrier
	s_waitcnt lgkmcnt(0)
	v_mfma_f32_16x16x32_bf16 v[142:145], v[50:53], v[176:179], v[142:145]
	v_mfma_f32_16x16x32_bf16 v[138:141], v[66:69], v[176:179], v[138:141]
	v_mfma_f32_16x16x32_bf16 v[126:129], v[50:53], v[184:187], v[126:129]
	v_mfma_f32_16x16x32_bf16 v[122:125], v[66:69], v[184:187], v[122:125]
	v_mfma_f32_16x16x32_bf16 v[110:113], v[50:53], v[192:195], v[110:113]
	v_mfma_f32_16x16x32_bf16 v[106:109], v[66:69], v[192:195], v[106:109]
	v_mfma_f32_16x16x32_bf16 v[94:97], v[50:53], v[210:213], v[94:97]
	v_mfma_f32_16x16x32_bf16 v[90:93], v[66:69], v[210:213], v[90:93]
	v_mfma_f32_16x16x32_bf16 v[142:145], v[54:57], v[180:183], v[142:145]
	v_mfma_f32_16x16x32_bf16 v[138:141], v[70:73], v[180:183], v[138:141]
	v_mfma_f32_16x16x32_bf16 v[126:129], v[54:57], v[188:191], v[126:129]
	v_mfma_f32_16x16x32_bf16 v[122:125], v[70:73], v[188:191], v[122:125]
	v_mfma_f32_16x16x32_bf16 v[110:113], v[54:57], v[196:199], v[110:113]
	v_mfma_f32_16x16x32_bf16 v[106:109], v[70:73], v[196:199], v[106:109]
	v_mfma_f32_16x16x32_bf16 v[94:97], v[54:57], v[214:217], v[94:97]
	v_mfma_f32_16x16x32_bf16 v[90:93], v[70:73], v[214:217], v[90:93]
	s_barrier
	s_add_i32 s54, 0, 0x14000
	v_add_u32_e32 v170, s54, v173
	s_add_i32 s50, s50, s31
	ds_read_b128 v[218:221], v170
	ds_read_b128 v[222:225], v170 offset:1024
	ds_read_b128 v[226:229], v170 offset:2048
	ds_read_b128 v[230:233], v170 offset:3072
	v_lshl_add_u64 v[170:171], s[20:21], 0, v[0:1]
	s_mov_b32 m0, s50
	v_lshl_add_u64 v[200:201], s[20:21], 0, v[164:165]
	global_load_lds_dwordx4 v[170:171], off
	s_add_i32 m0, s50, 0x2000
	s_nop 0
	global_load_lds_dwordx4 v[200:201], off
	s_barrier
	s_waitcnt lgkmcnt(0)
	v_mfma_f32_16x16x32_bf16 v[134:137], v[218:221], v[176:179], v[134:137]
	v_mfma_f32_16x16x32_bf16 v[130:133], v[226:229], v[176:179], v[130:133]
	v_mfma_f32_16x16x32_bf16 v[118:121], v[218:221], v[184:187], v[118:121]
	v_mfma_f32_16x16x32_bf16 v[114:117], v[226:229], v[184:187], v[114:117]
	v_mfma_f32_16x16x32_bf16 v[102:105], v[218:221], v[192:195], v[102:105]
	v_mfma_f32_16x16x32_bf16 v[98:101], v[226:229], v[192:195], v[98:101]
	v_mfma_f32_16x16x32_bf16 v[86:89], v[218:221], v[210:213], v[86:89]
	v_mfma_f32_16x16x32_bf16 v[82:85], v[226:229], v[210:213], v[82:85]
	v_mfma_f32_16x16x32_bf16 v[134:137], v[222:225], v[180:183], v[134:137]
	v_mfma_f32_16x16x32_bf16 v[130:133], v[230:233], v[180:183], v[130:133]
	v_mfma_f32_16x16x32_bf16 v[118:121], v[222:225], v[188:191], v[118:121]
	v_mfma_f32_16x16x32_bf16 v[114:117], v[230:233], v[188:191], v[114:117]
	v_mfma_f32_16x16x32_bf16 v[102:105], v[222:225], v[196:199], v[102:105]
	v_mfma_f32_16x16x32_bf16 v[98:101], v[230:233], v[196:199], v[98:101]
	v_mfma_f32_16x16x32_bf16 v[86:89], v[222:225], v[214:217], v[86:89]
	v_mfma_f32_16x16x32_bf16 v[82:85], v[230:233], v[214:217], v[82:85]
	s_mov_b32 m0, s3
	v_lshl_add_u64 v[234:235], s[22:23], 0, v[160:161]
	s_barrier
	ds_read_b128 v[176:179], v174 offset:16384
	ds_read_b128 v[180:183], v174 offset:17408
	ds_read_b128 v[184:187], v174 offset:18432
	ds_read_b128 v[188:191], v174 offset:19456
	ds_read_b128 v[192:195], v174 offset:20480
	ds_read_b128 v[196:199], v174 offset:21504
	ds_read_b128 v[210:213], v174 offset:22528
	ds_read_b128 v[214:217], v174 offset:23552
	global_load_lds_dwordx4 v[234:235], off
	v_lshl_add_u64 v[236:237], s[22:23], 0, v[162:163]
	s_mov_b32 m0, s34
	s_nop 0
	global_load_lds_dwordx4 v[236:237], off
	s_barrier
	s_waitcnt lgkmcnt(0)
	v_mfma_f32_16x16x32_bf16 v[78:81], v[50:53], v[176:179], v[78:81]
	v_mfma_f32_16x16x32_bf16 v[74:77], v[66:69], v[176:179], v[74:77]
	v_mfma_f32_16x16x32_bf16 v[46:49], v[50:53], v[184:187], v[46:49]
	v_mfma_f32_16x16x32_bf16 v[42:45], v[66:69], v[184:187], v[42:45]
	v_mfma_f32_16x16x32_bf16 v[30:33], v[50:53], v[192:195], v[30:33]
	v_mfma_f32_16x16x32_bf16 v[26:29], v[66:69], v[192:195], v[26:29]
	v_mfma_f32_16x16x32_bf16 v[14:17], v[50:53], v[210:213], v[14:17]
	v_mfma_f32_16x16x32_bf16 v[10:13], v[66:69], v[210:213], v[10:13]
	v_mfma_f32_16x16x32_bf16 v[78:81], v[54:57], v[180:183], v[78:81]
	v_mfma_f32_16x16x32_bf16 v[74:77], v[70:73], v[180:183], v[74:77]
	v_mfma_f32_16x16x32_bf16 v[46:49], v[54:57], v[188:191], v[46:49]
	v_mfma_f32_16x16x32_bf16 v[42:45], v[70:73], v[188:191], v[42:45]
	v_mfma_f32_16x16x32_bf16 v[30:33], v[54:57], v[196:199], v[30:33]
	v_mfma_f32_16x16x32_bf16 v[26:29], v[70:73], v[196:199], v[26:29]
	v_mfma_f32_16x16x32_bf16 v[14:17], v[54:57], v[214:217], v[14:17]
	v_mfma_f32_16x16x32_bf16 v[10:13], v[70:73], v[214:217], v[10:13]
	s_barrier
	s_add_u32 s52, s20, 0x200000
	s_addc_u32 s53, s21, 0
	s_add_i32 s50, s54, s31
	s_mov_b32 m0, s50
	s_nop 0
	global_load_lds_dwordx4 v0, s[52:53]
	s_add_i32 m0, s50, 0x2000
	s_nop 0
	global_load_lds_dwordx4 v164, s[52:53]
	s_waitcnt vmcnt(6)
	s_barrier
; #define PG8_STAGE(bufoff, gbase, voff) do { _Pragma("unroll") for (int _i = 0; _i < 2; ++_i) \
;         __builtin_amdgcn_global_load_lds((const unsigned*)((const char*)(gbase) + (voff)[_i]), (LAS unsigned*)(lds + (bufoff) + ldsw + _i * 8192), 16, 0, 0); } while (0)
; #define PG8_LDA(dst, b, h) do { _Pragma("unroll") for (int m = 0; m < 4; ++m) _Pragma("unroll") for (int k = 0; k < 2; ++k) dst[m][k] = *(const LAS bf16x8*)(lds + PG8_SA(b, h) + aoff + m * 2048 + k * 1024); } while (0)
; #define PG8_LDB(dst, b, h) do { _Pragma("unroll") for (int n = 0; n < 2; ++n) _Pragma("unroll") for (int k = 0; k < 2; ++k) dst[n][k] = *(const LAS bf16x8*)(lds + PG8_SB(b, h) + boff + n * 2048 + k * 1024); } while (0)
; #define PG8_MMA(ai, bj, At, Bt) do { __builtin_amdgcn_s_setprio(1); _Pragma("unroll") for (int m = 0; m < 4; ++m) _Pragma("unroll") for (int n = 0; n < 2; ++n) _Pragma("unroll") for (int k = 0; k < 2; ++k) \
;         acc[ai][bj][m][n] = __builtin_amdgcn_mfma_f32_16x16x32_bf16(Bt[n][k], At[m][k], acc[ai][bj][m][n], 0, 0, 0); __builtin_amdgcn_s_setprio(0); } while (0)
; #define PG8_WAIT_V(n) asm volatile("s_waitcnt vmcnt(" #n ")" ::: "memory")
; #define PG8_WAIT_L(n) asm volatile("s_waitcnt lgkmcnt(" #n ")" ::: "memory")
; #define PG8_BAR __builtin_amdgcn_s_barrier()
; #define PG8_SCHED __builtin_amdgcn_sched_barrier(0)
; template <class Epi>
; __device__ __forceinline__ void gemm_phase(LAS unsigned char* lds, const Gemm g, const StaticOrder& S, const Epi& E, const int tid) {
;     ...
;             PG8_WAIT_V(6); PG8_BAR; PG8_MMA(1, 1, At, B1); PG8_BAR;
;             PG8_LDB(B0, 1, 0); PG8_SCHED; PG8_LDA(At, 1, 0); PG8_STAGE(PG8_SA(0, 1), a2 + hstep, voffA);
;             PG8_WAIT_L(8); PG8_BAR; PG8_WAIT_L(0); PG8_MMA(0, 0, At, B0); PG8_BAR; PG8_SCHED;
;             PG8_LDB(B1, 1, 1); PG8_STAGE(PG8_SB(1, 0), b3, voffB);
;             PG8_BAR; PG8_WAIT_L(0); PG8_MMA(0, 1, At, B1); PG8_BAR;
;             PG8_LDA(At, 1, 1); PG8_STAGE(PG8_SA(1, 0), a3, voffA);
	v_mfma_f32_16x16x32_bf16 v[38:41], v[218:221], v[184:187], v[38:41]
	v_mfma_f32_16x16x32_bf16 v[34:37], v[226:229], v[184:187], v[34:37]
	v_mfma_f32_16x16x32_bf16 v[22:25], v[218:221], v[192:195], v[22:25]
	v_mfma_f32_16x16x32_bf16 v[18:21], v[226:229], v[192:195], v[18:21]
	v_mfma_f32_16x16x32_bf16 v[6:9], v[218:221], v[210:213], v[6:9]
	v_mfma_f32_16x16x32_bf16 v[2:5], v[226:229], v[210:213], v[2:5]
	v_mfma_f32_16x16x32_bf16 v[50:53], v[218:221], v[176:179], v[62:65]
	v_mfma_f32_16x16x32_bf16 v[54:57], v[226:229], v[176:179], v[58:61]
	v_mfma_f32_16x16x32_bf16 v[38:41], v[222:225], v[188:191], v[38:41]
	v_mfma_f32_16x16x32_bf16 v[34:37], v[230:233], v[188:191], v[34:37]
	v_mfma_f32_16x16x32_bf16 v[22:25], v[222:225], v[196:199], v[22:25]
	v_mfma_f32_16x16x32_bf16 v[18:21], v[230:233], v[196:199], v[18:21]
	v_mfma_f32_16x16x32_bf16 v[6:9], v[222:225], v[214:217], v[6:9]
	v_mfma_f32_16x16x32_bf16 v[2:5], v[230:233], v[214:217], v[2:5]
	v_mfma_f32_16x16x32_bf16 v[50:53], v[222:225], v[180:183], v[50:53]
	v_mfma_f32_16x16x32_bf16 v[54:57], v[230:233], v[180:183], v[54:57]
	s_add_i32 s50, 0, 0x18000
	v_add_u32_e32 v70, s50, v173
	s_barrier
	ds_read_b128 v[58:61], v70
	ds_read_b128 v[62:65], v70 offset:1024
	ds_read_b128 v[66:69], v70 offset:2048
	ds_read_b128 v[70:73], v70 offset:3072
	s_add_u32 s22, s22, 0x200000
	s_addc_u32 s23, s23, 0
	s_mov_b32 m0, s35
	ds_read_b128 v[176:179], v174 offset:32768
	ds_read_b128 v[180:183], v174 offset:33792
	ds_read_b128 v[184:187], v174 offset:34816
	ds_read_b128 v[188:191], v174 offset:35840
	ds_read_b128 v[192:195], v174 offset:36864
	ds_read_b128 v[196:199], v174 offset:37888
	ds_read_b128 v[210:213], v174 offset:38912
	ds_read_b128 v[214:217], v174 offset:39936
	global_load_lds_dwordx4 v160, s[22:23]
	s_mov_b32 m0, s36
	s_nop 0
	global_load_lds_dwordx4 v162, s[22:23]
	s_waitcnt lgkmcnt(8)
	s_barrier
	s_waitcnt lgkmcnt(0)
	v_mfma_f32_16x16x32_bf16 v[142:145], v[58:61], v[176:179], v[142:145]
	v_mfma_f32_16x16x32_bf16 v[138:141], v[66:69], v[176:179], v[138:141]
	v_mfma_f32_16x16x32_bf16 v[126:129], v[58:61], v[184:187], v[126:129]
	v_mfma_f32_16x16x32_bf16 v[122:125], v[66:69], v[184:187], v[122:125]
	v_mfma_f32_16x16x32_bf16 v[110:113], v[58:61], v[192:195], v[110:113]
	v_mfma_f32_16x16x32_bf16 v[106:109], v[66:69], v[192:195], v[106:109]
	v_mfma_f32_16x16x32_bf16 v[94:97], v[58:61], v[210:213], v[94:97]
	v_mfma_f32_16x16x32_bf16 v[90:93], v[66:69], v[210:213], v[90:93]
	v_mfma_f32_16x16x32_bf16 v[142:145], v[62:65], v[180:183], v[142:145]
	v_mfma_f32_16x16x32_bf16 v[138:141], v[70:73], v[180:183], v[138:141]
	v_mfma_f32_16x16x32_bf16 v[126:129], v[62:65], v[188:191], v[126:129]
	v_mfma_f32_16x16x32_bf16 v[122:125], v[70:73], v[188:191], v[122:125]
	v_mfma_f32_16x16x32_bf16 v[110:113], v[62:65], v[196:199], v[110:113]
	v_mfma_f32_16x16x32_bf16 v[106:109], v[70:73], v[196:199], v[106:109]
	v_mfma_f32_16x16x32_bf16 v[94:97], v[62:65], v[214:217], v[94:97]
	v_mfma_f32_16x16x32_bf16 v[90:93], v[70:73], v[214:217], v[90:93]
	s_barrier
	s_add_i32 s22, 0, 0x1c000
	s_add_i32 s23, s50, s31
	v_add_u32_e32 v175, s22, v173
	v_lshl_add_u64 v[170:171], v[170:171], 0, s[56:57]
	s_mov_b32 m0, s23
	ds_read_b128 v[218:221], v175
	ds_read_b128 v[222:225], v175 offset:1024
	ds_read_b128 v[226:229], v175 offset:2048
	ds_read_b128 v[230:233], v175 offset:3072
	global_load_lds_dwordx4 v[170:171], off
	v_lshl_add_u64 v[170:171], v[200:201], 0, s[56:57]
	s_add_i32 m0, s23, 0x2000
	s_nop 0
	global_load_lds_dwordx4 v[170:171], off
	s_barrier
	s_waitcnt lgkmcnt(0)
	v_mfma_f32_16x16x32_bf16 v[134:137], v[218:221], v[176:179], v[134:137]
	v_mfma_f32_16x16x32_bf16 v[130:133], v[226:229], v[176:179], v[130:133]
	v_mfma_f32_16x16x32_bf16 v[118:121], v[218:221], v[184:187], v[118:121]
	v_mfma_f32_16x16x32_bf16 v[114:117], v[226:229], v[184:187], v[114:117]
	v_mfma_f32_16x16x32_bf16 v[102:105], v[218:221], v[192:195], v[102:105]
	v_mfma_f32_16x16x32_bf16 v[98:101], v[226:229], v[192:195], v[98:101]
	v_mfma_f32_16x16x32_bf16 v[86:89], v[218:221], v[210:213], v[86:89]
	v_mfma_f32_16x16x32_bf16 v[82:85], v[226:229], v[210:213], v[82:85]
	v_mfma_f32_16x16x32_bf16 v[134:137], v[222:225], v[180:183], v[134:137]
	v_mfma_f32_16x16x32_bf16 v[130:133], v[230:233], v[180:183], v[130:133]
	v_mfma_f32_16x16x32_bf16 v[118:121], v[222:225], v[188:191], v[118:121]
	v_mfma_f32_16x16x32_bf16 v[114:117], v[230:233], v[188:191], v[114:117]
	v_mfma_f32_16x16x32_bf16 v[102:105], v[222:225], v[196:199], v[102:105]
	v_mfma_f32_16x16x32_bf16 v[98:101], v[230:233], v[196:199], v[98:101]
	v_mfma_f32_16x16x32_bf16 v[86:89], v[222:225], v[214:217], v[86:89]
	v_mfma_f32_16x16x32_bf16 v[82:85], v[230:233], v[214:217], v[82:85]
	s_mov_b32 m0, s39
	v_lshl_add_u64 v[170:171], v[234:235], 0, s[56:57]
	s_barrier
	ds_read_b128 v[176:179], v174 offset:49152
	ds_read_b128 v[180:183], v174 offset:50176
	ds_read_b128 v[184:187], v174 offset:51200
	ds_read_b128 v[188:191], v174 offset:52224
	ds_read_b128 v[192:195], v174 offset:53248
	ds_read_b128 v[196:199], v174 offset:54272
	ds_read_b128 v[210:213], v174 offset:55296
	ds_read_b128 v[214:217], v174 offset:56320
	global_load_lds_dwordx4 v[170:171], off
	v_lshl_add_u64 v[170:171], v[236:237], 0, s[56:57]
	s_mov_b32 m0, s40
	s_nop 0
	global_load_lds_dwordx4 v[170:171], off
	s_barrier
; __device__ __forceinline__ unsigned pk2(float lo, float hi) { f32x2 v = {lo, hi}; return __builtin_bit_cast(unsigned, __builtin_convertvector(v, bf16x2_t)); }
; __device__ __forceinline__ float bf_lo(unsigned w) { return __uint_as_float(w << 16); }
; __device__ __forceinline__ float bf_hi(unsigned w) { return __uint_as_float(w & 0xffff0000u); }
;     __device__ __forceinline__ void operator()(const f32x4 (&acc)[2][2][4][2], const Unit& u, int wr, int wc, int fr, int fq) const {
;     ...
;         const int row0 = u.pm * BM + wr * 64 + fr, col0 = u.pn * BM + wc * 32 + 8 * fq;
;         const float* gp = gate + (size_t)(u.pm >> 5) * 12288 + col0;
;         f32x4 gv[2][2];
; #pragma unroll
;         for (int bj = 0; bj < 2; ++bj)
; #pragma unroll
;             for (int n = 0; n < 2; ++n) gv[bj][n] = *(const f32x4*)(gp + bj * HALF + 4 * n);
; #pragma unroll
;         for (int ai = 0; ai < 2; ++ai)
; #pragma unroll
;             for (int m = 0; m < 4; ++m) {
;                 const size_t ro = (size_t)(row0 + ai * HALF + m * 16) * DM + col0;
; #pragma unroll
;                 for (int bj = 0; bj < 2; ++bj) {
;                     f32x4 r0, r1;
;                     if (RB) { const u32x4 rw = *(const u32x4*)((const bf16_t*)resid + ro + bj * HALF);
;                         r0 = (f32x4){bf_lo(rw.x), bf_hi(rw.x), bf_lo(rw.y), bf_hi(rw.y)}; r1 = (f32x4){bf_lo(rw.z), bf_hi(rw.z), bf_lo(rw.w), bf_hi(rw.w)}; }
;                     else { r0 = *(const f32x4*)((const float*)resid + ro + bj * HALF); r1 = *(const f32x4*)((const float*)resid + ro + bj * HALF + 4); }
;                     const f32x4 v0 = r0 + gv[bj][0] * acc[ai][bj][m][0], v1 = r1 + gv[bj][1] * acc[ai][bj][m][1];
;                     if (OB) { u32x4 w; w.x = pk2(v0[0], v0[1]); w.y = pk2(v0[2], v0[3]); w.z = pk2(v1[0], v1[1]); w.w = pk2(v1[2], v1[3]); *(u32x4*)((bf16_t*)out + ro + bj * HALF) = w; }
;                     else { *(f32x4*)((float*)out + ro + bj * HALF) = v0; *(f32x4*)((float*)out + ro + bj * HALF + 4) = v1; }
; template <class Epi>
; __device__ __forceinline__ void gemm_phase(LAS unsigned char* lds, const Gemm g, const StaticOrder& S, const Epi& E, const int tid) {
;     ...
;             PG8_BAR; PG8_WAIT_L(0); PG8_MMA(1, 0, At, B0); PG8_BAR; PG8_SCHED;
;             PG8_STAGE(PG8_SB(1, 1), b3 + hstep, voffB);
;             PG8_WAIT_V(6); PG8_BAR; PG8_MMA(1, 1, At, B1); PG8_BAR;
	s_waitcnt lgkmcnt(0)
	v_mfma_f32_16x16x32_bf16 v[78:81], v[58:61], v[176:179], v[78:81]
	v_mfma_f32_16x16x32_bf16 v[74:77], v[66:69], v[176:179], v[74:77]
	v_mfma_f32_16x16x32_bf16 v[46:49], v[58:61], v[184:187], v[46:49]
	v_mfma_f32_16x16x32_bf16 v[42:45], v[66:69], v[184:187], v[42:45]
	v_mfma_f32_16x16x32_bf16 v[30:33], v[58:61], v[192:195], v[30:33]
	v_mfma_f32_16x16x32_bf16 v[26:29], v[66:69], v[192:195], v[26:29]
	v_mfma_f32_16x16x32_bf16 v[14:17], v[58:61], v[210:213], v[14:17]
	v_mfma_f32_16x16x32_bf16 v[10:13], v[66:69], v[210:213], v[10:13]
	v_mfma_f32_16x16x32_bf16 v[78:81], v[62:65], v[180:183], v[78:81]
	v_mfma_f32_16x16x32_bf16 v[74:77], v[70:73], v[180:183], v[74:77]
	v_mfma_f32_16x16x32_bf16 v[46:49], v[62:65], v[188:191], v[46:49]
	v_mfma_f32_16x16x32_bf16 v[42:45], v[70:73], v[188:191], v[42:45]
	v_mfma_f32_16x16x32_bf16 v[30:33], v[62:65], v[196:199], v[30:33]
	v_mfma_f32_16x16x32_bf16 v[26:29], v[70:73], v[196:199], v[26:29]
	v_mfma_f32_16x16x32_bf16 v[14:17], v[62:65], v[214:217], v[14:17]
	v_mfma_f32_16x16x32_bf16 v[10:13], v[70:73], v[214:217], v[10:13]
	s_barrier
	s_add_u32 s20, s20, 0x200080
	s_addc_u32 s21, s21, 0
	s_add_i32 s22, s22, s31
	s_mov_b32 m0, s22
	s_nop 0
	global_load_lds_dwordx4 v0, s[20:21]
	s_add_i32 m0, s22, 0x2000
	s_nop 0
	global_load_lds_dwordx4 v164, s[20:21]
	s_waitcnt vmcnt(6)
	s_barrier
	v_mfma_f32_16x16x32_bf16 v[50:53], v[218:221], v[176:179], v[50:53]
	v_mfma_f32_16x16x32_bf16 v[62:65], v[222:225], v[180:183], v[50:53]
	v_mfma_f32_16x16x32_bf16 v[50:53], v[226:229], v[176:179], v[54:57]
	v_mfma_f32_16x16x32_bf16 v[38:41], v[218:221], v[184:187], v[38:41]
	v_mfma_f32_16x16x32_bf16 v[34:37], v[226:229], v[184:187], v[34:37]
	v_mfma_f32_16x16x32_bf16 v[22:25], v[218:221], v[192:195], v[22:25]
	v_mfma_f32_16x16x32_bf16 v[18:21], v[226:229], v[192:195], v[18:21]
	v_mfma_f32_16x16x32_bf16 v[6:9], v[218:221], v[210:213], v[6:9]
	v_mfma_f32_16x16x32_bf16 v[2:5], v[226:229], v[210:213], v[2:5]
	v_mfma_f32_16x16x32_bf16 v[58:61], v[230:233], v[180:183], v[50:53]
	v_mfma_f32_16x16x32_bf16 v[38:41], v[222:225], v[188:191], v[38:41]
	v_mfma_f32_16x16x32_bf16 v[34:37], v[230:233], v[188:191], v[34:37]
	v_mfma_f32_16x16x32_bf16 v[22:25], v[222:225], v[196:199], v[22:25]
	v_mfma_f32_16x16x32_bf16 v[18:21], v[230:233], v[196:199], v[18:21]
	v_mfma_f32_16x16x32_bf16 v[6:9], v[222:225], v[214:217], v[6:9]
	v_mfma_f32_16x16x32_bf16 v[2:5], v[230:233], v[214:217], v[2:5]
	s_add_i32 s49, s49, 2
	s_add_u32 s47, s47, 0x100
	s_addc_u32 s48, s48, 0
	s_add_u32 s18, s18, 0x100
	s_addc_u32 s19, s19, 0
	s_cmpk_gt_u32 s49, 0x7d
	s_barrier
	s_cbranch_scc0 .LBB0_40
	s_setprio 0
	s_lshl_b32 s11, s2, 8
	s_lshl_b32 s13, s43, 8
	v_mov_b32_e32 v50, v172
	v_mov_b32_e32 v175, v159
	s_add_i32 s11, s11, s37
	s_or_b32 s13, s13, s38
	s_ashr_i32 s2, s2, 5
	s_mov_b32 s43, s10
	v_lshl_add_u32 v170, v50, 3, s13
	s_mul_hi_i32 s13, s2, 0xc000
	s_mul_i32 s2, s2, 0xc000
	v_add_u32_e32 v176, s11, v175
	s_add_u32 s18, s27, s2
	v_ashrrev_i32_e32 v177, 31, v176
	s_addc_u32 s19, s28, s13
	v_ashrrev_i32_e32 v171, 31, v170
	v_lshlrev_b64 v[176:177], 11, v[176:177]
	v_lshl_add_u64 v[54:55], v[170:171], 2, s[18:19]
	v_lshl_add_u64 v[170:171], v[176:177], 0, v[170:171]
	v_lshl_add_u64 v[180:181], v[170:171], 1, s[8:9]
	global_load_dwordx4 v[66:69], v[54:55], off offset:16
	global_load_dwordx4 v[70:73], v[54:55], off
	global_load_dwordx4 v[50:53], v[54:55], off offset:528
	s_nop 0
	global_load_dwordx4 v[54:57], v[54:55], off offset:512
	v_lshlrev_b32_e32 v175, 1, v170
	v_lshlrev_b32_e32 v200, 2, v170
	s_mov_b64 s[92:93], s[8:9]
	s_mov_b64 s[94:95], s[6:7]
	global_load_dwordx4 v[184:187], v175, s[92:93]
	global_load_dwordx4 v[188:191], v175, s[92:93] offset:256
	s_add_u32 s92, s92, 0x10000
	s_addc_u32 s93, s93, 0
	global_load_dwordx4 v[192:195], v175, s[92:93]
	global_load_dwordx4 v[196:199], v175, s[92:93] offset:256
	s_add_u32 s92, s92, 0x10000
	s_addc_u32 s93, s93, 0
	global_load_dwordx4 v[210:213], v175, s[92:93]
	global_load_dwordx4 v[214:217], v175, s[92:93] offset:256
	s_add_u32 s92, s92, 0x10000
	s_addc_u32 s93, s93, 0
	global_load_dwordx4 v[218:221], v175, s[92:93]
	global_load_dwordx4 v[222:225], v175, s[92:93] offset:256
	s_add_u32 s92, s92, 0x50000
	s_addc_u32 s93, s93, 0
	global_load_dwordx4 v[226:229], v175, s[92:93]
	global_load_dwordx4 v[230:233], v175, s[92:93] offset:256
	s_add_u32 s92, s92, 0x10000
	s_addc_u32 s93, s93, 0
	global_load_dwordx4 v[234:237], v175, s[92:93]
	s_waitcnt vmcnt(10)
	v_lshlrev_b32_e32 v176, 16, v184
	v_and_b32_e32 v177, 0xffff0000, v184
	v_lshlrev_b32_e32 v178, 16, v185
	v_and_b32_e32 v179, 0xffff0000, v185
	v_lshlrev_b32_e32 v180, 16, v186
	v_and_b32_e32 v181, 0xffff0000, v186
	v_lshlrev_b32_e32 v182, 16, v187
	v_and_b32_e32 v183, 0xffff0000, v187
	v_pk_fma_f32 v[142:143], v[142:143], v[70:71], v[176:177]
	v_pk_fma_f32 v[144:145], v[144:145], v[72:73], v[178:179]
	v_pk_fma_f32 v[138:139], v[138:139], v[66:67], v[180:181]
	v_pk_fma_f32 v[140:141], v[140:141], v[68:69], v[182:183]
	global_load_dwordx4 v[184:187], v175, s[92:93] offset:256
	global_store_dwordx4 v200, v[142:145], s[94:95]
	global_store_dwordx4 v200, v[138:141], s[94:95] offset:16
	s_waitcnt vmcnt(12)
	v_lshlrev_b32_e32 v176, 16, v188
	v_and_b32_e32 v177, 0xffff0000, v188
	v_lshlrev_b32_e32 v178, 16, v189
	v_and_b32_e32 v179, 0xffff0000, v189
	v_lshlrev_b32_e32 v180, 16, v190
	v_and_b32_e32 v181, 0xffff0000, v190
	v_lshlrev_b32_e32 v182, 16, v191
	v_and_b32_e32 v183, 0xffff0000, v191
	v_pk_fma_f32 v[134:135], v[134:135], v[54:55], v[176:177]
	v_pk_fma_f32 v[136:137], v[136:137], v[56:57], v[178:179]
	v_pk_fma_f32 v[130:131], v[130:131], v[50:51], v[180:181]
	v_pk_fma_f32 v[132:133], v[132:133], v[52:53], v[182:183]
	s_add_u32 s92, s92, 0x10000
	s_addc_u32 s93, s93, 0
	global_load_dwordx4 v[188:191], v175, s[92:93]
	global_store_dwordx4 v200, v[134:137], s[94:95] offset:512
	global_store_dwordx4 v200, v[130:133], s[94:95] offset:528
	s_waitcnt vmcnt(14)
; __device__ __forceinline__ unsigned pk2(float lo, float hi) { f32x2 v = {lo, hi}; return __builtin_bit_cast(unsigned, __builtin_convertvector(v, bf16x2_t)); }
; __device__ __forceinline__ float bf_lo(unsigned w) { return __uint_as_float(w << 16); }
; __device__ __forceinline__ float bf_hi(unsigned w) { return __uint_as_float(w & 0xffff0000u); }
;     __device__ __forceinline__ void operator()(const f32x4 (&acc)[2][2][4][2], const Unit& u, int wr, int wc, int fr, int fq) const {
;     ...
;                 for (int bj = 0; bj < 2; ++bj) {
;                     f32x4 r0, r1;
;                     if (RB) { const u32x4 rw = *(const u32x4*)((const bf16_t*)resid + ro + bj * HALF);
;                         r0 = (f32x4){bf_lo(rw.x), bf_hi(rw.x), bf_lo(rw.y), bf_hi(rw.y)}; r1 = (f32x4){bf_lo(rw.z), bf_hi(rw.z), bf_lo(rw.w), bf_hi(rw.w)}; }
;                     else { r0 = *(const f32x4*)((const float*)resid + ro + bj * HALF); r1 = *(const f32x4*)((const float*)resid + ro + bj * HALF + 4); }
;                     const f32x4 v0 = r0 + gv[bj][0] * acc[ai][bj][m][0], v1 = r1 + gv[bj][1] * acc[ai][bj][m][1];
;                     if (OB) { u32x4 w; w.x = pk2(v0[0], v0[1]); w.y = pk2(v0[2], v0[3]); w.z = pk2(v1[0], v1[1]); w.w = pk2(v1[2], v1[3]); *(u32x4*)((bf16_t*)out + ro + bj * HALF) = w; }
;                     else { *(f32x4*)((float*)out + ro + bj * HALF) = v0; *(f32x4*)((float*)out + ro + bj * HALF + 4) = v1; }
	v_lshlrev_b32_e32 v176, 16, v192
	v_and_b32_e32 v177, 0xffff0000, v192
	v_lshlrev_b32_e32 v178, 16, v193
	v_and_b32_e32 v179, 0xffff0000, v193
	v_lshlrev_b32_e32 v180, 16, v194
	v_and_b32_e32 v181, 0xffff0000, v194
	v_lshlrev_b32_e32 v182, 16, v195
	v_and_b32_e32 v183, 0xffff0000, v195
	v_pk_fma_f32 v[126:127], v[126:127], v[70:71], v[176:177]
	v_pk_fma_f32 v[128:129], v[128:129], v[72:73], v[178:179]
	v_pk_fma_f32 v[122:123], v[122:123], v[66:67], v[180:181]
	v_pk_fma_f32 v[124:125], v[124:125], v[68:69], v[182:183]
	global_load_dwordx4 v[192:195], v175, s[92:93] offset:256
	s_add_u32 s94, s94, 0x20000
	s_addc_u32 s95, s95, 0
	global_store_dwordx4 v200, v[126:129], s[94:95]
	global_store_dwordx4 v200, v[122:125], s[94:95] offset:16
	s_waitcnt vmcnt(16)
	v_lshlrev_b32_e32 v176, 16, v196
	v_and_b32_e32 v177, 0xffff0000, v196
	v_lshlrev_b32_e32 v178, 16, v197
	v_and_b32_e32 v179, 0xffff0000, v197
	v_lshlrev_b32_e32 v180, 16, v198
	v_and_b32_e32 v181, 0xffff0000, v198
	v_lshlrev_b32_e32 v182, 16, v199
	v_and_b32_e32 v183, 0xffff0000, v199
	v_pk_fma_f32 v[118:119], v[118:119], v[54:55], v[176:177]
	v_pk_fma_f32 v[120:121], v[120:121], v[56:57], v[178:179]
	v_pk_fma_f32 v[114:115], v[114:115], v[50:51], v[180:181]
	v_pk_fma_f32 v[116:117], v[116:117], v[52:53], v[182:183]
	s_add_u32 s92, s92, 0x10000
	s_addc_u32 s93, s93, 0
	global_load_dwordx4 v[196:199], v175, s[92:93]
	global_store_dwordx4 v200, v[118:121], s[94:95] offset:512
	global_store_dwordx4 v200, v[114:117], s[94:95] offset:528
	s_waitcnt vmcnt(18)
	v_lshlrev_b32_e32 v176, 16, v210
	v_and_b32_e32 v177, 0xffff0000, v210
	v_lshlrev_b32_e32 v178, 16, v211
	v_and_b32_e32 v179, 0xffff0000, v211
	v_lshlrev_b32_e32 v180, 16, v212
	v_and_b32_e32 v181, 0xffff0000, v212
	v_lshlrev_b32_e32 v182, 16, v213
	v_and_b32_e32 v183, 0xffff0000, v213
	v_pk_fma_f32 v[110:111], v[110:111], v[70:71], v[176:177]
	v_pk_fma_f32 v[112:113], v[112:113], v[72:73], v[178:179]
	v_pk_fma_f32 v[106:107], v[106:107], v[66:67], v[180:181]
	v_pk_fma_f32 v[108:109], v[108:109], v[68:69], v[182:183]
	global_load_dwordx4 v[210:213], v175, s[92:93] offset:256
	s_add_u32 s94, s94, 0x20000
	s_addc_u32 s95, s95, 0
	global_store_dwordx4 v200, v[110:113], s[94:95]
	global_store_dwordx4 v200, v[106:109], s[94:95] offset:16
	s_waitcnt vmcnt(20)
	v_lshlrev_b32_e32 v176, 16, v214
	v_and_b32_e32 v177, 0xffff0000, v214
	v_lshlrev_b32_e32 v178, 16, v215
	v_and_b32_e32 v179, 0xffff0000, v215
	v_lshlrev_b32_e32 v180, 16, v216
	v_and_b32_e32 v181, 0xffff0000, v216
	v_lshlrev_b32_e32 v182, 16, v217
	v_and_b32_e32 v183, 0xffff0000, v217
	v_pk_fma_f32 v[102:103], v[102:103], v[54:55], v[176:177]
	v_pk_fma_f32 v[104:105], v[104:105], v[56:57], v[178:179]
	v_pk_fma_f32 v[98:99], v[98:99], v[50:51], v[180:181]
	v_pk_fma_f32 v[100:101], v[100:101], v[52:53], v[182:183]
	global_store_dwordx4 v200, v[102:105], s[94:95] offset:512
	global_store_dwordx4 v200, v[98:101], s[94:95] offset:528
	s_waitcnt vmcnt(21)
	v_lshlrev_b32_e32 v176, 16, v218
	v_and_b32_e32 v177, 0xffff0000, v218
	v_lshlrev_b32_e32 v178, 16, v219
	v_and_b32_e32 v179, 0xffff0000, v219
	v_lshlrev_b32_e32 v180, 16, v220
	v_and_b32_e32 v181, 0xffff0000, v220
	v_lshlrev_b32_e32 v182, 16, v221
	v_and_b32_e32 v183, 0xffff0000, v221
	v_pk_fma_f32 v[94:95], v[94:95], v[70:71], v[176:177]
	v_pk_fma_f32 v[96:97], v[96:97], v[72:73], v[178:179]
	v_pk_fma_f32 v[90:91], v[90:91], v[66:67], v[180:181]
	v_pk_fma_f32 v[92:93], v[92:93], v[68:69], v[182:183]
	s_add_u32 s94, s94, 0x20000
	s_addc_u32 s95, s95, 0
	global_store_dwordx4 v200, v[94:97], s[94:95]
	global_store_dwordx4 v200, v[90:93], s[94:95] offset:16
	s_waitcnt vmcnt(22)
	v_lshlrev_b32_e32 v176, 16, v222
	v_and_b32_e32 v177, 0xffff0000, v222
	v_lshlrev_b32_e32 v178, 16, v223
	v_and_b32_e32 v179, 0xffff0000, v223
	v_lshlrev_b32_e32 v180, 16, v224
	v_and_b32_e32 v181, 0xffff0000, v224
	v_lshlrev_b32_e32 v182, 16, v225
	v_and_b32_e32 v183, 0xffff0000, v225
	v_pk_fma_f32 v[86:87], v[86:87], v[54:55], v[176:177]
	v_pk_fma_f32 v[88:89], v[88:89], v[56:57], v[178:179]
	v_pk_fma_f32 v[82:83], v[82:83], v[50:51], v[180:181]
	v_pk_fma_f32 v[84:85], v[84:85], v[52:53], v[182:183]
	global_store_dwordx4 v200, v[86:89], s[94:95] offset:512
	global_store_dwordx4 v200, v[82:85], s[94:95] offset:528
	s_waitcnt vmcnt(23)
	v_lshlrev_b32_e32 v176, 16, v226
	v_and_b32_e32 v177, 0xffff0000, v226
	v_lshlrev_b32_e32 v178, 16, v227
	v_and_b32_e32 v179, 0xffff0000, v227
	v_lshlrev_b32_e32 v180, 16, v228
	v_and_b32_e32 v181, 0xffff0000, v228
	v_lshlrev_b32_e32 v182, 16, v229
	v_and_b32_e32 v183, 0xffff0000, v229
	v_pk_fma_f32 v[78:79], v[78:79], v[70:71], v[176:177]
	v_pk_fma_f32 v[80:81], v[80:81], v[72:73], v[178:179]
	v_pk_fma_f32 v[74:75], v[74:75], v[66:67], v[180:181]
	v_pk_fma_f32 v[76:77], v[76:77], v[68:69], v[182:183]
	s_add_u32 s94, s94, 0xa0000
	s_addc_u32 s95, s95, 0
	global_store_dwordx4 v200, v[78:81], s[94:95]
	global_store_dwordx4 v200, v[74:77], s[94:95] offset:16
	s_waitcnt vmcnt(24)
; __device__ __forceinline__ unsigned pk2(float lo, float hi) { f32x2 v = {lo, hi}; return __builtin_bit_cast(unsigned, __builtin_convertvector(v, bf16x2_t)); }
; __device__ __forceinline__ float bf_lo(unsigned w) { return __uint_as_float(w << 16); }
; __device__ __forceinline__ float bf_hi(unsigned w) { return __uint_as_float(w & 0xffff0000u); }
; #define PG8_WAIT_V(n) asm volatile("s_waitcnt vmcnt(" #n ")" ::: "memory")
; #define PG8_BAR __builtin_amdgcn_s_barrier()
;     __device__ __forceinline__ void operator()(const f32x4 (&acc)[2][2][4][2], const Unit& u, int wr, int wc, int fr, int fq) const {
;     ...
;                 for (int bj = 0; bj < 2; ++bj) {
;                     f32x4 r0, r1;
;                     if (RB) { const u32x4 rw = *(const u32x4*)((const bf16_t*)resid + ro + bj * HALF);
;                         r0 = (f32x4){bf_lo(rw.x), bf_hi(rw.x), bf_lo(rw.y), bf_hi(rw.y)}; r1 = (f32x4){bf_lo(rw.z), bf_hi(rw.z), bf_lo(rw.w), bf_hi(rw.w)}; }
;                     else { r0 = *(const f32x4*)((const float*)resid + ro + bj * HALF); r1 = *(const f32x4*)((const float*)resid + ro + bj * HALF + 4); }
;                     const f32x4 v0 = r0 + gv[bj][0] * acc[ai][bj][m][0], v1 = r1 + gv[bj][1] * acc[ai][bj][m][1];
;                     if (OB) { u32x4 w; w.x = pk2(v0[0], v0[1]); w.y = pk2(v0[2], v0[3]); w.z = pk2(v1[0], v1[1]); w.w = pk2(v1[2], v1[3]); *(u32x4*)((bf16_t*)out + ro + bj * HALF) = w; }
;                     else { *(f32x4*)((float*)out + ro + bj * HALF) = v0; *(f32x4*)((float*)out + ro + bj * HALF + 4) = v1; }
; template <class Epi>
; __device__ __forceinline__ void gemm_phase(LAS unsigned char* lds, const Gemm g, const StaticOrder& S, const Epi& E, const int tid) {
;     ...
;         E(acc, cur, wr, wc, fr, fq);
;         if (!has_next) break;
; #pragma unroll
;         for (int a = 0; a < 2; ++a)
; #pragma unroll
;             for (int b = 0; b < 2; ++b)
; #pragma unroll
;                 for (int m = 0; m < 4; ++m)
; #pragma unroll
;                     for (int n = 0; n < 2; ++n) acc[a][b][m][n] = (f32x4){0.f, 0.f, 0.f, 0.f};
;         cur = nxt; cA = nA; cB = nB; ++ui;
;     }
;     PG8_WAIT_V(0);
;     if (wr == 0) PG8_BAR;
	v_lshlrev_b32_e32 v176, 16, v230
	v_and_b32_e32 v177, 0xffff0000, v230
	v_lshlrev_b32_e32 v178, 16, v231
	v_and_b32_e32 v179, 0xffff0000, v231
	v_lshlrev_b32_e32 v180, 16, v232
	v_and_b32_e32 v181, 0xffff0000, v232
	v_lshlrev_b32_e32 v182, 16, v233
	v_and_b32_e32 v183, 0xffff0000, v233
	v_pk_fma_f32 v[62:63], v[62:63], v[54:55], v[176:177]
	v_pk_fma_f32 v[64:65], v[64:65], v[56:57], v[178:179]
	v_pk_fma_f32 v[58:59], v[58:59], v[50:51], v[180:181]
	v_pk_fma_f32 v[60:61], v[60:61], v[52:53], v[182:183]
	global_store_dwordx4 v200, v[62:65], s[94:95] offset:512
	global_store_dwordx4 v200, v[58:61], s[94:95] offset:528
	s_waitcnt vmcnt(25)
	v_lshlrev_b32_e32 v176, 16, v234
	v_and_b32_e32 v177, 0xffff0000, v234
	v_lshlrev_b32_e32 v178, 16, v235
	v_and_b32_e32 v179, 0xffff0000, v235
	v_lshlrev_b32_e32 v180, 16, v236
	v_and_b32_e32 v181, 0xffff0000, v236
	v_lshlrev_b32_e32 v182, 16, v237
	v_and_b32_e32 v183, 0xffff0000, v237
	v_pk_fma_f32 v[46:47], v[46:47], v[70:71], v[176:177]
	v_pk_fma_f32 v[48:49], v[48:49], v[72:73], v[178:179]
	v_pk_fma_f32 v[42:43], v[42:43], v[66:67], v[180:181]
	v_pk_fma_f32 v[44:45], v[44:45], v[68:69], v[182:183]
	s_add_u32 s94, s94, 0x20000
	s_addc_u32 s95, s95, 0
	global_store_dwordx4 v200, v[46:49], s[94:95]
	global_store_dwordx4 v200, v[42:45], s[94:95] offset:16
	s_waitcnt vmcnt(26)
	v_lshlrev_b32_e32 v176, 16, v184
	v_and_b32_e32 v177, 0xffff0000, v184
	v_lshlrev_b32_e32 v178, 16, v185
	v_and_b32_e32 v179, 0xffff0000, v185
	v_lshlrev_b32_e32 v180, 16, v186
	v_and_b32_e32 v181, 0xffff0000, v186
	v_lshlrev_b32_e32 v182, 16, v187
	v_and_b32_e32 v183, 0xffff0000, v187
	v_pk_fma_f32 v[38:39], v[38:39], v[54:55], v[176:177]
	v_pk_fma_f32 v[40:41], v[40:41], v[56:57], v[178:179]
	v_pk_fma_f32 v[34:35], v[34:35], v[50:51], v[180:181]
	v_pk_fma_f32 v[36:37], v[36:37], v[52:53], v[182:183]
	global_store_dwordx4 v200, v[38:41], s[94:95] offset:512
	global_store_dwordx4 v200, v[34:37], s[94:95] offset:528
	s_waitcnt vmcnt(25)
	v_lshlrev_b32_e32 v176, 16, v188
	v_and_b32_e32 v177, 0xffff0000, v188
	v_lshlrev_b32_e32 v178, 16, v189
	v_and_b32_e32 v179, 0xffff0000, v189
	v_lshlrev_b32_e32 v180, 16, v190
	v_and_b32_e32 v181, 0xffff0000, v190
	v_lshlrev_b32_e32 v182, 16, v191
	v_and_b32_e32 v183, 0xffff0000, v191
	v_pk_fma_f32 v[30:31], v[30:31], v[70:71], v[176:177]
	v_pk_fma_f32 v[32:33], v[32:33], v[72:73], v[178:179]
	v_pk_fma_f32 v[26:27], v[26:27], v[66:67], v[180:181]
	v_pk_fma_f32 v[28:29], v[28:29], v[68:69], v[182:183]
	s_add_u32 s94, s94, 0x20000
	s_addc_u32 s95, s95, 0
	global_store_dwordx4 v200, v[30:33], s[94:95]
	global_store_dwordx4 v200, v[26:29], s[94:95] offset:16
	s_waitcnt vmcnt(24)
	v_lshlrev_b32_e32 v176, 16, v192
	v_and_b32_e32 v177, 0xffff0000, v192
	v_lshlrev_b32_e32 v178, 16, v193
	v_and_b32_e32 v179, 0xffff0000, v193
	v_lshlrev_b32_e32 v180, 16, v194
	v_and_b32_e32 v181, 0xffff0000, v194
	v_lshlrev_b32_e32 v182, 16, v195
	v_and_b32_e32 v183, 0xffff0000, v195
	v_pk_fma_f32 v[22:23], v[22:23], v[54:55], v[176:177]
	v_pk_fma_f32 v[24:25], v[24:25], v[56:57], v[178:179]
	v_pk_fma_f32 v[18:19], v[18:19], v[50:51], v[180:181]
	v_pk_fma_f32 v[20:21], v[20:21], v[52:53], v[182:183]
	global_store_dwordx4 v200, v[22:25], s[94:95] offset:512
	global_store_dwordx4 v200, v[18:21], s[94:95] offset:528
	s_waitcnt vmcnt(23)
	v_lshlrev_b32_e32 v176, 16, v196
	v_and_b32_e32 v177, 0xffff0000, v196
	v_lshlrev_b32_e32 v178, 16, v197
	v_and_b32_e32 v179, 0xffff0000, v197
	v_lshlrev_b32_e32 v180, 16, v198
	v_and_b32_e32 v181, 0xffff0000, v198
	v_lshlrev_b32_e32 v182, 16, v199
	v_and_b32_e32 v183, 0xffff0000, v199
	v_pk_fma_f32 v[14:15], v[14:15], v[70:71], v[176:177]
	v_pk_fma_f32 v[16:17], v[16:17], v[72:73], v[178:179]
	v_pk_fma_f32 v[10:11], v[10:11], v[66:67], v[180:181]
	v_pk_fma_f32 v[12:13], v[12:13], v[68:69], v[182:183]
	s_add_u32 s94, s94, 0x20000
	s_addc_u32 s95, s95, 0
	global_store_dwordx4 v200, v[14:17], s[94:95]
	global_store_dwordx4 v200, v[10:13], s[94:95] offset:16
	s_waitcnt vmcnt(22)
	v_lshlrev_b32_e32 v176, 16, v210
	v_and_b32_e32 v177, 0xffff0000, v210
	v_lshlrev_b32_e32 v178, 16, v211
	v_and_b32_e32 v179, 0xffff0000, v211
	v_lshlrev_b32_e32 v180, 16, v212
	v_and_b32_e32 v181, 0xffff0000, v212
	v_lshlrev_b32_e32 v182, 16, v213
	v_and_b32_e32 v183, 0xffff0000, v213
	v_pk_fma_f32 v[6:7], v[6:7], v[54:55], v[176:177]
	v_pk_fma_f32 v[8:9], v[8:9], v[56:57], v[178:179]
	v_pk_fma_f32 v[2:3], v[2:3], v[50:51], v[180:181]
	v_pk_fma_f32 v[4:5], v[4:5], v[52:53], v[182:183]
	global_store_dwordx4 v200, v[6:9], s[94:95] offset:512
	global_store_dwordx4 v200, v[2:5], s[94:95] offset:528
	s_mov_b32 s2, s12
	s_mov_b64 s[20:21], s[14:15]
	s_mov_b64 s[18:19], s[16:17]
	s_and_b64 vcc, exec, s[4:5]
	s_nop 1
	s_cbranch_vccz .LBB0_33
	s_waitcnt vmcnt(0)
	s_cmpk_gt_u32 s29, 0xff
	s_cbranch_scc1 .LBB0_44
	s_barrier

; #define PG8_STAGE(bufoff, gbase, voff) do { _Pragma("unroll") for (int _i = 0; _i < 2; ++_i) \
;         __builtin_amdgcn_global_load_lds((const unsigned*)((const char*)(gbase) + (voff)[_i]), (LAS unsigned*)(lds + (bufoff) + ldsw + _i * 8192), 16, 0, 0); } while (0)
; #define PG8_LDA(dst, b, h) do { _Pragma("unroll") for (int m = 0; m < 4; ++m) _Pragma("unroll") for (int k = 0; k < 2; ++k) dst[m][k] = *(const LAS bf16x8*)(lds + PG8_SA(b, h) + aoff + m * 2048 + k * 1024); } while (0)
; #define PG8_LDB(dst, b, h) do { _Pragma("unroll") for (int n = 0; n < 2; ++n) _Pragma("unroll") for (int k = 0; k < 2; ++k) dst[n][k] = *(const LAS bf16x8*)(lds + PG8_SB(b, h) + boff + n * 2048 + k * 1024); } while (0)
; #define PG8_MMA(ai, bj, At, Bt) do { __builtin_amdgcn_s_setprio(1); _Pragma("unroll") for (int m = 0; m < 4; ++m) _Pragma("unroll") for (int n = 0; n < 2; ++n) _Pragma("unroll") for (int k = 0; k < 2; ++k) \
;         acc[ai][bj][m][n] = __builtin_amdgcn_mfma_f32_16x16x32_bf16(Bt[n][k], At[m][k], acc[ai][bj][m][n], 0, 0, 0); __builtin_amdgcn_s_setprio(0); } while (0)
; #define PG8_WAIT_V(n) asm volatile("s_waitcnt vmcnt(" #n ")" ::: "memory")
; #define PG8_WAIT_L(n) asm volatile("s_waitcnt lgkmcnt(" #n ")" ::: "memory")
; #define PG8_BAR __builtin_amdgcn_s_barrier()
; template <class Epi>
; __device__ __forceinline__ void gemm_phase(LAS unsigned char* lds, const Gemm g, const StaticOrder& S, const Epi& E, const int tid) {
;     ...
;             const bool last = (t == nt - 2);
;             const char* a1 = cA + (size_t)(t + 1) * kstep;
;             const char* a2 = last ? nA : cA + (size_t)(t + 2) * kstep; const char* b2 = last ? nB : cB + (size_t)(t + 2) * kstep;
;             const char* a3 = a2 + kstep; const char* b3 = b2 + kstep;
;             PG8_LDB(B0, 0, 0); PG8_SCHED; PG8_LDA(At, 0, 0); PG8_STAGE(PG8_SA(1, 1), a1 + hstep, voffA);
;             PG8_WAIT_L(8); PG8_BAR; PG8_WAIT_L(0); PG8_MMA(0, 0, At, B0); PG8_BAR; PG8_SCHED;
;             PG8_LDB(B1, 0, 1); PG8_STAGE(PG8_SB(0, 0), b2, voffB);
;             PG8_BAR; PG8_WAIT_L(0); PG8_MMA(0, 1, At, B1); PG8_BAR;
;             PG8_LDA(At, 0, 1); PG8_STAGE(PG8_SA(0, 0), a2, voffA);
;             PG8_BAR; PG8_WAIT_L(0); PG8_MMA(1, 0, At, B0); PG8_BAR; PG8_SCHED;
;             PG8_STAGE(PG8_SB(0, 1), b2 + hstep, voffB);
;             PG8_WAIT_V(6); PG8_BAR; PG8_MMA(1, 1, At, B1); PG8_BAR;
.Lgprio1:
.LBB0_62:
	s_add_u32 s20, s18, 0xffe00080
	s_addc_u32 s21, s19, -1
	s_add_i32 s50, 0, 0x10000
	v_add_u32_e32 v62, s50, v173
	ds_read_b128 v[42:45], v62
	ds_read_b128 v[46:49], v62 offset:1024
	ds_read_b128 v[58:61], v62 offset:2048
	ds_read_b128 v[62:65], v62 offset:3072
	s_cmpk_eq_i32 s49, 0x7c
	s_cselect_b32 s23, s13, s21
	s_cselect_b32 s22, s44, s20
	s_cselect_b32 s21, s11, s48
	s_cselect_b32 s20, s45, s47
	s_add_i32 m0, s3, 0xc000
	ds_read_b128 v[176:179], v174
	ds_read_b128 v[180:183], v174 offset:1024
	ds_read_b128 v[184:187], v174 offset:2048
	ds_read_b128 v[188:191], v174 offset:3072
	ds_read_b128 v[192:195], v174 offset:4096
	ds_read_b128 v[196:199], v174 offset:5120
	ds_read_b128 v[210:213], v174 offset:6144
	ds_read_b128 v[214:217], v174 offset:7168
	global_load_lds_dwordx4 v168, s[18:19]
	v_lshl_add_u64 v[170:171], s[18:19], 0, v[166:167]
	s_add_i32 m0, s3, 0xe000
	s_nop 0
	global_load_lds_dwordx4 v[170:171], off
	s_waitcnt lgkmcnt(8)
	s_barrier
	s_waitcnt lgkmcnt(0)
	v_mfma_f32_16x16x32_bf16 v[142:145], v[42:45], v[176:179], v[142:145]
	v_mfma_f32_16x16x32_bf16 v[138:141], v[58:61], v[176:179], v[138:141]
	v_mfma_f32_16x16x32_bf16 v[126:129], v[42:45], v[184:187], v[126:129]
	v_mfma_f32_16x16x32_bf16 v[122:125], v[58:61], v[184:187], v[122:125]
	v_mfma_f32_16x16x32_bf16 v[110:113], v[42:45], v[192:195], v[110:113]
	v_mfma_f32_16x16x32_bf16 v[106:109], v[58:61], v[192:195], v[106:109]
	v_mfma_f32_16x16x32_bf16 v[94:97], v[42:45], v[210:213], v[94:97]
	v_mfma_f32_16x16x32_bf16 v[90:93], v[58:61], v[210:213], v[90:93]
	v_mfma_f32_16x16x32_bf16 v[142:145], v[46:49], v[180:183], v[142:145]
	v_mfma_f32_16x16x32_bf16 v[138:141], v[62:65], v[180:183], v[138:141]
	v_mfma_f32_16x16x32_bf16 v[126:129], v[46:49], v[188:191], v[126:129]
	v_mfma_f32_16x16x32_bf16 v[122:125], v[62:65], v[188:191], v[122:125]
	v_mfma_f32_16x16x32_bf16 v[110:113], v[46:49], v[196:199], v[110:113]
	v_mfma_f32_16x16x32_bf16 v[106:109], v[62:65], v[196:199], v[106:109]
	v_mfma_f32_16x16x32_bf16 v[94:97], v[46:49], v[214:217], v[94:97]
	v_mfma_f32_16x16x32_bf16 v[90:93], v[62:65], v[214:217], v[90:93]
	s_barrier
	s_add_i32 s54, 0, 0x14000
	v_add_u32_e32 v170, s54, v173
	s_add_i32 s50, s50, s31
	ds_read_b128 v[218:221], v170
	ds_read_b128 v[222:225], v170 offset:1024
	ds_read_b128 v[226:229], v170 offset:2048
	ds_read_b128 v[230:233], v170 offset:3072
	v_lshl_add_u64 v[170:171], s[20:21], 0, v[0:1]
	s_mov_b32 m0, s50
	v_lshl_add_u64 v[200:201], s[20:21], 0, v[164:165]
	global_load_lds_dwordx4 v[170:171], off
	s_add_i32 m0, s50, 0x2000
	s_nop 0
	global_load_lds_dwordx4 v[200:201], off
	s_barrier
	s_waitcnt lgkmcnt(0)
	v_mfma_f32_16x16x32_bf16 v[134:137], v[218:221], v[176:179], v[134:137]
	v_mfma_f32_16x16x32_bf16 v[130:133], v[226:229], v[176:179], v[130:133]
	v_mfma_f32_16x16x32_bf16 v[118:121], v[218:221], v[184:187], v[118:121]
	v_mfma_f32_16x16x32_bf16 v[114:117], v[226:229], v[184:187], v[114:117]
	v_mfma_f32_16x16x32_bf16 v[102:105], v[218:221], v[192:195], v[102:105]
	v_mfma_f32_16x16x32_bf16 v[98:101], v[226:229], v[192:195], v[98:101]
	v_mfma_f32_16x16x32_bf16 v[86:89], v[218:221], v[210:213], v[86:89]
	v_mfma_f32_16x16x32_bf16 v[82:85], v[226:229], v[210:213], v[82:85]
	v_mfma_f32_16x16x32_bf16 v[134:137], v[222:225], v[180:183], v[134:137]
	v_mfma_f32_16x16x32_bf16 v[130:133], v[230:233], v[180:183], v[130:133]
	v_mfma_f32_16x16x32_bf16 v[118:121], v[222:225], v[188:191], v[118:121]
	v_mfma_f32_16x16x32_bf16 v[114:117], v[230:233], v[188:191], v[114:117]
	v_mfma_f32_16x16x32_bf16 v[102:105], v[222:225], v[196:199], v[102:105]
	v_mfma_f32_16x16x32_bf16 v[98:101], v[230:233], v[196:199], v[98:101]
	v_mfma_f32_16x16x32_bf16 v[86:89], v[222:225], v[214:217], v[86:89]
	v_mfma_f32_16x16x32_bf16 v[82:85], v[230:233], v[214:217], v[82:85]
	s_mov_b32 m0, s3
	v_lshl_add_u64 v[234:235], s[22:23], 0, v[160:161]
	s_barrier
	ds_read_b128 v[176:179], v174 offset:16384
	ds_read_b128 v[180:183], v174 offset:17408
	ds_read_b128 v[184:187], v174 offset:18432
	ds_read_b128 v[188:191], v174 offset:19456
	ds_read_b128 v[192:195], v174 offset:20480
	ds_read_b128 v[196:199], v174 offset:21504
	ds_read_b128 v[210:213], v174 offset:22528
	ds_read_b128 v[214:217], v174 offset:23552
	global_load_lds_dwordx4 v[234:235], off
	v_lshl_add_u64 v[236:237], s[22:23], 0, v[162:163]
	s_mov_b32 m0, s34
	s_nop 0
	global_load_lds_dwordx4 v[236:237], off
	s_barrier
	s_waitcnt lgkmcnt(0)
	v_mfma_f32_16x16x32_bf16 v[78:81], v[42:45], v[176:179], v[78:81]
	v_mfma_f32_16x16x32_bf16 v[74:77], v[58:61], v[176:179], v[74:77]
	v_mfma_f32_16x16x32_bf16 v[54:57], v[42:45], v[184:187], v[54:57]
	v_mfma_f32_16x16x32_bf16 v[50:53], v[58:61], v[184:187], v[50:53]
	v_mfma_f32_16x16x32_bf16 v[30:33], v[42:45], v[192:195], v[30:33]
	v_mfma_f32_16x16x32_bf16 v[26:29], v[58:61], v[192:195], v[26:29]
	v_mfma_f32_16x16x32_bf16 v[14:17], v[42:45], v[210:213], v[14:17]
	v_mfma_f32_16x16x32_bf16 v[10:13], v[58:61], v[210:213], v[10:13]
	v_mfma_f32_16x16x32_bf16 v[78:81], v[46:49], v[180:183], v[78:81]
	v_mfma_f32_16x16x32_bf16 v[74:77], v[62:65], v[180:183], v[74:77]
	v_mfma_f32_16x16x32_bf16 v[54:57], v[46:49], v[188:191], v[54:57]
	v_mfma_f32_16x16x32_bf16 v[50:53], v[62:65], v[188:191], v[50:53]
	v_mfma_f32_16x16x32_bf16 v[30:33], v[46:49], v[196:199], v[30:33]
	v_mfma_f32_16x16x32_bf16 v[26:29], v[62:65], v[196:199], v[26:29]
	v_mfma_f32_16x16x32_bf16 v[14:17], v[46:49], v[214:217], v[14:17]
	v_mfma_f32_16x16x32_bf16 v[10:13], v[62:65], v[214:217], v[10:13]
	s_barrier
	s_add_u32 s52, s20, 0x200000
	s_addc_u32 s53, s21, 0
	s_add_i32 s50, s54, s31
	s_mov_b32 m0, s50
	s_nop 0
	global_load_lds_dwordx4 v0, s[52:53]
	s_add_i32 m0, s50, 0x2000
	s_nop 0
	global_load_lds_dwordx4 v164, s[52:53]
	s_waitcnt vmcnt(6)
	s_barrier
; #define PG8_STAGE(bufoff, gbase, voff) do { _Pragma("unroll") for (int _i = 0; _i < 2; ++_i) \
;         __builtin_amdgcn_global_load_lds((const unsigned*)((const char*)(gbase) + (voff)[_i]), (LAS unsigned*)(lds + (bufoff) + ldsw + _i * 8192), 16, 0, 0); } while (0)
; #define PG8_LDA(dst, b, h) do { _Pragma("unroll") for (int m = 0; m < 4; ++m) _Pragma("unroll") for (int k = 0; k < 2; ++k) dst[m][k] = *(const LAS bf16x8*)(lds + PG8_SA(b, h) + aoff + m * 2048 + k * 1024); } while (0)
; #define PG8_LDB(dst, b, h) do { _Pragma("unroll") for (int n = 0; n < 2; ++n) _Pragma("unroll") for (int k = 0; k < 2; ++k) dst[n][k] = *(const LAS bf16x8*)(lds + PG8_SB(b, h) + boff + n * 2048 + k * 1024); } while (0)
; #define PG8_MMA(ai, bj, At, Bt) do { __builtin_amdgcn_s_setprio(1); _Pragma("unroll") for (int m = 0; m < 4; ++m) _Pragma("unroll") for (int n = 0; n < 2; ++n) _Pragma("unroll") for (int k = 0; k < 2; ++k) \
;         acc[ai][bj][m][n] = __builtin_amdgcn_mfma_f32_16x16x32_bf16(Bt[n][k], At[m][k], acc[ai][bj][m][n], 0, 0, 0); __builtin_amdgcn_s_setprio(0); } while (0)
; #define PG8_WAIT_V(n) asm volatile("s_waitcnt vmcnt(" #n ")" ::: "memory")
; #define PG8_WAIT_L(n) asm volatile("s_waitcnt lgkmcnt(" #n ")" ::: "memory")
; #define PG8_BAR __builtin_amdgcn_s_barrier()
; #define PG8_SCHED __builtin_amdgcn_sched_barrier(0)
; template <class Epi>
; __device__ __forceinline__ void gemm_phase(LAS unsigned char* lds, const Gemm g, const StaticOrder& S, const Epi& E, const int tid) {
;     ...
;             PG8_WAIT_V(6); PG8_BAR; PG8_MMA(1, 1, At, B1); PG8_BAR;
;             PG8_LDB(B0, 1, 0); PG8_SCHED; PG8_LDA(At, 1, 0); PG8_STAGE(PG8_SA(0, 1), a2 + hstep, voffA);
;             PG8_WAIT_L(8); PG8_BAR; PG8_WAIT_L(0); PG8_MMA(0, 0, At, B0); PG8_BAR; PG8_SCHED;
;             PG8_LDB(B1, 1, 1); PG8_STAGE(PG8_SB(1, 0), b3, voffB);
;             PG8_BAR; PG8_WAIT_L(0); PG8_MMA(0, 1, At, B1); PG8_BAR;
;             PG8_LDA(At, 1, 1); PG8_STAGE(PG8_SA(1, 0), a3, voffA);
	v_mfma_f32_16x16x32_bf16 v[38:41], v[218:221], v[184:187], v[38:41]
	v_mfma_f32_16x16x32_bf16 v[34:37], v[226:229], v[184:187], v[34:37]
	v_mfma_f32_16x16x32_bf16 v[22:25], v[218:221], v[192:195], v[22:25]
	v_mfma_f32_16x16x32_bf16 v[18:21], v[226:229], v[192:195], v[18:21]
	v_mfma_f32_16x16x32_bf16 v[6:9], v[218:221], v[210:213], v[6:9]
	v_mfma_f32_16x16x32_bf16 v[2:5], v[226:229], v[210:213], v[2:5]
	v_mfma_f32_16x16x32_bf16 v[42:45], v[218:221], v[176:179], v[70:73]
	v_mfma_f32_16x16x32_bf16 v[46:49], v[226:229], v[176:179], v[66:69]
	v_mfma_f32_16x16x32_bf16 v[38:41], v[222:225], v[188:191], v[38:41]
	v_mfma_f32_16x16x32_bf16 v[34:37], v[230:233], v[188:191], v[34:37]
	v_mfma_f32_16x16x32_bf16 v[22:25], v[222:225], v[196:199], v[22:25]
	v_mfma_f32_16x16x32_bf16 v[18:21], v[230:233], v[196:199], v[18:21]
	v_mfma_f32_16x16x32_bf16 v[6:9], v[222:225], v[214:217], v[6:9]
	v_mfma_f32_16x16x32_bf16 v[2:5], v[230:233], v[214:217], v[2:5]
	v_mfma_f32_16x16x32_bf16 v[42:45], v[222:225], v[180:183], v[42:45]
	v_mfma_f32_16x16x32_bf16 v[46:49], v[230:233], v[180:183], v[46:49]
	s_add_i32 s50, 0, 0x18000
	v_add_u32_e32 v70, s50, v173
	s_barrier
	ds_read_b128 v[58:61], v70
	ds_read_b128 v[62:65], v70 offset:1024
	ds_read_b128 v[66:69], v70 offset:2048
	ds_read_b128 v[70:73], v70 offset:3072
	s_add_u32 s22, s22, 0x200000
	s_addc_u32 s23, s23, 0
	s_mov_b32 m0, s35
	ds_read_b128 v[176:179], v174 offset:32768
	ds_read_b128 v[180:183], v174 offset:33792
	ds_read_b128 v[184:187], v174 offset:34816
	ds_read_b128 v[188:191], v174 offset:35840
	ds_read_b128 v[192:195], v174 offset:36864
	ds_read_b128 v[196:199], v174 offset:37888
	ds_read_b128 v[210:213], v174 offset:38912
	ds_read_b128 v[214:217], v174 offset:39936
	global_load_lds_dwordx4 v160, s[22:23]
	s_mov_b32 m0, s36
	s_nop 0
	global_load_lds_dwordx4 v162, s[22:23]
	s_waitcnt lgkmcnt(8)
	s_barrier
	s_waitcnt lgkmcnt(0)
	v_mfma_f32_16x16x32_bf16 v[142:145], v[58:61], v[176:179], v[142:145]
	v_mfma_f32_16x16x32_bf16 v[138:141], v[66:69], v[176:179], v[138:141]
	v_mfma_f32_16x16x32_bf16 v[126:129], v[58:61], v[184:187], v[126:129]
	v_mfma_f32_16x16x32_bf16 v[122:125], v[66:69], v[184:187], v[122:125]
	v_mfma_f32_16x16x32_bf16 v[110:113], v[58:61], v[192:195], v[110:113]
	v_mfma_f32_16x16x32_bf16 v[106:109], v[66:69], v[192:195], v[106:109]
	v_mfma_f32_16x16x32_bf16 v[94:97], v[58:61], v[210:213], v[94:97]
	v_mfma_f32_16x16x32_bf16 v[90:93], v[66:69], v[210:213], v[90:93]
	v_mfma_f32_16x16x32_bf16 v[142:145], v[62:65], v[180:183], v[142:145]
	v_mfma_f32_16x16x32_bf16 v[138:141], v[70:73], v[180:183], v[138:141]
	v_mfma_f32_16x16x32_bf16 v[126:129], v[62:65], v[188:191], v[126:129]
	v_mfma_f32_16x16x32_bf16 v[122:125], v[70:73], v[188:191], v[122:125]
	v_mfma_f32_16x16x32_bf16 v[110:113], v[62:65], v[196:199], v[110:113]
	v_mfma_f32_16x16x32_bf16 v[106:109], v[70:73], v[196:199], v[106:109]
	v_mfma_f32_16x16x32_bf16 v[94:97], v[62:65], v[214:217], v[94:97]
	v_mfma_f32_16x16x32_bf16 v[90:93], v[70:73], v[214:217], v[90:93]
	s_barrier
	s_add_i32 s22, 0, 0x1c000
	s_add_i32 s23, s50, s31
	v_add_u32_e32 v175, s22, v173
	v_lshl_add_u64 v[170:171], v[170:171], 0, s[56:57]
	s_mov_b32 m0, s23
	ds_read_b128 v[218:221], v175
	ds_read_b128 v[222:225], v175 offset:1024
	ds_read_b128 v[226:229], v175 offset:2048
	ds_read_b128 v[230:233], v175 offset:3072
	global_load_lds_dwordx4 v[170:171], off
	v_lshl_add_u64 v[170:171], v[200:201], 0, s[56:57]
	s_add_i32 m0, s23, 0x2000
	s_nop 0
	global_load_lds_dwordx4 v[170:171], off
	s_barrier
	s_waitcnt lgkmcnt(0)
	v_mfma_f32_16x16x32_bf16 v[134:137], v[218:221], v[176:179], v[134:137]
	v_mfma_f32_16x16x32_bf16 v[130:133], v[226:229], v[176:179], v[130:133]
	v_mfma_f32_16x16x32_bf16 v[118:121], v[218:221], v[184:187], v[118:121]
	v_mfma_f32_16x16x32_bf16 v[114:117], v[226:229], v[184:187], v[114:117]
	v_mfma_f32_16x16x32_bf16 v[102:105], v[218:221], v[192:195], v[102:105]
	v_mfma_f32_16x16x32_bf16 v[98:101], v[226:229], v[192:195], v[98:101]
	v_mfma_f32_16x16x32_bf16 v[86:89], v[218:221], v[210:213], v[86:89]
	v_mfma_f32_16x16x32_bf16 v[82:85], v[226:229], v[210:213], v[82:85]
	v_mfma_f32_16x16x32_bf16 v[134:137], v[222:225], v[180:183], v[134:137]
	v_mfma_f32_16x16x32_bf16 v[130:133], v[230:233], v[180:183], v[130:133]
	v_mfma_f32_16x16x32_bf16 v[118:121], v[222:225], v[188:191], v[118:121]
	v_mfma_f32_16x16x32_bf16 v[114:117], v[230:233], v[188:191], v[114:117]
	v_mfma_f32_16x16x32_bf16 v[102:105], v[222:225], v[196:199], v[102:105]
	v_mfma_f32_16x16x32_bf16 v[98:101], v[230:233], v[196:199], v[98:101]
	v_mfma_f32_16x16x32_bf16 v[86:89], v[222:225], v[214:217], v[86:89]
	v_mfma_f32_16x16x32_bf16 v[82:85], v[230:233], v[214:217], v[82:85]
	s_mov_b32 m0, s39
	v_lshl_add_u64 v[170:171], v[234:235], 0, s[56:57]
	s_barrier
	ds_read_b128 v[176:179], v174 offset:49152
	ds_read_b128 v[180:183], v174 offset:50176
	ds_read_b128 v[184:187], v174 offset:51200
	ds_read_b128 v[188:191], v174 offset:52224
	ds_read_b128 v[192:195], v174 offset:53248
	ds_read_b128 v[196:199], v174 offset:54272
	ds_read_b128 v[210:213], v174 offset:55296
	ds_read_b128 v[214:217], v174 offset:56320
	global_load_lds_dwordx4 v[170:171], off
	v_lshl_add_u64 v[170:171], v[236:237], 0, s[56:57]
	s_mov_b32 m0, s40
	s_nop 0
	global_load_lds_dwordx4 v[170:171], off
	s_barrier
; __device__ __forceinline__ unsigned pk2(float lo, float hi) { f32x2 v = {lo, hi}; return __builtin_bit_cast(unsigned, __builtin_convertvector(v, bf16x2_t)); }
; __device__ __forceinline__ float bf_lo(unsigned w) { return __uint_as_float(w << 16); }
; __device__ __forceinline__ float bf_hi(unsigned w) { return __uint_as_float(w & 0xffff0000u); }
;     __device__ __forceinline__ void operator()(const f32x4 (&acc)[2][2][4][2], const Unit& u, int wr, int wc, int fr, int fq) const {
;     ...
;         const int row0 = u.pm * BM + wr * 64 + fr, col0 = u.pn * BM + wc * 32 + 8 * fq;
;         const float* gp = gate + (size_t)(u.pm >> 5) * 12288 + col0;
;         f32x4 gv[2][2];
; #pragma unroll
;         for (int bj = 0; bj < 2; ++bj)
; #pragma unroll
;             for (int n = 0; n < 2; ++n) gv[bj][n] = *(const f32x4*)(gp + bj * HALF + 4 * n);
; #pragma unroll
;         for (int ai = 0; ai < 2; ++ai)
; #pragma unroll
;             for (int m = 0; m < 4; ++m) {
;                 const size_t ro = (size_t)(row0 + ai * HALF + m * 16) * DM + col0;
; #pragma unroll
;                 for (int bj = 0; bj < 2; ++bj) {
;                     f32x4 r0, r1;
;                     if (RB) { const u32x4 rw = *(const u32x4*)((const bf16_t*)resid + ro + bj * HALF);
;                         r0 = (f32x4){bf_lo(rw.x), bf_hi(rw.x), bf_lo(rw.y), bf_hi(rw.y)}; r1 = (f32x4){bf_lo(rw.z), bf_hi(rw.z), bf_lo(rw.w), bf_hi(rw.w)}; }
;                     else { r0 = *(const f32x4*)((const float*)resid + ro + bj * HALF); r1 = *(const f32x4*)((const float*)resid + ro + bj * HALF + 4); }
;                     const f32x4 v0 = r0 + gv[bj][0] * acc[ai][bj][m][0], v1 = r1 + gv[bj][1] * acc[ai][bj][m][1];
;                     if (OB) { u32x4 w; w.x = pk2(v0[0], v0[1]); w.y = pk2(v0[2], v0[3]); w.z = pk2(v1[0], v1[1]); w.w = pk2(v1[2], v1[3]); *(u32x4*)((bf16_t*)out + ro + bj * HALF) = w; }
;                     else { *(f32x4*)((float*)out + ro + bj * HALF) = v0; *(f32x4*)((float*)out + ro + bj * HALF + 4) = v1; }
; template <class Epi>
; __device__ __forceinline__ void gemm_phase(LAS unsigned char* lds, const Gemm g, const StaticOrder& S, const Epi& E, const int tid) {
;     ...
;             PG8_BAR; PG8_WAIT_L(0); PG8_MMA(1, 0, At, B0); PG8_BAR; PG8_SCHED;
;             PG8_STAGE(PG8_SB(1, 1), b3 + hstep, voffB);
;             PG8_WAIT_V(6); PG8_BAR; PG8_MMA(1, 1, At, B1); PG8_BAR;
	s_waitcnt lgkmcnt(0)
	v_mfma_f32_16x16x32_bf16 v[78:81], v[58:61], v[176:179], v[78:81]
	v_mfma_f32_16x16x32_bf16 v[74:77], v[66:69], v[176:179], v[74:77]
	v_mfma_f32_16x16x32_bf16 v[54:57], v[58:61], v[184:187], v[54:57]
	v_mfma_f32_16x16x32_bf16 v[50:53], v[66:69], v[184:187], v[50:53]
	v_mfma_f32_16x16x32_bf16 v[30:33], v[58:61], v[192:195], v[30:33]
	v_mfma_f32_16x16x32_bf16 v[26:29], v[66:69], v[192:195], v[26:29]
	v_mfma_f32_16x16x32_bf16 v[14:17], v[58:61], v[210:213], v[14:17]
	v_mfma_f32_16x16x32_bf16 v[10:13], v[66:69], v[210:213], v[10:13]
	v_mfma_f32_16x16x32_bf16 v[78:81], v[62:65], v[180:183], v[78:81]
	v_mfma_f32_16x16x32_bf16 v[74:77], v[70:73], v[180:183], v[74:77]
	v_mfma_f32_16x16x32_bf16 v[54:57], v[62:65], v[188:191], v[54:57]
	v_mfma_f32_16x16x32_bf16 v[50:53], v[70:73], v[188:191], v[50:53]
	v_mfma_f32_16x16x32_bf16 v[30:33], v[62:65], v[196:199], v[30:33]
	v_mfma_f32_16x16x32_bf16 v[26:29], v[70:73], v[196:199], v[26:29]
	v_mfma_f32_16x16x32_bf16 v[14:17], v[62:65], v[214:217], v[14:17]
	v_mfma_f32_16x16x32_bf16 v[10:13], v[70:73], v[214:217], v[10:13]
	s_barrier
	s_add_u32 s20, s20, 0x200080
	s_addc_u32 s21, s21, 0
	s_add_i32 s22, s22, s31
	s_mov_b32 m0, s22
	s_nop 0
	global_load_lds_dwordx4 v0, s[20:21]
	s_add_i32 m0, s22, 0x2000
	s_nop 0
	global_load_lds_dwordx4 v164, s[20:21]
	s_waitcnt vmcnt(6)
	s_barrier
	v_mfma_f32_16x16x32_bf16 v[42:45], v[218:221], v[176:179], v[42:45]
	v_mfma_f32_16x16x32_bf16 v[70:73], v[222:225], v[180:183], v[42:45]
	v_mfma_f32_16x16x32_bf16 v[42:45], v[226:229], v[176:179], v[46:49]
	v_mfma_f32_16x16x32_bf16 v[38:41], v[218:221], v[184:187], v[38:41]
	v_mfma_f32_16x16x32_bf16 v[34:37], v[226:229], v[184:187], v[34:37]
	v_mfma_f32_16x16x32_bf16 v[22:25], v[218:221], v[192:195], v[22:25]
	v_mfma_f32_16x16x32_bf16 v[18:21], v[226:229], v[192:195], v[18:21]
	v_mfma_f32_16x16x32_bf16 v[6:9], v[218:221], v[210:213], v[6:9]
	v_mfma_f32_16x16x32_bf16 v[2:5], v[226:229], v[210:213], v[2:5]
	v_mfma_f32_16x16x32_bf16 v[66:69], v[230:233], v[180:183], v[42:45]
	v_mfma_f32_16x16x32_bf16 v[38:41], v[222:225], v[188:191], v[38:41]
	v_mfma_f32_16x16x32_bf16 v[34:37], v[230:233], v[188:191], v[34:37]
	v_mfma_f32_16x16x32_bf16 v[22:25], v[222:225], v[196:199], v[22:25]
	v_mfma_f32_16x16x32_bf16 v[18:21], v[230:233], v[196:199], v[18:21]
	v_mfma_f32_16x16x32_bf16 v[6:9], v[222:225], v[214:217], v[6:9]
	v_mfma_f32_16x16x32_bf16 v[2:5], v[230:233], v[214:217], v[2:5]
	s_add_i32 s49, s49, 2
	s_add_u32 s47, s47, 0x100
	s_addc_u32 s48, s48, 0
	s_add_u32 s18, s18, 0x100
	s_addc_u32 s19, s19, 0
	s_cmpk_gt_u32 s49, 0x7d
	s_barrier
	s_cbranch_scc0 .LBB0_62
	s_setprio 0
	s_lshl_b32 s11, s2, 8
	s_lshl_b32 s13, s43, 8
	v_mov_b32_e32 v175, v172
	v_mov_b32_e32 v42, v159
	s_add_i32 s11, s11, s37
	s_or_b32 s13, s13, s38
	s_ashr_i32 s2, s2, 5
	s_mov_b32 s43, s10
	v_lshl_add_u32 v170, v42, 3, s13
	s_mul_hi_i32 s13, s2, 0xc000
	s_mul_i32 s2, s2, 0xc000
	v_add_u32_e32 v176, s11, v175
	s_add_u32 s18, s27, s2
	v_ashrrev_i32_e32 v177, 31, v176
	s_addc_u32 s19, s28, s13
	v_ashrrev_i32_e32 v171, 31, v170
	v_lshlrev_b64 v[176:177], 11, v[176:177]
	v_lshl_add_u64 v[46:47], v[170:171], 2, s[18:19]
	v_lshl_add_u64 v[170:171], v[176:177], 0, v[170:171]
	v_lshlrev_b64 v[170:171], 1, v[170:171]
	v_lshl_add_u64 v[180:181], s[8:9], 0, v[170:171]
	global_load_dwordx4 v[58:61], v[46:47], off offset:16
	global_load_dwordx4 v[62:65], v[46:47], off
	global_load_dwordx4 v[42:45], v[46:47], off offset:528
	s_nop 0
	global_load_dwordx4 v[46:49], v[46:47], off offset:512
	s_mov_b64 s[92:93], s[8:9]
	s_mov_b64 s[94:95], s[6:7]
	global_load_dwordx4 v[184:187], v170, s[92:93]
	global_load_dwordx4 v[188:191], v170, s[92:93] offset:256
	s_add_u32 s92, s92, 0x10000
	s_addc_u32 s93, s93, 0
	global_load_dwordx4 v[192:195], v170, s[92:93]
	global_load_dwordx4 v[196:199], v170, s[92:93] offset:256
	s_add_u32 s92, s92, 0x10000
	s_addc_u32 s93, s93, 0
	global_load_dwordx4 v[210:213], v170, s[92:93]
	global_load_dwordx4 v[214:217], v170, s[92:93] offset:256
	s_add_u32 s92, s92, 0x10000
	s_addc_u32 s93, s93, 0
	global_load_dwordx4 v[218:221], v170, s[92:93]
	global_load_dwordx4 v[222:225], v170, s[92:93] offset:256
	s_add_u32 s92, s92, 0x50000
	s_addc_u32 s93, s93, 0
	global_load_dwordx4 v[226:229], v170, s[92:93]
	global_load_dwordx4 v[230:233], v170, s[92:93] offset:256
	s_add_u32 s92, s92, 0x10000
	s_addc_u32 s93, s93, 0
	global_load_dwordx4 v[234:237], v170, s[92:93]
	s_waitcnt vmcnt(10)
	v_lshlrev_b32_e32 v176, 16, v184
	v_and_b32_e32 v177, 0xffff0000, v184
	v_lshlrev_b32_e32 v178, 16, v185
	v_and_b32_e32 v179, 0xffff0000, v185
	v_lshlrev_b32_e32 v180, 16, v186
	v_and_b32_e32 v181, 0xffff0000, v186
	v_lshlrev_b32_e32 v182, 16, v187
	v_and_b32_e32 v183, 0xffff0000, v187
	v_pk_fma_f32 v[142:143], v[142:143], v[62:63], v[176:177]
	v_pk_fma_f32 v[144:145], v[144:145], v[64:65], v[178:179]
	v_pk_fma_f32 v[138:139], v[138:139], v[58:59], v[180:181]
	v_pk_fma_f32 v[140:141], v[140:141], v[60:61], v[182:183]
	global_load_dwordx4 v[184:187], v170, s[92:93] offset:256
	v_cvt_pk_bf16_f32 v142, v142, v143
	v_cvt_pk_bf16_f32 v143, v144, v145
	v_cvt_pk_bf16_f32 v144, v138, v139
	v_cvt_pk_bf16_f32 v145, v140, v141
	global_store_dwordx4 v170, v[142:145], s[94:95]
	s_waitcnt vmcnt(11)
; __device__ __forceinline__ unsigned pk2(float lo, float hi) { f32x2 v = {lo, hi}; return __builtin_bit_cast(unsigned, __builtin_convertvector(v, bf16x2_t)); }
; __device__ __forceinline__ float bf_lo(unsigned w) { return __uint_as_float(w << 16); }
; __device__ __forceinline__ float bf_hi(unsigned w) { return __uint_as_float(w & 0xffff0000u); }
;     __device__ __forceinline__ void operator()(const f32x4 (&acc)[2][2][4][2], const Unit& u, int wr, int wc, int fr, int fq) const {
;     ...
;                 for (int bj = 0; bj < 2; ++bj) {
;                     f32x4 r0, r1;
;                     if (RB) { const u32x4 rw = *(const u32x4*)((const bf16_t*)resid + ro + bj * HALF);
;                         r0 = (f32x4){bf_lo(rw.x), bf_hi(rw.x), bf_lo(rw.y), bf_hi(rw.y)}; r1 = (f32x4){bf_lo(rw.z), bf_hi(rw.z), bf_lo(rw.w), bf_hi(rw.w)}; }
;                     else { r0 = *(const f32x4*)((const float*)resid + ro + bj * HALF); r1 = *(const f32x4*)((const float*)resid + ro + bj * HALF + 4); }
;                     const f32x4 v0 = r0 + gv[bj][0] * acc[ai][bj][m][0], v1 = r1 + gv[bj][1] * acc[ai][bj][m][1];
;                     if (OB) { u32x4 w; w.x = pk2(v0[0], v0[1]); w.y = pk2(v0[2], v0[3]); w.z = pk2(v1[0], v1[1]); w.w = pk2(v1[2], v1[3]); *(u32x4*)((bf16_t*)out + ro + bj * HALF) = w; }
;                     else { *(f32x4*)((float*)out + ro + bj * HALF) = v0; *(f32x4*)((float*)out + ro + bj * HALF + 4) = v1; }
	v_lshlrev_b32_e32 v176, 16, v188
	v_and_b32_e32 v177, 0xffff0000, v188
	v_lshlrev_b32_e32 v178, 16, v189
	v_and_b32_e32 v179, 0xffff0000, v189
	v_lshlrev_b32_e32 v180, 16, v190
	v_and_b32_e32 v181, 0xffff0000, v190
	v_lshlrev_b32_e32 v182, 16, v191
	v_and_b32_e32 v183, 0xffff0000, v191
	v_pk_fma_f32 v[134:135], v[134:135], v[46:47], v[176:177]
	v_pk_fma_f32 v[136:137], v[136:137], v[48:49], v[178:179]
	v_pk_fma_f32 v[130:131], v[130:131], v[42:43], v[180:181]
	v_pk_fma_f32 v[132:133], v[132:133], v[44:45], v[182:183]
	s_add_u32 s92, s92, 0x10000
	s_addc_u32 s93, s93, 0
	global_load_dwordx4 v[188:191], v170, s[92:93]
	v_cvt_pk_bf16_f32 v134, v134, v135
	v_cvt_pk_bf16_f32 v135, v136, v137
	v_cvt_pk_bf16_f32 v136, v130, v131
	v_cvt_pk_bf16_f32 v137, v132, v133
	global_store_dwordx4 v170, v[134:137], s[94:95] offset:256
	s_waitcnt vmcnt(12)
	v_lshlrev_b32_e32 v176, 16, v192
	v_and_b32_e32 v177, 0xffff0000, v192
	v_lshlrev_b32_e32 v178, 16, v193
	v_and_b32_e32 v179, 0xffff0000, v193
	v_lshlrev_b32_e32 v180, 16, v194
	v_and_b32_e32 v181, 0xffff0000, v194
	v_lshlrev_b32_e32 v182, 16, v195
	v_and_b32_e32 v183, 0xffff0000, v195
	v_pk_fma_f32 v[126:127], v[126:127], v[62:63], v[176:177]
	v_pk_fma_f32 v[128:129], v[128:129], v[64:65], v[178:179]
	v_pk_fma_f32 v[122:123], v[122:123], v[58:59], v[180:181]
	v_pk_fma_f32 v[124:125], v[124:125], v[60:61], v[182:183]
	global_load_dwordx4 v[192:195], v170, s[92:93] offset:256
	s_add_u32 s94, s94, 0x10000
	s_addc_u32 s95, s95, 0
	v_cvt_pk_bf16_f32 v126, v126, v127
	v_cvt_pk_bf16_f32 v127, v128, v129
	v_cvt_pk_bf16_f32 v128, v122, v123
	v_cvt_pk_bf16_f32 v129, v124, v125
	global_store_dwordx4 v170, v[126:129], s[94:95]
	s_waitcnt vmcnt(13)
	v_lshlrev_b32_e32 v176, 16, v196
	v_and_b32_e32 v177, 0xffff0000, v196
	v_lshlrev_b32_e32 v178, 16, v197
	v_and_b32_e32 v179, 0xffff0000, v197
	v_lshlrev_b32_e32 v180, 16, v198
	v_and_b32_e32 v181, 0xffff0000, v198
	v_lshlrev_b32_e32 v182, 16, v199
	v_and_b32_e32 v183, 0xffff0000, v199
	v_pk_fma_f32 v[118:119], v[118:119], v[46:47], v[176:177]
	v_pk_fma_f32 v[120:121], v[120:121], v[48:49], v[178:179]
	v_pk_fma_f32 v[114:115], v[114:115], v[42:43], v[180:181]
	v_pk_fma_f32 v[116:117], v[116:117], v[44:45], v[182:183]
	s_add_u32 s92, s92, 0x10000
	s_addc_u32 s93, s93, 0
	global_load_dwordx4 v[196:199], v170, s[92:93]
	v_cvt_pk_bf16_f32 v118, v118, v119
	v_cvt_pk_bf16_f32 v119, v120, v121
	v_cvt_pk_bf16_f32 v120, v114, v115
	v_cvt_pk_bf16_f32 v121, v116, v117
	global_store_dwordx4 v170, v[118:121], s[94:95] offset:256
	s_waitcnt vmcnt(14)
	v_lshlrev_b32_e32 v176, 16, v210
	v_and_b32_e32 v177, 0xffff0000, v210
	v_lshlrev_b32_e32 v178, 16, v211
	v_and_b32_e32 v179, 0xffff0000, v211
	v_lshlrev_b32_e32 v180, 16, v212
	v_and_b32_e32 v181, 0xffff0000, v212
	v_lshlrev_b32_e32 v182, 16, v213
	v_and_b32_e32 v183, 0xffff0000, v213
	v_pk_fma_f32 v[110:111], v[110:111], v[62:63], v[176:177]
	v_pk_fma_f32 v[112:113], v[112:113], v[64:65], v[178:179]
	v_pk_fma_f32 v[106:107], v[106:107], v[58:59], v[180:181]
	v_pk_fma_f32 v[108:109], v[108:109], v[60:61], v[182:183]
	global_load_dwordx4 v[210:213], v170, s[92:93] offset:256
	s_add_u32 s94, s94, 0x10000
	s_addc_u32 s95, s95, 0
	v_cvt_pk_bf16_f32 v110, v110, v111
	v_cvt_pk_bf16_f32 v111, v112, v113
	v_cvt_pk_bf16_f32 v112, v106, v107
	v_cvt_pk_bf16_f32 v113, v108, v109
	global_store_dwordx4 v170, v[110:113], s[94:95]
	s_waitcnt vmcnt(15)
	v_lshlrev_b32_e32 v176, 16, v214
	v_and_b32_e32 v177, 0xffff0000, v214
	v_lshlrev_b32_e32 v178, 16, v215
	v_and_b32_e32 v179, 0xffff0000, v215
	v_lshlrev_b32_e32 v180, 16, v216
	v_and_b32_e32 v181, 0xffff0000, v216
	v_lshlrev_b32_e32 v182, 16, v217
	v_and_b32_e32 v183, 0xffff0000, v217
	v_pk_fma_f32 v[102:103], v[102:103], v[46:47], v[176:177]
	v_pk_fma_f32 v[104:105], v[104:105], v[48:49], v[178:179]
	v_pk_fma_f32 v[98:99], v[98:99], v[42:43], v[180:181]
	v_pk_fma_f32 v[100:101], v[100:101], v[44:45], v[182:183]
	v_cvt_pk_bf16_f32 v102, v102, v103
	v_cvt_pk_bf16_f32 v103, v104, v105
	v_cvt_pk_bf16_f32 v104, v98, v99
	v_cvt_pk_bf16_f32 v105, v100, v101
	global_store_dwordx4 v170, v[102:105], s[94:95] offset:256
	s_waitcnt vmcnt(15)
	v_lshlrev_b32_e32 v176, 16, v218
	v_and_b32_e32 v177, 0xffff0000, v218
	v_lshlrev_b32_e32 v178, 16, v219
	v_and_b32_e32 v179, 0xffff0000, v219
	v_lshlrev_b32_e32 v180, 16, v220
	v_and_b32_e32 v181, 0xffff0000, v220
	v_lshlrev_b32_e32 v182, 16, v221
	v_and_b32_e32 v183, 0xffff0000, v221
	v_pk_fma_f32 v[94:95], v[94:95], v[62:63], v[176:177]
	v_pk_fma_f32 v[96:97], v[96:97], v[64:65], v[178:179]
	v_pk_fma_f32 v[90:91], v[90:91], v[58:59], v[180:181]
	v_pk_fma_f32 v[92:93], v[92:93], v[60:61], v[182:183]
	s_add_u32 s94, s94, 0x10000
	s_addc_u32 s95, s95, 0
	v_cvt_pk_bf16_f32 v94, v94, v95
	v_cvt_pk_bf16_f32 v95, v96, v97
	v_cvt_pk_bf16_f32 v96, v90, v91
	v_cvt_pk_bf16_f32 v97, v92, v93
	global_store_dwordx4 v170, v[94:97], s[94:95]
	s_waitcnt vmcnt(15)
	v_lshlrev_b32_e32 v176, 16, v222
	v_and_b32_e32 v177, 0xffff0000, v222
	v_lshlrev_b32_e32 v178, 16, v223
	v_and_b32_e32 v179, 0xffff0000, v223
	v_lshlrev_b32_e32 v180, 16, v224
	v_and_b32_e32 v181, 0xffff0000, v224
	v_lshlrev_b32_e32 v182, 16, v225
	v_and_b32_e32 v183, 0xffff0000, v225
	v_pk_fma_f32 v[86:87], v[86:87], v[46:47], v[176:177]
	v_pk_fma_f32 v[88:89], v[88:89], v[48:49], v[178:179]
	v_pk_fma_f32 v[82:83], v[82:83], v[42:43], v[180:181]
	v_pk_fma_f32 v[84:85], v[84:85], v[44:45], v[182:183]
	v_cvt_pk_bf16_f32 v86, v86, v87
	v_cvt_pk_bf16_f32 v87, v88, v89
	v_cvt_pk_bf16_f32 v88, v82, v83
	v_cvt_pk_bf16_f32 v89, v84, v85
	global_store_dwordx4 v170, v[86:89], s[94:95] offset:256
	s_waitcnt vmcnt(15)
; __device__ __forceinline__ unsigned pk2(float lo, float hi) { f32x2 v = {lo, hi}; return __builtin_bit_cast(unsigned, __builtin_convertvector(v, bf16x2_t)); }
; __device__ __forceinline__ float bf_lo(unsigned w) { return __uint_as_float(w << 16); }
; __device__ __forceinline__ float bf_hi(unsigned w) { return __uint_as_float(w & 0xffff0000u); }
; #define PG8_WAIT_V(n) asm volatile("s_waitcnt vmcnt(" #n ")" ::: "memory")
; #define PG8_BAR __builtin_amdgcn_s_barrier()
;     __device__ __forceinline__ void operator()(const f32x4 (&acc)[2][2][4][2], const Unit& u, int wr, int wc, int fr, int fq) const {
;     ...
;                 for (int bj = 0; bj < 2; ++bj) {
;                     f32x4 r0, r1;
;                     if (RB) { const u32x4 rw = *(const u32x4*)((const bf16_t*)resid + ro + bj * HALF);
;                         r0 = (f32x4){bf_lo(rw.x), bf_hi(rw.x), bf_lo(rw.y), bf_hi(rw.y)}; r1 = (f32x4){bf_lo(rw.z), bf_hi(rw.z), bf_lo(rw.w), bf_hi(rw.w)}; }
;                     else { r0 = *(const f32x4*)((const float*)resid + ro + bj * HALF); r1 = *(const f32x4*)((const float*)resid + ro + bj * HALF + 4); }
;                     const f32x4 v0 = r0 + gv[bj][0] * acc[ai][bj][m][0], v1 = r1 + gv[bj][1] * acc[ai][bj][m][1];
;                     if (OB) { u32x4 w; w.x = pk2(v0[0], v0[1]); w.y = pk2(v0[2], v0[3]); w.z = pk2(v1[0], v1[1]); w.w = pk2(v1[2], v1[3]); *(u32x4*)((bf16_t*)out + ro + bj * HALF) = w; }
;                     else { *(f32x4*)((float*)out + ro + bj * HALF) = v0; *(f32x4*)((float*)out + ro + bj * HALF + 4) = v1; }
; template <class Epi>
; __device__ __forceinline__ void gemm_phase(LAS unsigned char* lds, const Gemm g, const StaticOrder& S, const Epi& E, const int tid) {
;     ...
;         E(acc, cur, wr, wc, fr, fq);
;         if (!has_next) break;
; #pragma unroll
;         for (int a = 0; a < 2; ++a)
; #pragma unroll
;             for (int b = 0; b < 2; ++b)
; #pragma unroll
;                 for (int m = 0; m < 4; ++m)
; #pragma unroll
;                     for (int n = 0; n < 2; ++n) acc[a][b][m][n] = (f32x4){0.f, 0.f, 0.f, 0.f};
;         cur = nxt; cA = nA; cB = nB; ++ui;
;     }
;     PG8_WAIT_V(0);
;     if (wr == 0) PG8_BAR;
	v_lshlrev_b32_e32 v176, 16, v226
	v_and_b32_e32 v177, 0xffff0000, v226
	v_lshlrev_b32_e32 v178, 16, v227
	v_and_b32_e32 v179, 0xffff0000, v227
	v_lshlrev_b32_e32 v180, 16, v228
	v_and_b32_e32 v181, 0xffff0000, v228
	v_lshlrev_b32_e32 v182, 16, v229
	v_and_b32_e32 v183, 0xffff0000, v229
	v_pk_fma_f32 v[78:79], v[78:79], v[62:63], v[176:177]
	v_pk_fma_f32 v[80:81], v[80:81], v[64:65], v[178:179]
	v_pk_fma_f32 v[74:75], v[74:75], v[58:59], v[180:181]
	v_pk_fma_f32 v[76:77], v[76:77], v[60:61], v[182:183]
	s_add_u32 s94, s94, 0x50000
	s_addc_u32 s95, s95, 0
	v_cvt_pk_bf16_f32 v78, v78, v79
	v_cvt_pk_bf16_f32 v79, v80, v81
	v_cvt_pk_bf16_f32 v80, v74, v75
	v_cvt_pk_bf16_f32 v81, v76, v77
	global_store_dwordx4 v170, v[78:81], s[94:95]
	s_waitcnt vmcnt(15)
	v_lshlrev_b32_e32 v176, 16, v230
	v_and_b32_e32 v177, 0xffff0000, v230
	v_lshlrev_b32_e32 v178, 16, v231
	v_and_b32_e32 v179, 0xffff0000, v231
	v_lshlrev_b32_e32 v180, 16, v232
	v_and_b32_e32 v181, 0xffff0000, v232
	v_lshlrev_b32_e32 v182, 16, v233
	v_and_b32_e32 v183, 0xffff0000, v233
	v_pk_fma_f32 v[70:71], v[70:71], v[46:47], v[176:177]
	v_pk_fma_f32 v[72:73], v[72:73], v[48:49], v[178:179]
	v_pk_fma_f32 v[66:67], v[66:67], v[42:43], v[180:181]
	v_pk_fma_f32 v[68:69], v[68:69], v[44:45], v[182:183]
	v_cvt_pk_bf16_f32 v70, v70, v71
	v_cvt_pk_bf16_f32 v71, v72, v73
	v_cvt_pk_bf16_f32 v72, v66, v67
	v_cvt_pk_bf16_f32 v73, v68, v69
	global_store_dwordx4 v170, v[70:73], s[94:95] offset:256
	s_waitcnt vmcnt(15)
	v_lshlrev_b32_e32 v176, 16, v234
	v_and_b32_e32 v177, 0xffff0000, v234
	v_lshlrev_b32_e32 v178, 16, v235
	v_and_b32_e32 v179, 0xffff0000, v235
	v_lshlrev_b32_e32 v180, 16, v236
	v_and_b32_e32 v181, 0xffff0000, v236
	v_lshlrev_b32_e32 v182, 16, v237
	v_and_b32_e32 v183, 0xffff0000, v237
	v_pk_fma_f32 v[54:55], v[54:55], v[62:63], v[176:177]
	v_pk_fma_f32 v[56:57], v[56:57], v[64:65], v[178:179]
	v_pk_fma_f32 v[50:51], v[50:51], v[58:59], v[180:181]
	v_pk_fma_f32 v[52:53], v[52:53], v[60:61], v[182:183]
	s_add_u32 s94, s94, 0x10000
	s_addc_u32 s95, s95, 0
	v_cvt_pk_bf16_f32 v54, v54, v55
	v_cvt_pk_bf16_f32 v55, v56, v57
	v_cvt_pk_bf16_f32 v56, v50, v51
	v_cvt_pk_bf16_f32 v57, v52, v53
	global_store_dwordx4 v170, v[54:57], s[94:95]
	s_waitcnt vmcnt(15)
	v_lshlrev_b32_e32 v176, 16, v184
	v_and_b32_e32 v177, 0xffff0000, v184
	v_lshlrev_b32_e32 v178, 16, v185
	v_and_b32_e32 v179, 0xffff0000, v185
	v_lshlrev_b32_e32 v180, 16, v186
	v_and_b32_e32 v181, 0xffff0000, v186
	v_lshlrev_b32_e32 v182, 16, v187
	v_and_b32_e32 v183, 0xffff0000, v187
	v_pk_fma_f32 v[38:39], v[38:39], v[46:47], v[176:177]
	v_pk_fma_f32 v[40:41], v[40:41], v[48:49], v[178:179]
	v_pk_fma_f32 v[34:35], v[34:35], v[42:43], v[180:181]
	v_pk_fma_f32 v[36:37], v[36:37], v[44:45], v[182:183]
	v_cvt_pk_bf16_f32 v38, v38, v39
	v_cvt_pk_bf16_f32 v39, v40, v41
	v_cvt_pk_bf16_f32 v40, v34, v35
	v_cvt_pk_bf16_f32 v41, v36, v37
	global_store_dwordx4 v170, v[38:41], s[94:95] offset:256
	s_waitcnt vmcnt(14)
	v_lshlrev_b32_e32 v176, 16, v188
	v_and_b32_e32 v177, 0xffff0000, v188
	v_lshlrev_b32_e32 v178, 16, v189
	v_and_b32_e32 v179, 0xffff0000, v189
	v_lshlrev_b32_e32 v180, 16, v190
	v_and_b32_e32 v181, 0xffff0000, v190
	v_lshlrev_b32_e32 v182, 16, v191
	v_and_b32_e32 v183, 0xffff0000, v191
	v_pk_fma_f32 v[30:31], v[30:31], v[62:63], v[176:177]
	v_pk_fma_f32 v[32:33], v[32:33], v[64:65], v[178:179]
	v_pk_fma_f32 v[26:27], v[26:27], v[58:59], v[180:181]
	v_pk_fma_f32 v[28:29], v[28:29], v[60:61], v[182:183]
	s_add_u32 s94, s94, 0x10000
	s_addc_u32 s95, s95, 0
	v_cvt_pk_bf16_f32 v30, v30, v31
	v_cvt_pk_bf16_f32 v31, v32, v33
	v_cvt_pk_bf16_f32 v32, v26, v27
	v_cvt_pk_bf16_f32 v33, v28, v29
	global_store_dwordx4 v170, v[30:33], s[94:95]
	s_waitcnt vmcnt(13)
	v_lshlrev_b32_e32 v176, 16, v192
	v_and_b32_e32 v177, 0xffff0000, v192
	v_lshlrev_b32_e32 v178, 16, v193
	v_and_b32_e32 v179, 0xffff0000, v193
	v_lshlrev_b32_e32 v180, 16, v194
	v_and_b32_e32 v181, 0xffff0000, v194
	v_lshlrev_b32_e32 v182, 16, v195
	v_and_b32_e32 v183, 0xffff0000, v195
	v_pk_fma_f32 v[22:23], v[22:23], v[46:47], v[176:177]
	v_pk_fma_f32 v[24:25], v[24:25], v[48:49], v[178:179]
	v_pk_fma_f32 v[18:19], v[18:19], v[42:43], v[180:181]
	v_pk_fma_f32 v[20:21], v[20:21], v[44:45], v[182:183]
	v_cvt_pk_bf16_f32 v22, v22, v23
	v_cvt_pk_bf16_f32 v23, v24, v25
	v_cvt_pk_bf16_f32 v24, v18, v19
	v_cvt_pk_bf16_f32 v25, v20, v21
	global_store_dwordx4 v170, v[22:25], s[94:95] offset:256
	s_waitcnt vmcnt(12)
	v_lshlrev_b32_e32 v176, 16, v196
	v_and_b32_e32 v177, 0xffff0000, v196
	v_lshlrev_b32_e32 v178, 16, v197
	v_and_b32_e32 v179, 0xffff0000, v197
	v_lshlrev_b32_e32 v180, 16, v198
	v_and_b32_e32 v181, 0xffff0000, v198
	v_lshlrev_b32_e32 v182, 16, v199
	v_and_b32_e32 v183, 0xffff0000, v199
	v_pk_fma_f32 v[14:15], v[14:15], v[62:63], v[176:177]
	v_pk_fma_f32 v[16:17], v[16:17], v[64:65], v[178:179]
	v_pk_fma_f32 v[10:11], v[10:11], v[58:59], v[180:181]
	v_pk_fma_f32 v[12:13], v[12:13], v[60:61], v[182:183]
	s_add_u32 s94, s94, 0x10000
	s_addc_u32 s95, s95, 0
	v_cvt_pk_bf16_f32 v14, v14, v15
	v_cvt_pk_bf16_f32 v15, v16, v17
	v_cvt_pk_bf16_f32 v16, v10, v11
	v_cvt_pk_bf16_f32 v17, v12, v13
	global_store_dwordx4 v170, v[14:17], s[94:95]
	s_waitcnt vmcnt(11)
	v_lshlrev_b32_e32 v176, 16, v210
	v_and_b32_e32 v177, 0xffff0000, v210
	v_lshlrev_b32_e32 v178, 16, v211
	v_and_b32_e32 v179, 0xffff0000, v211
	v_lshlrev_b32_e32 v180, 16, v212
	v_and_b32_e32 v181, 0xffff0000, v212
	v_lshlrev_b32_e32 v182, 16, v213
	v_and_b32_e32 v183, 0xffff0000, v213
	v_pk_fma_f32 v[6:7], v[6:7], v[46:47], v[176:177]
	v_pk_fma_f32 v[8:9], v[8:9], v[48:49], v[178:179]
	v_pk_fma_f32 v[2:3], v[2:3], v[42:43], v[180:181]
	v_pk_fma_f32 v[4:5], v[4:5], v[44:45], v[182:183]
	v_cvt_pk_bf16_f32 v6, v6, v7
	v_cvt_pk_bf16_f32 v7, v8, v9
	v_cvt_pk_bf16_f32 v8, v2, v3
	v_cvt_pk_bf16_f32 v9, v4, v5
	global_store_dwordx4 v170, v[6:9], s[94:95] offset:256
	s_mov_b32 s2, s12
	s_mov_b64 s[20:21], s[14:15]
	s_mov_b64 s[18:19], s[16:17]
	s_and_b64 vcc, exec, s[4:5]
	s_nop 1
	s_cbranch_vccz .LBB0_55
	s_waitcnt vmcnt(0)
	s_cmpk_gt_u32 s29, 0xff
	s_cbranch_scc1 .LBB0_66
	s_barrier

; #define PG8_STAGE(bufoff, gbase, voff) do { _Pragma("unroll") for (int _i = 0; _i < 2; ++_i) \
;         __builtin_amdgcn_global_load_lds((const unsigned*)((const char*)(gbase) + (voff)[_i]), (LAS unsigned*)(lds + (bufoff) + ldsw + _i * 8192), 16, 0, 0); } while (0)
; #define PG8_LDA(dst, b, h) do { _Pragma("unroll") for (int m = 0; m < 4; ++m) _Pragma("unroll") for (int k = 0; k < 2; ++k) dst[m][k] = *(const LAS bf16x8*)(lds + PG8_SA(b, h) + aoff + m * 2048 + k * 1024); } while (0)
; #define PG8_LDB(dst, b, h) do { _Pragma("unroll") for (int n = 0; n < 2; ++n) _Pragma("unroll") for (int k = 0; k < 2; ++k) dst[n][k] = *(const LAS bf16x8*)(lds + PG8_SB(b, h) + boff + n * 2048 + k * 1024); } while (0)
; #define PG8_MMA(ai, bj, At, Bt) do { __builtin_amdgcn_s_setprio(1); _Pragma("unroll") for (int m = 0; m < 4; ++m) _Pragma("unroll") for (int n = 0; n < 2; ++n) _Pragma("unroll") for (int k = 0; k < 2; ++k) \
;         acc[ai][bj][m][n] = __builtin_amdgcn_mfma_f32_16x16x32_bf16(Bt[n][k], At[m][k], acc[ai][bj][m][n], 0, 0, 0); __builtin_amdgcn_s_setprio(0); } while (0)
; #define PG8_WAIT_L(n) asm volatile("s_waitcnt lgkmcnt(" #n ")" ::: "memory")
; #define PG8_BAR __builtin_amdgcn_s_barrier()
; #define PG8_SCHED __builtin_amdgcn_sched_barrier(0)
; template <class Epi>
; __device__ __forceinline__ void gemm_phase(LAS unsigned char* lds, const Gemm g, const StaticOrder& S, const Epi& E, const int tid) {
;     ...
;             const bool last = (t == nt - 2);
;             const char* a1 = cA + (size_t)(t + 1) * kstep;
;             const char* a2 = last ? nA : cA + (size_t)(t + 2) * kstep; const char* b2 = last ? nB : cB + (size_t)(t + 2) * kstep;
;             const char* a3 = a2 + kstep; const char* b3 = b2 + kstep;
;             PG8_LDB(B0, 0, 0); PG8_SCHED; PG8_LDA(At, 0, 0); PG8_STAGE(PG8_SA(1, 1), a1 + hstep, voffA);
;             PG8_WAIT_L(8); PG8_BAR; PG8_WAIT_L(0); PG8_MMA(0, 0, At, B0); PG8_BAR; PG8_SCHED;
;             PG8_LDB(B1, 0, 1); PG8_STAGE(PG8_SB(0, 0), b2, voffB);
;             PG8_BAR; PG8_WAIT_L(0); PG8_MMA(0, 1, At, B1); PG8_BAR;
;             PG8_LDA(At, 0, 1); PG8_STAGE(PG8_SA(0, 0), a2, voffA);
;             PG8_BAR; PG8_WAIT_L(0); PG8_MMA(1, 0, At, B0); PG8_BAR; PG8_SCHED;
.Lgprio2:
.LBB0_84:
	s_add_u32 s18, s16, 0xfff80080
	s_addc_u32 s19, s17, -1
	s_add_i32 s45, 0, 0x10000
	v_add_u32_e32 v140, s45, v144
	ds_read_b128 v[160:163], v140
	ds_read_b128 v[164:167], v140 offset:1024
	ds_read_b128 v[168:171], v140 offset:2048
	ds_read_b128 v[172:175], v140 offset:3072
	s_cmp_eq_u32 s44, 28
	s_cselect_b32 s21, s9, s19
	s_cselect_b32 s20, s40, s18
	s_cselect_b32 s19, s7, s43
	s_cselect_b32 s18, s41, s42
	s_add_i32 m0, s15, 0xc000
	ds_read_b128 v[176:179], v145
	ds_read_b128 v[180:183], v145 offset:1024
	ds_read_b128 v[184:187], v145 offset:2048
	ds_read_b128 v[188:191], v145 offset:3072
	ds_read_b128 v[192:195], v145 offset:4096
	ds_read_b128 v[196:199], v145 offset:5120
	ds_read_b128 v[210:213], v145 offset:6144
	ds_read_b128 v[214:217], v145 offset:7168
	global_load_lds_dwordx4 v138, s[16:17]
	v_lshl_add_u64 v[140:141], s[16:17], 0, v[136:137]
	s_add_i32 m0, s15, 0xe000
	s_nop 0
	global_load_lds_dwordx4 v[140:141], off
	s_waitcnt lgkmcnt(8)
	s_barrier
	s_waitcnt lgkmcnt(0)
	v_mfma_f32_16x16x32_bf16 v[126:129], v[160:163], v[176:179], v[126:129]
	v_mfma_f32_16x16x32_bf16 v[122:125], v[168:171], v[176:179], v[122:125]
	v_mfma_f32_16x16x32_bf16 v[110:113], v[160:163], v[184:187], v[110:113]
	v_mfma_f32_16x16x32_bf16 v[106:109], v[168:171], v[184:187], v[106:109]
	v_mfma_f32_16x16x32_bf16 v[94:97], v[160:163], v[192:195], v[94:97]
	v_mfma_f32_16x16x32_bf16 v[90:93], v[168:171], v[192:195], v[90:93]
	v_mfma_f32_16x16x32_bf16 v[78:81], v[160:163], v[210:213], v[78:81]
	v_mfma_f32_16x16x32_bf16 v[74:77], v[168:171], v[210:213], v[74:77]
	v_mfma_f32_16x16x32_bf16 v[126:129], v[164:167], v[180:183], v[126:129]
	v_mfma_f32_16x16x32_bf16 v[122:125], v[172:175], v[180:183], v[122:125]
	v_mfma_f32_16x16x32_bf16 v[110:113], v[164:167], v[188:191], v[110:113]
	v_mfma_f32_16x16x32_bf16 v[106:109], v[172:175], v[188:191], v[106:109]
	v_mfma_f32_16x16x32_bf16 v[94:97], v[164:167], v[196:199], v[94:97]
	v_mfma_f32_16x16x32_bf16 v[90:93], v[172:175], v[196:199], v[90:93]
	v_mfma_f32_16x16x32_bf16 v[78:81], v[164:167], v[214:217], v[78:81]
	v_mfma_f32_16x16x32_bf16 v[74:77], v[172:175], v[214:217], v[74:77]
	s_barrier
	s_add_i32 s47, 0, 0x14000
	v_add_u32_e32 v140, s47, v144
	s_add_i32 s45, s45, s26
	ds_read_b128 v[218:221], v140
	ds_read_b128 v[222:225], v140 offset:1024
	ds_read_b128 v[226:229], v140 offset:2048
	ds_read_b128 v[230:233], v140 offset:3072
	v_lshl_add_u64 v[140:141], s[18:19], 0, v[0:1]
	s_mov_b32 m0, s45
	v_lshl_add_u64 v[200:201], s[18:19], 0, v[134:135]
	global_load_lds_dwordx4 v[140:141], off
	s_add_i32 m0, s45, 0x2000
	s_nop 0
	global_load_lds_dwordx4 v[200:201], off
	s_barrier
	s_waitcnt lgkmcnt(0)
	v_mfma_f32_16x16x32_bf16 v[118:121], v[218:221], v[176:179], v[118:121]
	v_mfma_f32_16x16x32_bf16 v[114:117], v[226:229], v[176:179], v[114:117]
	v_mfma_f32_16x16x32_bf16 v[102:105], v[218:221], v[184:187], v[102:105]
	v_mfma_f32_16x16x32_bf16 v[98:101], v[226:229], v[184:187], v[98:101]
	v_mfma_f32_16x16x32_bf16 v[86:89], v[218:221], v[192:195], v[86:89]
	v_mfma_f32_16x16x32_bf16 v[82:85], v[226:229], v[192:195], v[82:85]
	v_mfma_f32_16x16x32_bf16 v[70:73], v[218:221], v[210:213], v[70:73]
	v_mfma_f32_16x16x32_bf16 v[66:69], v[226:229], v[210:213], v[66:69]
	v_mfma_f32_16x16x32_bf16 v[118:121], v[222:225], v[180:183], v[118:121]
	v_mfma_f32_16x16x32_bf16 v[114:117], v[230:233], v[180:183], v[114:117]
	v_mfma_f32_16x16x32_bf16 v[102:105], v[222:225], v[188:191], v[102:105]
	v_mfma_f32_16x16x32_bf16 v[98:101], v[230:233], v[188:191], v[98:101]
	v_mfma_f32_16x16x32_bf16 v[86:89], v[222:225], v[196:199], v[86:89]
	v_mfma_f32_16x16x32_bf16 v[82:85], v[230:233], v[196:199], v[82:85]
	v_mfma_f32_16x16x32_bf16 v[70:73], v[222:225], v[214:217], v[70:73]
	v_mfma_f32_16x16x32_bf16 v[66:69], v[230:233], v[214:217], v[66:69]
	s_mov_b32 m0, s15
	v_lshl_add_u64 v[234:235], s[20:21], 0, v[130:131]
	s_barrier
	ds_read_b128 v[176:179], v145 offset:16384
	ds_read_b128 v[180:183], v145 offset:17408
	ds_read_b128 v[184:187], v145 offset:18432
	ds_read_b128 v[188:191], v145 offset:19456
	ds_read_b128 v[192:195], v145 offset:20480
	ds_read_b128 v[196:199], v145 offset:21504
	ds_read_b128 v[210:213], v145 offset:22528
	ds_read_b128 v[214:217], v145 offset:23552
	global_load_lds_dwordx4 v[234:235], off
	v_lshl_add_u64 v[236:237], s[20:21], 0, v[132:133]
	s_mov_b32 m0, s27
	s_nop 0
	global_load_lds_dwordx4 v[236:237], off
	s_barrier
	s_waitcnt lgkmcnt(0)
	v_mfma_f32_16x16x32_bf16 v[62:65], v[160:163], v[176:179], v[62:65]
	v_mfma_f32_16x16x32_bf16 v[58:61], v[168:171], v[176:179], v[58:61]
	v_mfma_f32_16x16x32_bf16 v[46:49], v[160:163], v[184:187], v[46:49]
	v_mfma_f32_16x16x32_bf16 v[42:45], v[168:171], v[184:187], v[42:45]
	v_mfma_f32_16x16x32_bf16 v[30:33], v[160:163], v[192:195], v[30:33]
	v_mfma_f32_16x16x32_bf16 v[26:29], v[168:171], v[192:195], v[26:29]
	v_mfma_f32_16x16x32_bf16 v[14:17], v[160:163], v[210:213], v[14:17]
	v_mfma_f32_16x16x32_bf16 v[10:13], v[168:171], v[210:213], v[10:13]
	v_mfma_f32_16x16x32_bf16 v[62:65], v[164:167], v[180:183], v[62:65]
	v_mfma_f32_16x16x32_bf16 v[58:61], v[172:175], v[180:183], v[58:61]
	v_mfma_f32_16x16x32_bf16 v[46:49], v[164:167], v[188:191], v[46:49]
	v_mfma_f32_16x16x32_bf16 v[42:45], v[172:175], v[188:191], v[42:45]
	v_mfma_f32_16x16x32_bf16 v[30:33], v[164:167], v[196:199], v[30:33]
	v_mfma_f32_16x16x32_bf16 v[26:29], v[172:175], v[196:199], v[26:29]
	v_mfma_f32_16x16x32_bf16 v[14:17], v[164:167], v[214:217], v[14:17]
	v_mfma_f32_16x16x32_bf16 v[10:13], v[172:175], v[214:217], v[10:13]
	s_barrier
; #define PG8_STAGE(bufoff, gbase, voff) do { _Pragma("unroll") for (int _i = 0; _i < 2; ++_i) \
;         __builtin_amdgcn_global_load_lds((const unsigned*)((const char*)(gbase) + (voff)[_i]), (LAS unsigned*)(lds + (bufoff) + ldsw + _i * 8192), 16, 0, 0); } while (0)
; #define PG8_LDA(dst, b, h) do { _Pragma("unroll") for (int m = 0; m < 4; ++m) _Pragma("unroll") for (int k = 0; k < 2; ++k) dst[m][k] = *(const LAS bf16x8*)(lds + PG8_SA(b, h) + aoff + m * 2048 + k * 1024); } while (0)
; #define PG8_LDB(dst, b, h) do { _Pragma("unroll") for (int n = 0; n < 2; ++n) _Pragma("unroll") for (int k = 0; k < 2; ++k) dst[n][k] = *(const LAS bf16x8*)(lds + PG8_SB(b, h) + boff + n * 2048 + k * 1024); } while (0)
; #define PG8_MMA(ai, bj, At, Bt) do { __builtin_amdgcn_s_setprio(1); _Pragma("unroll") for (int m = 0; m < 4; ++m) _Pragma("unroll") for (int n = 0; n < 2; ++n) _Pragma("unroll") for (int k = 0; k < 2; ++k) \
;         acc[ai][bj][m][n] = __builtin_amdgcn_mfma_f32_16x16x32_bf16(Bt[n][k], At[m][k], acc[ai][bj][m][n], 0, 0, 0); __builtin_amdgcn_s_setprio(0); } while (0)
; #define PG8_WAIT_V(n) asm volatile("s_waitcnt vmcnt(" #n ")" ::: "memory")
; #define PG8_WAIT_L(n) asm volatile("s_waitcnt lgkmcnt(" #n ")" ::: "memory")
; #define PG8_BAR __builtin_amdgcn_s_barrier()
; #define PG8_SCHED __builtin_amdgcn_sched_barrier(0)
; template <class Epi>
; __device__ __forceinline__ void gemm_phase(LAS unsigned char* lds, const Gemm g, const StaticOrder& S, const Epi& E, const int tid) {
;     ...
;             PG8_STAGE(PG8_SB(0, 1), b2 + hstep, voffB);
;             PG8_WAIT_V(6); PG8_BAR; PG8_MMA(1, 1, At, B1); PG8_BAR;
;             PG8_LDB(B0, 1, 0); PG8_SCHED; PG8_LDA(At, 1, 0); PG8_STAGE(PG8_SA(0, 1), a2 + hstep, voffA);
;             PG8_WAIT_L(8); PG8_BAR; PG8_WAIT_L(0); PG8_MMA(0, 0, At, B0); PG8_BAR; PG8_SCHED;
;             PG8_LDB(B1, 1, 1); PG8_STAGE(PG8_SB(1, 0), b3, voffB);
;             PG8_BAR; PG8_WAIT_L(0); PG8_MMA(0, 1, At, B1); PG8_BAR;
;             PG8_LDA(At, 1, 1); PG8_STAGE(PG8_SA(1, 0), a3, voffA);
	s_add_u32 s48, s18, 0x80000
	s_addc_u32 s49, s19, 0
	s_add_i32 s45, s47, s26
	s_mov_b32 m0, s45
	s_nop 0
	global_load_lds_dwordx4 v0, s[48:49]
	s_add_i32 m0, s45, 0x2000
	s_nop 0
	global_load_lds_dwordx4 v134, s[48:49]
	s_waitcnt vmcnt(6)
	s_barrier
	v_mfma_f32_16x16x32_bf16 v[54:57], v[218:221], v[176:179], v[54:57]
	v_mfma_f32_16x16x32_bf16 v[50:53], v[226:229], v[176:179], v[50:53]
	v_mfma_f32_16x16x32_bf16 v[38:41], v[218:221], v[184:187], v[38:41]
	v_mfma_f32_16x16x32_bf16 v[34:37], v[226:229], v[184:187], v[34:37]
	v_mfma_f32_16x16x32_bf16 v[22:25], v[218:221], v[192:195], v[22:25]
	v_mfma_f32_16x16x32_bf16 v[18:21], v[226:229], v[192:195], v[18:21]
	v_mfma_f32_16x16x32_bf16 v[6:9], v[218:221], v[210:213], v[6:9]
	v_mfma_f32_16x16x32_bf16 v[2:5], v[226:229], v[210:213], v[2:5]
	v_mfma_f32_16x16x32_bf16 v[54:57], v[222:225], v[180:183], v[54:57]
	v_mfma_f32_16x16x32_bf16 v[50:53], v[230:233], v[180:183], v[50:53]
	v_mfma_f32_16x16x32_bf16 v[38:41], v[222:225], v[188:191], v[38:41]
	v_mfma_f32_16x16x32_bf16 v[34:37], v[230:233], v[188:191], v[34:37]
	v_mfma_f32_16x16x32_bf16 v[22:25], v[222:225], v[196:199], v[22:25]
	v_mfma_f32_16x16x32_bf16 v[18:21], v[230:233], v[196:199], v[18:21]
	v_mfma_f32_16x16x32_bf16 v[6:9], v[222:225], v[214:217], v[6:9]
	v_mfma_f32_16x16x32_bf16 v[2:5], v[230:233], v[214:217], v[2:5]
	s_add_i32 s45, 0, 0x18000
	v_add_u32_e32 v159, s45, v144
	s_barrier
	ds_read_b128 v[160:163], v159
	ds_read_b128 v[164:167], v159 offset:1024
	ds_read_b128 v[168:171], v159 offset:2048
	ds_read_b128 v[172:175], v159 offset:3072
	s_add_u32 s20, s20, 0x80000
	s_addc_u32 s21, s21, 0
	s_mov_b32 m0, s28
	ds_read_b128 v[176:179], v145 offset:32768
	ds_read_b128 v[180:183], v145 offset:33792
	ds_read_b128 v[184:187], v145 offset:34816
	ds_read_b128 v[188:191], v145 offset:35840
	ds_read_b128 v[192:195], v145 offset:36864
	ds_read_b128 v[196:199], v145 offset:37888
	ds_read_b128 v[210:213], v145 offset:38912
	ds_read_b128 v[214:217], v145 offset:39936
	global_load_lds_dwordx4 v130, s[20:21]
	s_mov_b32 m0, s29
	s_nop 0
	global_load_lds_dwordx4 v132, s[20:21]
	s_waitcnt lgkmcnt(8)
	s_barrier
	s_waitcnt lgkmcnt(0)
	v_mfma_f32_16x16x32_bf16 v[126:129], v[160:163], v[176:179], v[126:129]
	v_mfma_f32_16x16x32_bf16 v[122:125], v[168:171], v[176:179], v[122:125]
	v_mfma_f32_16x16x32_bf16 v[110:113], v[160:163], v[184:187], v[110:113]
	v_mfma_f32_16x16x32_bf16 v[106:109], v[168:171], v[184:187], v[106:109]
	v_mfma_f32_16x16x32_bf16 v[94:97], v[160:163], v[192:195], v[94:97]
	v_mfma_f32_16x16x32_bf16 v[90:93], v[168:171], v[192:195], v[90:93]
	v_mfma_f32_16x16x32_bf16 v[78:81], v[160:163], v[210:213], v[78:81]
	v_mfma_f32_16x16x32_bf16 v[74:77], v[168:171], v[210:213], v[74:77]
	v_mfma_f32_16x16x32_bf16 v[126:129], v[164:167], v[180:183], v[126:129]
	v_mfma_f32_16x16x32_bf16 v[122:125], v[172:175], v[180:183], v[122:125]
	v_mfma_f32_16x16x32_bf16 v[110:113], v[164:167], v[188:191], v[110:113]
	v_mfma_f32_16x16x32_bf16 v[106:109], v[172:175], v[188:191], v[106:109]
	v_mfma_f32_16x16x32_bf16 v[94:97], v[164:167], v[196:199], v[94:97]
	v_mfma_f32_16x16x32_bf16 v[90:93], v[172:175], v[196:199], v[90:93]
	v_mfma_f32_16x16x32_bf16 v[78:81], v[164:167], v[214:217], v[78:81]
	v_mfma_f32_16x16x32_bf16 v[74:77], v[172:175], v[214:217], v[74:77]
	s_barrier
	s_add_i32 s20, 0, 0x1c000
	s_add_i32 s21, s45, s26
	v_add_u32_e32 v159, s20, v144
	v_lshl_add_u64 v[140:141], v[140:141], 0, s[56:57]
	s_mov_b32 m0, s21
	ds_read_b128 v[218:221], v159
	ds_read_b128 v[222:225], v159 offset:1024
	ds_read_b128 v[226:229], v159 offset:2048
	ds_read_b128 v[230:233], v159 offset:3072
	global_load_lds_dwordx4 v[140:141], off
	v_lshl_add_u64 v[140:141], v[200:201], 0, s[56:57]
	s_add_i32 m0, s21, 0x2000
	s_nop 0
	global_load_lds_dwordx4 v[140:141], off
	s_barrier
	s_waitcnt lgkmcnt(0)
	v_mfma_f32_16x16x32_bf16 v[118:121], v[218:221], v[176:179], v[118:121]
	v_mfma_f32_16x16x32_bf16 v[114:117], v[226:229], v[176:179], v[114:117]
	v_mfma_f32_16x16x32_bf16 v[102:105], v[218:221], v[184:187], v[102:105]
	v_mfma_f32_16x16x32_bf16 v[98:101], v[226:229], v[184:187], v[98:101]
	v_mfma_f32_16x16x32_bf16 v[86:89], v[218:221], v[192:195], v[86:89]
	v_mfma_f32_16x16x32_bf16 v[82:85], v[226:229], v[192:195], v[82:85]
	v_mfma_f32_16x16x32_bf16 v[70:73], v[218:221], v[210:213], v[70:73]
	v_mfma_f32_16x16x32_bf16 v[66:69], v[226:229], v[210:213], v[66:69]
	v_mfma_f32_16x16x32_bf16 v[118:121], v[222:225], v[180:183], v[118:121]
	v_mfma_f32_16x16x32_bf16 v[114:117], v[230:233], v[180:183], v[114:117]
	v_mfma_f32_16x16x32_bf16 v[102:105], v[222:225], v[188:191], v[102:105]
	v_mfma_f32_16x16x32_bf16 v[98:101], v[230:233], v[188:191], v[98:101]
	v_mfma_f32_16x16x32_bf16 v[86:89], v[222:225], v[196:199], v[86:89]
	v_mfma_f32_16x16x32_bf16 v[82:85], v[230:233], v[196:199], v[82:85]
	v_mfma_f32_16x16x32_bf16 v[70:73], v[222:225], v[214:217], v[70:73]
	v_mfma_f32_16x16x32_bf16 v[66:69], v[230:233], v[214:217], v[66:69]
	s_mov_b32 m0, s35
	v_lshl_add_u64 v[140:141], v[234:235], 0, s[56:57]
	s_barrier
	ds_read_b128 v[176:179], v145 offset:49152
	ds_read_b128 v[180:183], v145 offset:50176
	ds_read_b128 v[184:187], v145 offset:51200
	ds_read_b128 v[188:191], v145 offset:52224
	ds_read_b128 v[192:195], v145 offset:53248
	ds_read_b128 v[196:199], v145 offset:54272
	ds_read_b128 v[210:213], v145 offset:55296
	ds_read_b128 v[214:217], v145 offset:56320
	global_load_lds_dwordx4 v[140:141], off
	v_lshl_add_u64 v[140:141], v[236:237], 0, s[56:57]
	s_mov_b32 m0, s36
	s_nop 0
	global_load_lds_dwordx4 v[140:141], off
	s_barrier
; __device__ __forceinline__ unsigned pk2(float lo, float hi) { f32x2 v = {lo, hi}; return __builtin_bit_cast(unsigned, __builtin_convertvector(v, bf16x2_t)); }
; #define PG8_STAGE(bufoff, gbase, voff) do { _Pragma("unroll") for (int _i = 0; _i < 2; ++_i) \
;         __builtin_amdgcn_global_load_lds((const unsigned*)((const char*)(gbase) + (voff)[_i]), (LAS unsigned*)(lds + (bufoff) + ldsw + _i * 8192), 16, 0, 0); } while (0)
; #define PG8_MMA(ai, bj, At, Bt) do { __builtin_amdgcn_s_setprio(1); _Pragma("unroll") for (int m = 0; m < 4; ++m) _Pragma("unroll") for (int n = 0; n < 2; ++n) _Pragma("unroll") for (int k = 0; k < 2; ++k) \
;         acc[ai][bj][m][n] = __builtin_amdgcn_mfma_f32_16x16x32_bf16(Bt[n][k], At[m][k], acc[ai][bj][m][n], 0, 0, 0); __builtin_amdgcn_s_setprio(0); } while (0)
; #define PG8_WAIT_V(n) asm volatile("s_waitcnt vmcnt(" #n ")" ::: "memory")
; #define PG8_WAIT_L(n) asm volatile("s_waitcnt lgkmcnt(" #n ")" ::: "memory")
; #define PG8_BAR __builtin_amdgcn_s_barrier()
; #define PG8_SCHED __builtin_amdgcn_sched_barrier(0)
;     __device__ __forceinline__ void operator()(const f32x4 (&acc)[2][2][4][2], const Unit& u, int wr, int wc, int fr, int fq) const {
;     ...
;         const int row0 = u.pm * BM + wr * 64 + fr, col0 = u.pn * BM + wc * 32 + 8 * fq;
; #pragma unroll
;         for (int ai = 0; ai < 2; ++ai)
; #pragma unroll
;             for (int m = 0; m < 4; ++m) {
;                 bf16_t* rowp = O + (size_t)(row0 + ai * HALF + m * 16) * ldc + col0;
; #pragma unroll
;                 for (int bj = 0; bj < 2; ++bj) {
;                     f32x4 v0 = acc[ai][bj][m][0], v1 = acc[ai][bj][m][1];
; #pragma unroll
;                     for (int j = 0; j < 4; ++j) { const float a = fmaxf(v0[j], 0.f), b = fmaxf(v1[j], 0.f); v0[j] = a * a; v1[j] = b * b; }
;                     u32x4 w; w.x = pk2(v0[0], v0[1]); w.y = pk2(v0[2], v0[3]); w.z = pk2(v1[0], v1[1]); w.w = pk2(v1[2], v1[3]);
;                     *(u32x4*)(rowp + bj * HALF) = w;
; template <class Epi>
; __device__ __forceinline__ void gemm_phase(LAS unsigned char* lds, const Gemm g, const StaticOrder& S, const Epi& E, const int tid) {
;     ...
;             PG8_BAR; PG8_WAIT_L(0); PG8_MMA(1, 0, At, B0); PG8_BAR; PG8_SCHED;
;             PG8_STAGE(PG8_SB(1, 1), b3 + hstep, voffB);
;             PG8_WAIT_V(6); PG8_BAR; PG8_MMA(1, 1, At, B1); PG8_BAR;
	s_waitcnt lgkmcnt(0)
	v_mfma_f32_16x16x32_bf16 v[62:65], v[160:163], v[176:179], v[62:65]
	v_mfma_f32_16x16x32_bf16 v[58:61], v[168:171], v[176:179], v[58:61]
	v_mfma_f32_16x16x32_bf16 v[46:49], v[160:163], v[184:187], v[46:49]
	v_mfma_f32_16x16x32_bf16 v[42:45], v[168:171], v[184:187], v[42:45]
	v_mfma_f32_16x16x32_bf16 v[30:33], v[160:163], v[192:195], v[30:33]
	v_mfma_f32_16x16x32_bf16 v[26:29], v[168:171], v[192:195], v[26:29]
	v_mfma_f32_16x16x32_bf16 v[14:17], v[160:163], v[210:213], v[14:17]
	v_mfma_f32_16x16x32_bf16 v[10:13], v[168:171], v[210:213], v[10:13]
	v_mfma_f32_16x16x32_bf16 v[62:65], v[164:167], v[180:183], v[62:65]
	v_mfma_f32_16x16x32_bf16 v[58:61], v[172:175], v[180:183], v[58:61]
	v_mfma_f32_16x16x32_bf16 v[46:49], v[164:167], v[188:191], v[46:49]
	v_mfma_f32_16x16x32_bf16 v[42:45], v[172:175], v[188:191], v[42:45]
	v_mfma_f32_16x16x32_bf16 v[30:33], v[164:167], v[196:199], v[30:33]
	v_mfma_f32_16x16x32_bf16 v[26:29], v[172:175], v[196:199], v[26:29]
	v_mfma_f32_16x16x32_bf16 v[14:17], v[164:167], v[214:217], v[14:17]
	v_mfma_f32_16x16x32_bf16 v[10:13], v[172:175], v[214:217], v[10:13]
	s_barrier
	s_add_u32 s18, s18, 0x80080
	s_addc_u32 s19, s19, 0
	s_add_i32 s20, s20, s26
	s_mov_b32 m0, s20
	s_nop 0
	global_load_lds_dwordx4 v0, s[18:19]
	v_lshl_add_u64 v[140:141], s[18:19], 0, v[134:135]
	s_add_i32 m0, s20, 0x2000
	s_nop 0
	global_load_lds_dwordx4 v[140:141], off
	s_waitcnt vmcnt(6)
	s_barrier
	v_mfma_f32_16x16x32_bf16 v[54:57], v[218:221], v[176:179], v[54:57]
	v_mfma_f32_16x16x32_bf16 v[50:53], v[226:229], v[176:179], v[50:53]
	v_mfma_f32_16x16x32_bf16 v[38:41], v[218:221], v[184:187], v[38:41]
	v_mfma_f32_16x16x32_bf16 v[34:37], v[226:229], v[184:187], v[34:37]
	v_mfma_f32_16x16x32_bf16 v[22:25], v[218:221], v[192:195], v[22:25]
	v_mfma_f32_16x16x32_bf16 v[18:21], v[226:229], v[192:195], v[18:21]
	v_mfma_f32_16x16x32_bf16 v[6:9], v[218:221], v[210:213], v[6:9]
	v_mfma_f32_16x16x32_bf16 v[2:5], v[226:229], v[210:213], v[2:5]
	v_mfma_f32_16x16x32_bf16 v[54:57], v[222:225], v[180:183], v[54:57]
	v_mfma_f32_16x16x32_bf16 v[50:53], v[230:233], v[180:183], v[50:53]
	v_mfma_f32_16x16x32_bf16 v[38:41], v[222:225], v[188:191], v[38:41]
	v_mfma_f32_16x16x32_bf16 v[34:37], v[230:233], v[188:191], v[34:37]
	v_mfma_f32_16x16x32_bf16 v[22:25], v[222:225], v[196:199], v[22:25]
	v_mfma_f32_16x16x32_bf16 v[18:21], v[230:233], v[196:199], v[18:21]
	v_mfma_f32_16x16x32_bf16 v[6:9], v[222:225], v[214:217], v[6:9]
	v_mfma_f32_16x16x32_bf16 v[2:5], v[230:233], v[214:217], v[2:5]
	s_add_i32 s44, s44, 2
	s_add_u32 s42, s42, 0x100
	s_addc_u32 s43, s43, 0
	s_add_u32 s16, s16, 0x100
	s_addc_u32 s17, s17, 0
	s_cmp_gt_u32 s44, 29
	s_barrier
	s_cbranch_scc0 .LBB0_84
	s_setprio 0
	v_mov_b32_e32 v141, v143
	v_mov_b32_e32 v140, v142
	s_lshl_b32 s7, s14, 8
	s_add_i32 s7, s7, s31
	v_add_u32_e32 v140, s7, v140
	s_lshl_b32 s7, s39, 8
	s_or_b32 s7, s7, s34
	v_lshl_add_u32 v160, v141, 3, s7
	v_ashrrev_i32_e32 v141, 31, v140
	v_lshlrev_b64 v[140:141], 14, v[140:141]
	v_max_f32_e32 v122, v122, v122
	v_max_f32_e32 v123, v123, v123
	v_ashrrev_i32_e32 v161, 31, v160
	v_lshl_add_u64 v[140:141], s[2:3], 0, v[140:141]
	v_max_f32_e32 v122, 0, v122
	v_max_f32_e32 v123, 0, v123
	v_lshl_add_u64 v[140:141], v[160:161], 1, v[140:141]
	v_pk_mul_f32 v[160:161], v[122:123], v[122:123]
	v_max_f32_e32 v123, v124, v124
	v_max_f32_e32 v126, v126, v126
	v_max_f32_e32 v127, v127, v127
	v_max_f32_e32 v122, v128, v128
	v_max_f32_e32 v124, 0, v123
	v_max_f32_e32 v123, v129, v129
	v_max_f32_e32 v125, v125, v125
	v_max_f32_e32 v126, 0, v126
	v_max_f32_e32 v127, 0, v127
	v_max_f32_e32 v122, 0, v122
	v_max_f32_e32 v123, 0, v123
	v_max_f32_e32 v125, 0, v125
	v_pk_mul_f32 v[126:127], v[126:127], v[126:127]
	v_pk_mul_f32 v[128:129], v[122:123], v[122:123]
	v_pk_mul_f32 v[162:163], v[124:125], v[124:125]
	v_max_f32_e32 v114, v114, v114
	v_max_f32_e32 v115, v115, v115
	v_cvt_pk_bf16_f32 v122, v126, v127
	v_cvt_pk_bf16_f32 v123, v128, v129
	v_cvt_pk_bf16_f32 v124, v160, v161
	v_cvt_pk_bf16_f32 v125, v162, v163
	v_max_f32_e32 v114, 0, v114
	v_max_f32_e32 v115, 0, v115
	global_store_dwordx4 v[140:141], v[122:125], off
	v_max_f32_e32 v118, v118, v118
	v_max_f32_e32 v119, v119, v119
	v_pk_mul_f32 v[122:123], v[114:115], v[114:115]
	v_max_f32_e32 v115, v116, v116
	v_max_f32_e32 v114, v120, v120
	v_max_f32_e32 v116, 0, v115
	v_max_f32_e32 v115, v121, v121
	v_max_f32_e32 v117, v117, v117
	v_max_f32_e32 v118, 0, v118
	v_max_f32_e32 v119, 0, v119
	v_max_f32_e32 v114, 0, v114
	v_max_f32_e32 v115, 0, v115
	v_max_f32_e32 v117, 0, v117
	v_pk_mul_f32 v[118:119], v[118:119], v[118:119]
	v_pk_mul_f32 v[120:121], v[114:115], v[114:115]
	v_pk_mul_f32 v[124:125], v[116:117], v[116:117]
	v_max_f32_e32 v106, v106, v106
	v_max_f32_e32 v107, v107, v107
	v_cvt_pk_bf16_f32 v114, v118, v119
	v_cvt_pk_bf16_f32 v115, v120, v121
	v_cvt_pk_bf16_f32 v116, v122, v123
	v_cvt_pk_bf16_f32 v117, v124, v125
	v_max_f32_e32 v106, 0, v106
	v_max_f32_e32 v107, 0, v107
	global_store_dwordx4 v[140:141], v[114:117], off offset:256
	v_max_f32_e32 v110, v110, v110
	v_max_f32_e32 v111, v111, v111
	v_pk_mul_f32 v[116:117], v[106:107], v[106:107]
	v_max_f32_e32 v107, v108, v108
	v_max_f32_e32 v110, 0, v110
	v_max_f32_e32 v111, 0, v111
	v_max_f32_e32 v106, v112, v112
	v_max_f32_e32 v108, 0, v107
	v_max_f32_e32 v107, v113, v113
	v_max_f32_e32 v109, v109, v109
	v_pk_mul_f32 v[110:111], v[110:111], v[110:111]
	v_max_f32_e32 v106, 0, v106
	v_max_f32_e32 v107, 0, v107
	v_max_f32_e32 v109, 0, v109
	s_mov_b32 s7, 0x40000
	v_pk_mul_f32 v[112:113], v[106:107], v[106:107]
	v_pk_mul_f32 v[118:119], v[108:109], v[108:109]
	v_cvt_pk_bf16_f32 v106, v110, v111
; __device__ __forceinline__ unsigned pk2(float lo, float hi) { f32x2 v = {lo, hi}; return __builtin_bit_cast(unsigned, __builtin_convertvector(v, bf16x2_t)); }
;     __device__ __forceinline__ void operator()(const f32x4 (&acc)[2][2][4][2], const Unit& u, int wr, int wc, int fr, int fq) const {
;     ...
;             for (int m = 0; m < 4; ++m) {
;                 bf16_t* rowp = O + (size_t)(row0 + ai * HALF + m * 16) * ldc + col0;
; #pragma unroll
;                 for (int bj = 0; bj < 2; ++bj) {
;                     f32x4 v0 = acc[ai][bj][m][0], v1 = acc[ai][bj][m][1];
; #pragma unroll
;                     for (int j = 0; j < 4; ++j) { const float a = fmaxf(v0[j], 0.f), b = fmaxf(v1[j], 0.f); v0[j] = a * a; v1[j] = b * b; }
;                     u32x4 w; w.x = pk2(v0[0], v0[1]); w.y = pk2(v0[2], v0[3]); w.z = pk2(v1[0], v1[1]); w.w = pk2(v1[2], v1[3]);
;                     *(u32x4*)(rowp + bj * HALF) = w;
;                 }
	v_add_co_u32_e32 v110, vcc, s7, v140
	v_max_f32_e32 v98, v98, v98
	v_max_f32_e32 v99, v99, v99
	v_cvt_pk_bf16_f32 v107, v112, v113
	v_cvt_pk_bf16_f32 v108, v116, v117
	v_cvt_pk_bf16_f32 v109, v118, v119
	v_addc_co_u32_e32 v111, vcc, 0, v141, vcc
	v_max_f32_e32 v98, 0, v98
	v_max_f32_e32 v99, 0, v99
	global_store_dwordx4 v[110:111], v[106:109], off
	v_max_f32_e32 v102, v102, v102
	v_max_f32_e32 v103, v103, v103
	v_pk_mul_f32 v[106:107], v[98:99], v[98:99]
	v_max_f32_e32 v99, v100, v100
	v_max_f32_e32 v98, v104, v104
	v_max_f32_e32 v100, 0, v99
	v_max_f32_e32 v99, v105, v105
	v_max_f32_e32 v101, v101, v101
	v_max_f32_e32 v102, 0, v102
	v_max_f32_e32 v103, 0, v103
	v_max_f32_e32 v98, 0, v98
	v_max_f32_e32 v99, 0, v99
	v_max_f32_e32 v101, 0, v101
	s_mov_b64 s[16:17], 0x40000
	v_pk_mul_f32 v[102:103], v[102:103], v[102:103]
	v_pk_mul_f32 v[104:105], v[98:99], v[98:99]
	v_pk_mul_f32 v[108:109], v[100:101], v[100:101]
	v_max_f32_e32 v90, v90, v90
	v_max_f32_e32 v91, v91, v91
	v_lshl_add_u64 v[114:115], v[140:141], 0, s[16:17]
	v_cvt_pk_bf16_f32 v98, v102, v103
	v_cvt_pk_bf16_f32 v99, v104, v105
	v_cvt_pk_bf16_f32 v100, v106, v107
	v_cvt_pk_bf16_f32 v101, v108, v109
	v_max_f32_e32 v90, 0, v90
	v_max_f32_e32 v91, 0, v91
	global_store_dwordx4 v[114:115], v[98:101], off offset:256
	v_max_f32_e32 v94, v94, v94
	v_max_f32_e32 v95, v95, v95
	v_pk_mul_f32 v[100:101], v[90:91], v[90:91]
	v_max_f32_e32 v91, v92, v92
	v_max_f32_e32 v94, 0, v94
	v_max_f32_e32 v95, 0, v95
	v_max_f32_e32 v90, v96, v96
	v_max_f32_e32 v92, 0, v91
	v_max_f32_e32 v91, v97, v97
	v_max_f32_e32 v93, v93, v93
	v_pk_mul_f32 v[94:95], v[94:95], v[94:95]
	v_max_f32_e32 v90, 0, v90
	v_max_f32_e32 v91, 0, v91
	v_max_f32_e32 v93, 0, v93
	s_mov_b32 s7, 0x80000
	v_pk_mul_f32 v[96:97], v[90:91], v[90:91]
	v_pk_mul_f32 v[102:103], v[92:93], v[92:93]
	v_cvt_pk_bf16_f32 v90, v94, v95
	v_add_co_u32_e32 v94, vcc, s7, v140
	v_max_f32_e32 v82, v82, v82
	v_max_f32_e32 v83, v83, v83
	v_cvt_pk_bf16_f32 v91, v96, v97
	v_cvt_pk_bf16_f32 v92, v100, v101
	v_cvt_pk_bf16_f32 v93, v102, v103
	v_addc_co_u32_e32 v95, vcc, 0, v141, vcc
	v_max_f32_e32 v82, 0, v82
	v_max_f32_e32 v83, 0, v83
	global_store_dwordx4 v[94:95], v[90:93], off
	v_max_f32_e32 v86, v86, v86
	v_max_f32_e32 v87, v87, v87
	v_pk_mul_f32 v[90:91], v[82:83], v[82:83]
	v_max_f32_e32 v83, v84, v84
	v_max_f32_e32 v82, v88, v88
	v_max_f32_e32 v84, 0, v83
	v_max_f32_e32 v83, v89, v89
	v_max_f32_e32 v85, v85, v85
	v_max_f32_e32 v86, 0, v86
	v_max_f32_e32 v87, 0, v87
	v_max_f32_e32 v82, 0, v82
	v_max_f32_e32 v83, 0, v83
	v_max_f32_e32 v85, 0, v85
	s_mov_b64 s[16:17], 0x80000
	v_pk_mul_f32 v[86:87], v[86:87], v[86:87]
	v_pk_mul_f32 v[88:89], v[82:83], v[82:83]
	v_pk_mul_f32 v[92:93], v[84:85], v[84:85]
	v_max_f32_e32 v74, v74, v74
	v_max_f32_e32 v75, v75, v75
	v_lshl_add_u64 v[98:99], v[140:141], 0, s[16:17]
	v_cvt_pk_bf16_f32 v82, v86, v87
	v_cvt_pk_bf16_f32 v83, v88, v89
	v_cvt_pk_bf16_f32 v84, v90, v91
	v_cvt_pk_bf16_f32 v85, v92, v93
	v_max_f32_e32 v74, 0, v74
	v_max_f32_e32 v75, 0, v75
	global_store_dwordx4 v[98:99], v[82:85], off offset:256
	v_max_f32_e32 v78, v78, v78
	v_max_f32_e32 v79, v79, v79
	v_pk_mul_f32 v[84:85], v[74:75], v[74:75]
	v_max_f32_e32 v75, v76, v76
	v_max_f32_e32 v78, 0, v78
	v_max_f32_e32 v79, 0, v79
	v_max_f32_e32 v74, v80, v80
	v_max_f32_e32 v76, 0, v75
	v_max_f32_e32 v75, v81, v81
	v_max_f32_e32 v77, v77, v77
	v_pk_mul_f32 v[78:79], v[78:79], v[78:79]
	v_max_f32_e32 v74, 0, v74
	v_max_f32_e32 v75, 0, v75
	v_max_f32_e32 v77, 0, v77
	s_mov_b32 s7, 0xc0000
	v_pk_mul_f32 v[80:81], v[74:75], v[74:75]
	v_pk_mul_f32 v[86:87], v[76:77], v[76:77]
	v_cvt_pk_bf16_f32 v74, v78, v79
	v_add_co_u32_e32 v78, vcc, s7, v140
	v_max_f32_e32 v66, v66, v66
	v_max_f32_e32 v67, v67, v67
	v_cvt_pk_bf16_f32 v75, v80, v81
	v_cvt_pk_bf16_f32 v76, v84, v85
	v_cvt_pk_bf16_f32 v77, v86, v87
	v_addc_co_u32_e32 v79, vcc, 0, v141, vcc
	v_max_f32_e32 v66, 0, v66
	v_max_f32_e32 v67, 0, v67
	global_store_dwordx4 v[78:79], v[74:77], off
	v_max_f32_e32 v70, v70, v70
	v_max_f32_e32 v71, v71, v71
	v_pk_mul_f32 v[74:75], v[66:67], v[66:67]
	v_max_f32_e32 v67, v68, v68
	v_max_f32_e32 v66, v72, v72
	v_max_f32_e32 v68, 0, v67
	v_max_f32_e32 v67, v73, v73
	v_max_f32_e32 v69, v69, v69
	v_max_f32_e32 v70, 0, v70
	v_max_f32_e32 v71, 0, v71
	v_max_f32_e32 v66, 0, v66
	v_max_f32_e32 v67, 0, v67
	v_max_f32_e32 v69, 0, v69
	s_mov_b64 s[16:17], 0xc0000
	v_pk_mul_f32 v[70:71], v[70:71], v[70:71]
	v_pk_mul_f32 v[72:73], v[66:67], v[66:67]
	v_pk_mul_f32 v[76:77], v[68:69], v[68:69]
	v_max_f32_e32 v58, v58, v58
	v_max_f32_e32 v59, v59, v59
	v_lshl_add_u64 v[82:83], v[140:141], 0, s[16:17]
	v_cvt_pk_bf16_f32 v66, v70, v71
	v_cvt_pk_bf16_f32 v67, v72, v73
	v_cvt_pk_bf16_f32 v68, v74, v75
	v_cvt_pk_bf16_f32 v69, v76, v77
	v_max_f32_e32 v58, 0, v58
	v_max_f32_e32 v59, 0, v59
	global_store_dwordx4 v[82:83], v[66:69], off offset:256
	v_max_f32_e32 v62, v62, v62
	v_max_f32_e32 v63, v63, v63
	v_pk_mul_f32 v[68:69], v[58:59], v[58:59]
	v_max_f32_e32 v59, v60, v60
	v_max_f32_e32 v62, 0, v62
	v_max_f32_e32 v63, 0, v63
	v_max_f32_e32 v58, v64, v64
	v_max_f32_e32 v60, 0, v59
	v_max_f32_e32 v59, v65, v65
	v_max_f32_e32 v61, v61, v61
	v_pk_mul_f32 v[62:63], v[62:63], v[62:63]
	v_max_f32_e32 v58, 0, v58
	v_max_f32_e32 v59, 0, v59
	v_max_f32_e32 v61, 0, v61
	s_mov_b32 s7, 0x200000
	v_pk_mul_f32 v[64:65], v[58:59], v[58:59]
	v_pk_mul_f32 v[70:71], v[60:61], v[60:61]
	v_cvt_pk_bf16_f32 v58, v62, v63
	v_add_co_u32_e32 v62, vcc, s7, v140
	v_max_f32_e32 v50, v50, v50
	v_max_f32_e32 v51, v51, v51
	v_cvt_pk_bf16_f32 v59, v64, v65
	v_cvt_pk_bf16_f32 v60, v68, v69
	v_cvt_pk_bf16_f32 v61, v70, v71
; __device__ __forceinline__ unsigned pk2(float lo, float hi) { f32x2 v = {lo, hi}; return __builtin_bit_cast(unsigned, __builtin_convertvector(v, bf16x2_t)); }
; #define PG8_WAIT_V(n) asm volatile("s_waitcnt vmcnt(" #n ")" ::: "memory")
; #define PG8_BAR __builtin_amdgcn_s_barrier()
;     __device__ __forceinline__ void operator()(const f32x4 (&acc)[2][2][4][2], const Unit& u, int wr, int wc, int fr, int fq) const {
;     ...
;             for (int m = 0; m < 4; ++m) {
;                 bf16_t* rowp = O + (size_t)(row0 + ai * HALF + m * 16) * ldc + col0;
; #pragma unroll
;                 for (int bj = 0; bj < 2; ++bj) {
;                     f32x4 v0 = acc[ai][bj][m][0], v1 = acc[ai][bj][m][1];
; #pragma unroll
;                     for (int j = 0; j < 4; ++j) { const float a = fmaxf(v0[j], 0.f), b = fmaxf(v1[j], 0.f); v0[j] = a * a; v1[j] = b * b; }
;                     u32x4 w; w.x = pk2(v0[0], v0[1]); w.y = pk2(v0[2], v0[3]); w.z = pk2(v1[0], v1[1]); w.w = pk2(v1[2], v1[3]);
;                     *(u32x4*)(rowp + bj * HALF) = w;
;                 }
; template <class Epi>
; __device__ __forceinline__ void gemm_phase(LAS unsigned char* lds, const Gemm g, const StaticOrder& S, const Epi& E, const int tid) {
;     ...
;         E(acc, cur, wr, wc, fr, fq);
;         if (!has_next) break;
; #pragma unroll
;         for (int a = 0; a < 2; ++a)
; #pragma unroll
;             for (int b = 0; b < 2; ++b)
; #pragma unroll
;                 for (int m = 0; m < 4; ++m)
; #pragma unroll
;                     for (int n = 0; n < 2; ++n) acc[a][b][m][n] = (f32x4){0.f, 0.f, 0.f, 0.f};
;         cur = nxt; cA = nA; cB = nB; ++ui;
;     }
;     PG8_WAIT_V(0);
;     if (wr == 0) PG8_BAR;
	v_addc_co_u32_e32 v63, vcc, 0, v141, vcc
	v_max_f32_e32 v50, 0, v50
	v_max_f32_e32 v51, 0, v51
	global_store_dwordx4 v[62:63], v[58:61], off
	v_max_f32_e32 v54, v54, v54
	v_max_f32_e32 v55, v55, v55
	v_pk_mul_f32 v[58:59], v[50:51], v[50:51]
	v_max_f32_e32 v51, v52, v52
	v_max_f32_e32 v50, v56, v56
	v_max_f32_e32 v52, 0, v51
	v_max_f32_e32 v51, v57, v57
	v_max_f32_e32 v53, v53, v53
	v_max_f32_e32 v54, 0, v54
	v_max_f32_e32 v55, 0, v55
	v_max_f32_e32 v50, 0, v50
	v_max_f32_e32 v51, 0, v51
	v_max_f32_e32 v53, 0, v53
	s_mov_b64 s[16:17], 0x200000
	v_pk_mul_f32 v[54:55], v[54:55], v[54:55]
	v_pk_mul_f32 v[56:57], v[50:51], v[50:51]
	v_pk_mul_f32 v[60:61], v[52:53], v[52:53]
	v_max_f32_e32 v42, v42, v42
	v_max_f32_e32 v43, v43, v43
	v_lshl_add_u64 v[66:67], v[140:141], 0, s[16:17]
	v_cvt_pk_bf16_f32 v50, v54, v55
	v_cvt_pk_bf16_f32 v51, v56, v57
	v_cvt_pk_bf16_f32 v52, v58, v59
	v_cvt_pk_bf16_f32 v53, v60, v61
	v_max_f32_e32 v42, 0, v42
	v_max_f32_e32 v43, 0, v43
	global_store_dwordx4 v[66:67], v[50:53], off offset:256
	v_max_f32_e32 v46, v46, v46
	v_max_f32_e32 v47, v47, v47
	v_pk_mul_f32 v[52:53], v[42:43], v[42:43]
	v_max_f32_e32 v43, v44, v44
	v_max_f32_e32 v46, 0, v46
	v_max_f32_e32 v47, 0, v47
	v_max_f32_e32 v42, v48, v48
	v_max_f32_e32 v44, 0, v43
	v_max_f32_e32 v43, v49, v49
	v_max_f32_e32 v45, v45, v45
	v_pk_mul_f32 v[46:47], v[46:47], v[46:47]
	v_max_f32_e32 v42, 0, v42
	v_max_f32_e32 v43, 0, v43
	v_max_f32_e32 v45, 0, v45
	s_mov_b32 s7, 0x240000
	v_pk_mul_f32 v[48:49], v[42:43], v[42:43]
	v_pk_mul_f32 v[54:55], v[44:45], v[44:45]
	v_cvt_pk_bf16_f32 v42, v46, v47
	v_add_co_u32_e32 v46, vcc, s7, v140
	v_max_f32_e32 v34, v34, v34
	v_max_f32_e32 v35, v35, v35
	v_cvt_pk_bf16_f32 v43, v48, v49
	v_cvt_pk_bf16_f32 v44, v52, v53
	v_cvt_pk_bf16_f32 v45, v54, v55
	v_addc_co_u32_e32 v47, vcc, 0, v141, vcc
	v_max_f32_e32 v34, 0, v34
	v_max_f32_e32 v35, 0, v35
	global_store_dwordx4 v[46:47], v[42:45], off
	v_max_f32_e32 v38, v38, v38
	v_max_f32_e32 v39, v39, v39
	v_pk_mul_f32 v[42:43], v[34:35], v[34:35]
	v_max_f32_e32 v35, v36, v36
	v_max_f32_e32 v34, v40, v40
	v_max_f32_e32 v36, 0, v35
	v_max_f32_e32 v35, v41, v41
	v_max_f32_e32 v37, v37, v37
	v_max_f32_e32 v38, 0, v38
	v_max_f32_e32 v39, 0, v39
	v_max_f32_e32 v34, 0, v34
	v_max_f32_e32 v35, 0, v35
	v_max_f32_e32 v37, 0, v37
	s_mov_b64 s[16:17], 0x240000
	v_pk_mul_f32 v[38:39], v[38:39], v[38:39]
	v_pk_mul_f32 v[40:41], v[34:35], v[34:35]
	v_pk_mul_f32 v[44:45], v[36:37], v[36:37]
	v_max_f32_e32 v26, v26, v26
	v_max_f32_e32 v27, v27, v27
	v_lshl_add_u64 v[50:51], v[140:141], 0, s[16:17]
	v_cvt_pk_bf16_f32 v34, v38, v39
	v_cvt_pk_bf16_f32 v35, v40, v41
	v_cvt_pk_bf16_f32 v36, v42, v43
	v_cvt_pk_bf16_f32 v37, v44, v45
	v_max_f32_e32 v26, 0, v26
	v_max_f32_e32 v27, 0, v27
	global_store_dwordx4 v[50:51], v[34:37], off offset:256
	v_max_f32_e32 v30, v30, v30
	v_max_f32_e32 v31, v31, v31
	v_pk_mul_f32 v[36:37], v[26:27], v[26:27]
	v_max_f32_e32 v27, v28, v28
	v_max_f32_e32 v30, 0, v30
	v_max_f32_e32 v31, 0, v31
	v_max_f32_e32 v26, v32, v32
	v_max_f32_e32 v28, 0, v27
	v_max_f32_e32 v27, v33, v33
	v_max_f32_e32 v29, v29, v29
	v_pk_mul_f32 v[30:31], v[30:31], v[30:31]
	v_max_f32_e32 v26, 0, v26
	v_max_f32_e32 v27, 0, v27
	v_max_f32_e32 v29, 0, v29
	s_mov_b32 s7, 0x280000
	v_pk_mul_f32 v[32:33], v[26:27], v[26:27]
	v_pk_mul_f32 v[38:39], v[28:29], v[28:29]
	v_cvt_pk_bf16_f32 v26, v30, v31
	v_add_co_u32_e32 v30, vcc, s7, v140
	v_max_f32_e32 v18, v18, v18
	v_max_f32_e32 v19, v19, v19
	v_cvt_pk_bf16_f32 v27, v32, v33
	v_cvt_pk_bf16_f32 v28, v36, v37
	v_cvt_pk_bf16_f32 v29, v38, v39
	v_addc_co_u32_e32 v31, vcc, 0, v141, vcc
	v_max_f32_e32 v18, 0, v18
	v_max_f32_e32 v19, 0, v19
	global_store_dwordx4 v[30:31], v[26:29], off
	v_max_f32_e32 v22, v22, v22
	v_max_f32_e32 v23, v23, v23
	v_pk_mul_f32 v[26:27], v[18:19], v[18:19]
	v_max_f32_e32 v19, v20, v20
	v_max_f32_e32 v18, v24, v24
	v_max_f32_e32 v20, 0, v19
	v_max_f32_e32 v19, v25, v25
	v_max_f32_e32 v21, v21, v21
	v_max_f32_e32 v22, 0, v22
	v_max_f32_e32 v23, 0, v23
	v_max_f32_e32 v18, 0, v18
	v_max_f32_e32 v19, 0, v19
	v_max_f32_e32 v21, 0, v21
	s_mov_b64 s[16:17], 0x280000
	v_pk_mul_f32 v[22:23], v[22:23], v[22:23]
	v_pk_mul_f32 v[24:25], v[18:19], v[18:19]
	v_pk_mul_f32 v[28:29], v[20:21], v[20:21]
	v_max_f32_e32 v10, v10, v10
	v_max_f32_e32 v11, v11, v11
	v_lshl_add_u64 v[34:35], v[140:141], 0, s[16:17]
	v_cvt_pk_bf16_f32 v18, v22, v23
	v_cvt_pk_bf16_f32 v19, v24, v25
	v_cvt_pk_bf16_f32 v20, v26, v27
	v_cvt_pk_bf16_f32 v21, v28, v29
	v_max_f32_e32 v10, 0, v10
	v_max_f32_e32 v11, 0, v11
	global_store_dwordx4 v[34:35], v[18:21], off offset:256
	v_max_f32_e32 v14, v14, v14
	v_max_f32_e32 v15, v15, v15
	v_pk_mul_f32 v[20:21], v[10:11], v[10:11]
	v_max_f32_e32 v11, v12, v12
	v_max_f32_e32 v14, 0, v14
	v_max_f32_e32 v15, 0, v15
	v_max_f32_e32 v10, v16, v16
	v_max_f32_e32 v12, 0, v11
	v_max_f32_e32 v11, v17, v17
	v_max_f32_e32 v13, v13, v13
	v_pk_mul_f32 v[14:15], v[14:15], v[14:15]
	v_max_f32_e32 v10, 0, v10
	v_max_f32_e32 v11, 0, v11
	v_max_f32_e32 v13, 0, v13
	s_mov_b32 s7, 0x2c0000
	v_pk_mul_f32 v[16:17], v[10:11], v[10:11]
	v_pk_mul_f32 v[22:23], v[12:13], v[12:13]
	v_cvt_pk_bf16_f32 v10, v14, v15
	v_add_co_u32_e32 v14, vcc, s7, v140
	v_max_f32_e32 v2, v2, v2
	v_max_f32_e32 v3, v3, v3
	v_cvt_pk_bf16_f32 v11, v16, v17
	v_cvt_pk_bf16_f32 v12, v20, v21
	v_cvt_pk_bf16_f32 v13, v22, v23
	v_addc_co_u32_e32 v15, vcc, 0, v141, vcc
	v_max_f32_e32 v2, 0, v2
	v_max_f32_e32 v3, 0, v3
	global_store_dwordx4 v[14:15], v[10:13], off
	v_max_f32_e32 v6, v6, v6
	v_max_f32_e32 v7, v7, v7
	v_pk_mul_f32 v[10:11], v[2:3], v[2:3]
	v_max_f32_e32 v3, v4, v4
	v_max_f32_e32 v2, v8, v8
	v_max_f32_e32 v4, 0, v3
	v_max_f32_e32 v3, v9, v9
	v_max_f32_e32 v5, v5, v5
	v_max_f32_e32 v6, 0, v6
	v_max_f32_e32 v7, 0, v7
	v_max_f32_e32 v2, 0, v2
	v_max_f32_e32 v3, 0, v3
	v_max_f32_e32 v5, 0, v5
	s_mov_b64 s[16:17], 0x2c0000
	v_pk_mul_f32 v[6:7], v[6:7], v[6:7]
	v_pk_mul_f32 v[8:9], v[2:3], v[2:3]
	v_pk_mul_f32 v[12:13], v[4:5], v[4:5]
	v_lshl_add_u64 v[18:19], v[140:141], 0, s[16:17]
	v_cvt_pk_bf16_f32 v2, v6, v7
	v_cvt_pk_bf16_f32 v3, v8, v9
	v_cvt_pk_bf16_f32 v4, v10, v11
	v_cvt_pk_bf16_f32 v5, v12, v13
	s_and_b64 vcc, exec, s[4:5]
	s_mov_b32 s39, s6
	s_mov_b32 s14, s8
	s_mov_b64 s[16:17], s[12:13]
	s_mov_b64 s[18:19], s[10:11]
	global_store_dwordx4 v[18:19], v[2:5], off offset:256
	s_cbranch_vccz .LBB0_77
	s_waitcnt vmcnt(0)
	s_cmpk_gt_u32 s0, 0xff
	s_cbranch_scc1 .LBB0_88
	s_barrier

; #define PG8_STAGE(bufoff, gbase, voff) do { _Pragma("unroll") for (int _i = 0; _i < 2; ++_i) \
;         __builtin_amdgcn_global_load_lds((const unsigned*)((const char*)(gbase) + (voff)[_i]), (LAS unsigned*)(lds + (bufoff) + ldsw + _i * 8192), 16, 0, 0); } while (0)
; #define PG8_LDA(dst, b, h) do { _Pragma("unroll") for (int m = 0; m < 4; ++m) _Pragma("unroll") for (int k = 0; k < 2; ++k) dst[m][k] = *(const LAS bf16x8*)(lds + PG8_SA(b, h) + aoff + m * 2048 + k * 1024); } while (0)
; #define PG8_LDB(dst, b, h) do { _Pragma("unroll") for (int n = 0; n < 2; ++n) _Pragma("unroll") for (int k = 0; k < 2; ++k) dst[n][k] = *(const LAS bf16x8*)(lds + PG8_SB(b, h) + boff + n * 2048 + k * 1024); } while (0)
; #define PG8_MMA(ai, bj, At, Bt) do { __builtin_amdgcn_s_setprio(1); _Pragma("unroll") for (int m = 0; m < 4; ++m) _Pragma("unroll") for (int n = 0; n < 2; ++n) _Pragma("unroll") for (int k = 0; k < 2; ++k) \
;         acc[ai][bj][m][n] = __builtin_amdgcn_mfma_f32_16x16x32_bf16(Bt[n][k], At[m][k], acc[ai][bj][m][n], 0, 0, 0); __builtin_amdgcn_s_setprio(0); } while (0)
; #define PG8_WAIT_V(n) asm volatile("s_waitcnt vmcnt(" #n ")" ::: "memory")
; #define PG8_WAIT_L(n) asm volatile("s_waitcnt lgkmcnt(" #n ")" ::: "memory")
; #define PG8_BAR __builtin_amdgcn_s_barrier()
; template <class Epi>
; __device__ __forceinline__ void gemm_phase(LAS unsigned char* lds, const Gemm g, const StaticOrder& S, const Epi& E, const int tid) {
;     ...
;             const bool last = (t == nt - 2);
;             const char* a1 = cA + (size_t)(t + 1) * kstep;
;             const char* a2 = last ? nA : cA + (size_t)(t + 2) * kstep; const char* b2 = last ? nB : cB + (size_t)(t + 2) * kstep;
;             const char* a3 = a2 + kstep; const char* b3 = b2 + kstep;
;             PG8_LDB(B0, 0, 0); PG8_SCHED; PG8_LDA(At, 0, 0); PG8_STAGE(PG8_SA(1, 1), a1 + hstep, voffA);
;             PG8_WAIT_L(8); PG8_BAR; PG8_WAIT_L(0); PG8_MMA(0, 0, At, B0); PG8_BAR; PG8_SCHED;
;             PG8_LDB(B1, 0, 1); PG8_STAGE(PG8_SB(0, 0), b2, voffB);
;             PG8_BAR; PG8_WAIT_L(0); PG8_MMA(0, 1, At, B1); PG8_BAR;
;             PG8_LDA(At, 0, 1); PG8_STAGE(PG8_SA(0, 0), a2, voffA);
;             PG8_BAR; PG8_WAIT_L(0); PG8_MMA(1, 0, At, B0); PG8_BAR; PG8_SCHED;
;             PG8_STAGE(PG8_SB(0, 1), b2 + hstep, voffB);
;             PG8_WAIT_V(6); PG8_BAR; PG8_MMA(1, 1, At, B1); PG8_BAR;
.Lgprio3:
.LBB0_119:
	s_add_u32 s20, s18, 0xfff80080
	s_addc_u32 s21, s19, -1
	s_add_i32 s50, 0, 0x10000
	v_add_u32_e32 v62, s50, v173
	ds_read_b128 v[42:45], v62
	ds_read_b128 v[46:49], v62 offset:1024
	ds_read_b128 v[58:61], v62 offset:2048
	ds_read_b128 v[62:65], v62 offset:3072
	s_cmp_eq_u32 s49, 28
	s_cselect_b32 s23, s13, s21
	s_cselect_b32 s22, s44, s20
	s_cselect_b32 s21, s11, s48
	s_cselect_b32 s20, s45, s47
	s_add_i32 m0, s3, 0xc000
	ds_read_b128 v[176:179], v174
	ds_read_b128 v[180:183], v174 offset:1024
	ds_read_b128 v[184:187], v174 offset:2048
	ds_read_b128 v[188:191], v174 offset:3072
	ds_read_b128 v[192:195], v174 offset:4096
	ds_read_b128 v[196:199], v174 offset:5120
	ds_read_b128 v[210:213], v174 offset:6144
	ds_read_b128 v[214:217], v174 offset:7168
	global_load_lds_dwordx4 v168, s[18:19]
	v_lshl_add_u64 v[170:171], s[18:19], 0, v[166:167]
	s_add_i32 m0, s3, 0xe000
	s_nop 0
	global_load_lds_dwordx4 v[170:171], off
	s_waitcnt lgkmcnt(8)
	s_barrier
	s_waitcnt lgkmcnt(0)
	v_mfma_f32_16x16x32_bf16 v[142:145], v[42:45], v[176:179], v[142:145]
	v_mfma_f32_16x16x32_bf16 v[138:141], v[58:61], v[176:179], v[138:141]
	v_mfma_f32_16x16x32_bf16 v[126:129], v[42:45], v[184:187], v[126:129]
	v_mfma_f32_16x16x32_bf16 v[122:125], v[58:61], v[184:187], v[122:125]
	v_mfma_f32_16x16x32_bf16 v[110:113], v[42:45], v[192:195], v[110:113]
	v_mfma_f32_16x16x32_bf16 v[106:109], v[58:61], v[192:195], v[106:109]
	v_mfma_f32_16x16x32_bf16 v[94:97], v[42:45], v[210:213], v[94:97]
	v_mfma_f32_16x16x32_bf16 v[90:93], v[58:61], v[210:213], v[90:93]
	v_mfma_f32_16x16x32_bf16 v[142:145], v[46:49], v[180:183], v[142:145]
	v_mfma_f32_16x16x32_bf16 v[138:141], v[62:65], v[180:183], v[138:141]
	v_mfma_f32_16x16x32_bf16 v[126:129], v[46:49], v[188:191], v[126:129]
	v_mfma_f32_16x16x32_bf16 v[122:125], v[62:65], v[188:191], v[122:125]
	v_mfma_f32_16x16x32_bf16 v[110:113], v[46:49], v[196:199], v[110:113]
	v_mfma_f32_16x16x32_bf16 v[106:109], v[62:65], v[196:199], v[106:109]
	v_mfma_f32_16x16x32_bf16 v[94:97], v[46:49], v[214:217], v[94:97]
	v_mfma_f32_16x16x32_bf16 v[90:93], v[62:65], v[214:217], v[90:93]
	s_barrier
	s_add_i32 s54, 0, 0x14000
	v_add_u32_e32 v170, s54, v173
	s_add_i32 s50, s50, s31
	ds_read_b128 v[218:221], v170
	ds_read_b128 v[222:225], v170 offset:1024
	ds_read_b128 v[226:229], v170 offset:2048
	ds_read_b128 v[230:233], v170 offset:3072
	v_lshl_add_u64 v[170:171], s[20:21], 0, v[0:1]
	s_mov_b32 m0, s50
	v_lshl_add_u64 v[200:201], s[20:21], 0, v[164:165]
	global_load_lds_dwordx4 v[170:171], off
	s_add_i32 m0, s50, 0x2000
	s_nop 0
	global_load_lds_dwordx4 v[200:201], off
	s_barrier
	s_waitcnt lgkmcnt(0)
	v_mfma_f32_16x16x32_bf16 v[134:137], v[218:221], v[176:179], v[134:137]
	v_mfma_f32_16x16x32_bf16 v[130:133], v[226:229], v[176:179], v[130:133]
	v_mfma_f32_16x16x32_bf16 v[118:121], v[218:221], v[184:187], v[118:121]
	v_mfma_f32_16x16x32_bf16 v[114:117], v[226:229], v[184:187], v[114:117]
	v_mfma_f32_16x16x32_bf16 v[102:105], v[218:221], v[192:195], v[102:105]
	v_mfma_f32_16x16x32_bf16 v[98:101], v[226:229], v[192:195], v[98:101]
	v_mfma_f32_16x16x32_bf16 v[86:89], v[218:221], v[210:213], v[86:89]
	v_mfma_f32_16x16x32_bf16 v[82:85], v[226:229], v[210:213], v[82:85]
	v_mfma_f32_16x16x32_bf16 v[134:137], v[222:225], v[180:183], v[134:137]
	v_mfma_f32_16x16x32_bf16 v[130:133], v[230:233], v[180:183], v[130:133]
	v_mfma_f32_16x16x32_bf16 v[118:121], v[222:225], v[188:191], v[118:121]
	v_mfma_f32_16x16x32_bf16 v[114:117], v[230:233], v[188:191], v[114:117]
	v_mfma_f32_16x16x32_bf16 v[102:105], v[222:225], v[196:199], v[102:105]
	v_mfma_f32_16x16x32_bf16 v[98:101], v[230:233], v[196:199], v[98:101]
	v_mfma_f32_16x16x32_bf16 v[86:89], v[222:225], v[214:217], v[86:89]
	v_mfma_f32_16x16x32_bf16 v[82:85], v[230:233], v[214:217], v[82:85]
	s_mov_b32 m0, s3
	v_lshl_add_u64 v[234:235], s[22:23], 0, v[160:161]
	s_barrier
	ds_read_b128 v[176:179], v174 offset:16384
	ds_read_b128 v[180:183], v174 offset:17408
	ds_read_b128 v[184:187], v174 offset:18432
	ds_read_b128 v[188:191], v174 offset:19456
	ds_read_b128 v[192:195], v174 offset:20480
	ds_read_b128 v[196:199], v174 offset:21504
	ds_read_b128 v[210:213], v174 offset:22528
	ds_read_b128 v[214:217], v174 offset:23552
	global_load_lds_dwordx4 v[234:235], off
	v_lshl_add_u64 v[236:237], s[22:23], 0, v[162:163]
	s_mov_b32 m0, s34
	s_nop 0
	global_load_lds_dwordx4 v[236:237], off
	s_barrier
	s_waitcnt lgkmcnt(0)
	v_mfma_f32_16x16x32_bf16 v[78:81], v[42:45], v[176:179], v[78:81]
	v_mfma_f32_16x16x32_bf16 v[74:77], v[58:61], v[176:179], v[74:77]
	v_mfma_f32_16x16x32_bf16 v[54:57], v[42:45], v[184:187], v[54:57]
	v_mfma_f32_16x16x32_bf16 v[50:53], v[58:61], v[184:187], v[50:53]
	v_mfma_f32_16x16x32_bf16 v[30:33], v[42:45], v[192:195], v[30:33]
	v_mfma_f32_16x16x32_bf16 v[26:29], v[58:61], v[192:195], v[26:29]
	v_mfma_f32_16x16x32_bf16 v[14:17], v[42:45], v[210:213], v[14:17]
	v_mfma_f32_16x16x32_bf16 v[10:13], v[58:61], v[210:213], v[10:13]
	v_mfma_f32_16x16x32_bf16 v[78:81], v[46:49], v[180:183], v[78:81]
	v_mfma_f32_16x16x32_bf16 v[74:77], v[62:65], v[180:183], v[74:77]
	v_mfma_f32_16x16x32_bf16 v[54:57], v[46:49], v[188:191], v[54:57]
	v_mfma_f32_16x16x32_bf16 v[50:53], v[62:65], v[188:191], v[50:53]
	v_mfma_f32_16x16x32_bf16 v[30:33], v[46:49], v[196:199], v[30:33]
	v_mfma_f32_16x16x32_bf16 v[26:29], v[62:65], v[196:199], v[26:29]
	v_mfma_f32_16x16x32_bf16 v[14:17], v[46:49], v[214:217], v[14:17]
	v_mfma_f32_16x16x32_bf16 v[10:13], v[62:65], v[214:217], v[10:13]
	s_barrier
	s_add_u32 s52, s20, 0x80000
	s_addc_u32 s53, s21, 0
	s_add_i32 s50, s54, s31
	s_mov_b32 m0, s50
	s_nop 0
	global_load_lds_dwordx4 v0, s[52:53]
	s_add_i32 m0, s50, 0x2000
	s_nop 0
	global_load_lds_dwordx4 v164, s[52:53]
	s_waitcnt vmcnt(6)
	s_barrier
; #define PG8_STAGE(bufoff, gbase, voff) do { _Pragma("unroll") for (int _i = 0; _i < 2; ++_i) \
;         __builtin_amdgcn_global_load_lds((const unsigned*)((const char*)(gbase) + (voff)[_i]), (LAS unsigned*)(lds + (bufoff) + ldsw + _i * 8192), 16, 0, 0); } while (0)
; #define PG8_LDA(dst, b, h) do { _Pragma("unroll") for (int m = 0; m < 4; ++m) _Pragma("unroll") for (int k = 0; k < 2; ++k) dst[m][k] = *(const LAS bf16x8*)(lds + PG8_SA(b, h) + aoff + m * 2048 + k * 1024); } while (0)
; #define PG8_LDB(dst, b, h) do { _Pragma("unroll") for (int n = 0; n < 2; ++n) _Pragma("unroll") for (int k = 0; k < 2; ++k) dst[n][k] = *(const LAS bf16x8*)(lds + PG8_SB(b, h) + boff + n * 2048 + k * 1024); } while (0)
; #define PG8_MMA(ai, bj, At, Bt) do { __builtin_amdgcn_s_setprio(1); _Pragma("unroll") for (int m = 0; m < 4; ++m) _Pragma("unroll") for (int n = 0; n < 2; ++n) _Pragma("unroll") for (int k = 0; k < 2; ++k) \
;         acc[ai][bj][m][n] = __builtin_amdgcn_mfma_f32_16x16x32_bf16(Bt[n][k], At[m][k], acc[ai][bj][m][n], 0, 0, 0); __builtin_amdgcn_s_setprio(0); } while (0)
; #define PG8_WAIT_V(n) asm volatile("s_waitcnt vmcnt(" #n ")" ::: "memory")
; #define PG8_WAIT_L(n) asm volatile("s_waitcnt lgkmcnt(" #n ")" ::: "memory")
; #define PG8_BAR __builtin_amdgcn_s_barrier()
; #define PG8_SCHED __builtin_amdgcn_sched_barrier(0)
; template <class Epi>
; __device__ __forceinline__ void gemm_phase(LAS unsigned char* lds, const Gemm g, const StaticOrder& S, const Epi& E, const int tid) {
;     ...
;             PG8_WAIT_V(6); PG8_BAR; PG8_MMA(1, 1, At, B1); PG8_BAR;
;             PG8_LDB(B0, 1, 0); PG8_SCHED; PG8_LDA(At, 1, 0); PG8_STAGE(PG8_SA(0, 1), a2 + hstep, voffA);
;             PG8_WAIT_L(8); PG8_BAR; PG8_WAIT_L(0); PG8_MMA(0, 0, At, B0); PG8_BAR; PG8_SCHED;
;             PG8_LDB(B1, 1, 1); PG8_STAGE(PG8_SB(1, 0), b3, voffB);
;             PG8_BAR; PG8_WAIT_L(0); PG8_MMA(0, 1, At, B1); PG8_BAR;
;             PG8_LDA(At, 1, 1); PG8_STAGE(PG8_SA(1, 0), a3, voffA);
	v_mfma_f32_16x16x32_bf16 v[38:41], v[218:221], v[184:187], v[38:41]
	v_mfma_f32_16x16x32_bf16 v[34:37], v[226:229], v[184:187], v[34:37]
	v_mfma_f32_16x16x32_bf16 v[22:25], v[218:221], v[192:195], v[22:25]
	v_mfma_f32_16x16x32_bf16 v[18:21], v[226:229], v[192:195], v[18:21]
	v_mfma_f32_16x16x32_bf16 v[6:9], v[218:221], v[210:213], v[6:9]
	v_mfma_f32_16x16x32_bf16 v[2:5], v[226:229], v[210:213], v[2:5]
	v_mfma_f32_16x16x32_bf16 v[42:45], v[218:221], v[176:179], v[70:73]
	v_mfma_f32_16x16x32_bf16 v[46:49], v[226:229], v[176:179], v[66:69]
	v_mfma_f32_16x16x32_bf16 v[38:41], v[222:225], v[188:191], v[38:41]
	v_mfma_f32_16x16x32_bf16 v[34:37], v[230:233], v[188:191], v[34:37]
	v_mfma_f32_16x16x32_bf16 v[22:25], v[222:225], v[196:199], v[22:25]
	v_mfma_f32_16x16x32_bf16 v[18:21], v[230:233], v[196:199], v[18:21]
	v_mfma_f32_16x16x32_bf16 v[6:9], v[222:225], v[214:217], v[6:9]
	v_mfma_f32_16x16x32_bf16 v[2:5], v[230:233], v[214:217], v[2:5]
	v_mfma_f32_16x16x32_bf16 v[42:45], v[222:225], v[180:183], v[42:45]
	v_mfma_f32_16x16x32_bf16 v[46:49], v[230:233], v[180:183], v[46:49]
	s_add_i32 s50, 0, 0x18000
	v_add_u32_e32 v70, s50, v173
	s_barrier
	ds_read_b128 v[58:61], v70
	ds_read_b128 v[62:65], v70 offset:1024
	ds_read_b128 v[66:69], v70 offset:2048
	ds_read_b128 v[70:73], v70 offset:3072
	s_add_u32 s22, s22, 0x80000
	s_addc_u32 s23, s23, 0
	s_mov_b32 m0, s35
	ds_read_b128 v[176:179], v174 offset:32768
	ds_read_b128 v[180:183], v174 offset:33792
	ds_read_b128 v[184:187], v174 offset:34816
	ds_read_b128 v[188:191], v174 offset:35840
	ds_read_b128 v[192:195], v174 offset:36864
	ds_read_b128 v[196:199], v174 offset:37888
	ds_read_b128 v[210:213], v174 offset:38912
	ds_read_b128 v[214:217], v174 offset:39936
	global_load_lds_dwordx4 v160, s[22:23]
	s_mov_b32 m0, s36
	s_nop 0
	global_load_lds_dwordx4 v162, s[22:23]
	s_waitcnt lgkmcnt(8)
	s_barrier
	s_waitcnt lgkmcnt(0)
	v_mfma_f32_16x16x32_bf16 v[142:145], v[58:61], v[176:179], v[142:145]
	v_mfma_f32_16x16x32_bf16 v[138:141], v[66:69], v[176:179], v[138:141]
	v_mfma_f32_16x16x32_bf16 v[126:129], v[58:61], v[184:187], v[126:129]
	v_mfma_f32_16x16x32_bf16 v[122:125], v[66:69], v[184:187], v[122:125]
	v_mfma_f32_16x16x32_bf16 v[110:113], v[58:61], v[192:195], v[110:113]
	v_mfma_f32_16x16x32_bf16 v[106:109], v[66:69], v[192:195], v[106:109]
	v_mfma_f32_16x16x32_bf16 v[94:97], v[58:61], v[210:213], v[94:97]
	v_mfma_f32_16x16x32_bf16 v[90:93], v[66:69], v[210:213], v[90:93]
	v_mfma_f32_16x16x32_bf16 v[142:145], v[62:65], v[180:183], v[142:145]
	v_mfma_f32_16x16x32_bf16 v[138:141], v[70:73], v[180:183], v[138:141]
	v_mfma_f32_16x16x32_bf16 v[126:129], v[62:65], v[188:191], v[126:129]
	v_mfma_f32_16x16x32_bf16 v[122:125], v[70:73], v[188:191], v[122:125]
	v_mfma_f32_16x16x32_bf16 v[110:113], v[62:65], v[196:199], v[110:113]
	v_mfma_f32_16x16x32_bf16 v[106:109], v[70:73], v[196:199], v[106:109]
	v_mfma_f32_16x16x32_bf16 v[94:97], v[62:65], v[214:217], v[94:97]
	v_mfma_f32_16x16x32_bf16 v[90:93], v[70:73], v[214:217], v[90:93]
	s_barrier
	s_add_i32 s22, 0, 0x1c000
	s_add_i32 s23, s50, s31
	v_add_u32_e32 v175, s22, v173
	v_lshl_add_u64 v[170:171], v[170:171], 0, s[56:57]
	s_mov_b32 m0, s23
	ds_read_b128 v[218:221], v175
	ds_read_b128 v[222:225], v175 offset:1024
	ds_read_b128 v[226:229], v175 offset:2048
	ds_read_b128 v[230:233], v175 offset:3072
	global_load_lds_dwordx4 v[170:171], off
	v_lshl_add_u64 v[170:171], v[200:201], 0, s[56:57]
	s_add_i32 m0, s23, 0x2000
	s_nop 0
	global_load_lds_dwordx4 v[170:171], off
	s_barrier
	s_waitcnt lgkmcnt(0)
	v_mfma_f32_16x16x32_bf16 v[134:137], v[218:221], v[176:179], v[134:137]
	v_mfma_f32_16x16x32_bf16 v[130:133], v[226:229], v[176:179], v[130:133]
	v_mfma_f32_16x16x32_bf16 v[118:121], v[218:221], v[184:187], v[118:121]
	v_mfma_f32_16x16x32_bf16 v[114:117], v[226:229], v[184:187], v[114:117]
	v_mfma_f32_16x16x32_bf16 v[102:105], v[218:221], v[192:195], v[102:105]
	v_mfma_f32_16x16x32_bf16 v[98:101], v[226:229], v[192:195], v[98:101]
	v_mfma_f32_16x16x32_bf16 v[86:89], v[218:221], v[210:213], v[86:89]
	v_mfma_f32_16x16x32_bf16 v[82:85], v[226:229], v[210:213], v[82:85]
	v_mfma_f32_16x16x32_bf16 v[134:137], v[222:225], v[180:183], v[134:137]
	v_mfma_f32_16x16x32_bf16 v[130:133], v[230:233], v[180:183], v[130:133]
	v_mfma_f32_16x16x32_bf16 v[118:121], v[222:225], v[188:191], v[118:121]
	v_mfma_f32_16x16x32_bf16 v[114:117], v[230:233], v[188:191], v[114:117]
	v_mfma_f32_16x16x32_bf16 v[102:105], v[222:225], v[196:199], v[102:105]
	v_mfma_f32_16x16x32_bf16 v[98:101], v[230:233], v[196:199], v[98:101]
	v_mfma_f32_16x16x32_bf16 v[86:89], v[222:225], v[214:217], v[86:89]
	v_mfma_f32_16x16x32_bf16 v[82:85], v[230:233], v[214:217], v[82:85]
	s_mov_b32 m0, s39
	v_lshl_add_u64 v[170:171], v[234:235], 0, s[56:57]
	s_barrier
	ds_read_b128 v[176:179], v174 offset:49152
	ds_read_b128 v[180:183], v174 offset:50176
	ds_read_b128 v[184:187], v174 offset:51200
	ds_read_b128 v[188:191], v174 offset:52224
	ds_read_b128 v[192:195], v174 offset:53248
	ds_read_b128 v[196:199], v174 offset:54272
	ds_read_b128 v[210:213], v174 offset:55296
	ds_read_b128 v[214:217], v174 offset:56320
	global_load_lds_dwordx4 v[170:171], off
	v_lshl_add_u64 v[170:171], v[236:237], 0, s[56:57]
	s_mov_b32 m0, s40
	s_nop 0
	global_load_lds_dwordx4 v[170:171], off
	s_barrier
; __device__ __forceinline__ unsigned pk2(float lo, float hi) { f32x2 v = {lo, hi}; return __builtin_bit_cast(unsigned, __builtin_convertvector(v, bf16x2_t)); }
; __device__ __forceinline__ float bf_lo(unsigned w) { return __uint_as_float(w << 16); }
; __device__ __forceinline__ float bf_hi(unsigned w) { return __uint_as_float(w & 0xffff0000u); }
;     __device__ __forceinline__ void operator()(const f32x4 (&acc)[2][2][4][2], const Unit& u, int wr, int wc, int fr, int fq) const {
;     ...
;         const int row0 = u.pm * BM + wr * 64 + fr, col0 = u.pn * BM + wc * 32 + 8 * fq;
;         const float* gp = gate + (size_t)(u.pm >> 5) * 12288 + col0;
;         f32x4 gv[2][2];
; #pragma unroll
;         for (int bj = 0; bj < 2; ++bj)
; #pragma unroll
;             for (int n = 0; n < 2; ++n) gv[bj][n] = *(const f32x4*)(gp + bj * HALF + 4 * n);
; #pragma unroll
;         for (int ai = 0; ai < 2; ++ai)
; #pragma unroll
;             for (int m = 0; m < 4; ++m) {
;                 const size_t ro = (size_t)(row0 + ai * HALF + m * 16) * DM + col0;
; #pragma unroll
;                 for (int bj = 0; bj < 2; ++bj) {
;                     f32x4 r0, r1;
;                     if (RB) { const u32x4 rw = *(const u32x4*)((const bf16_t*)resid + ro + bj * HALF);
;                         r0 = (f32x4){bf_lo(rw.x), bf_hi(rw.x), bf_lo(rw.y), bf_hi(rw.y)}; r1 = (f32x4){bf_lo(rw.z), bf_hi(rw.z), bf_lo(rw.w), bf_hi(rw.w)}; }
;                     else { r0 = *(const f32x4*)((const float*)resid + ro + bj * HALF); r1 = *(const f32x4*)((const float*)resid + ro + bj * HALF + 4); }
;                     const f32x4 v0 = r0 + gv[bj][0] * acc[ai][bj][m][0], v1 = r1 + gv[bj][1] * acc[ai][bj][m][1];
;                     if (OB) { u32x4 w; w.x = pk2(v0[0], v0[1]); w.y = pk2(v0[2], v0[3]); w.z = pk2(v1[0], v1[1]); w.w = pk2(v1[2], v1[3]); *(u32x4*)((bf16_t*)out + ro + bj * HALF) = w; }
;                     else { *(f32x4*)((float*)out + ro + bj * HALF) = v0; *(f32x4*)((float*)out + ro + bj * HALF + 4) = v1; }
; template <class Epi>
; __device__ __forceinline__ void gemm_phase(LAS unsigned char* lds, const Gemm g, const StaticOrder& S, const Epi& E, const int tid) {
;     ...
;             PG8_BAR; PG8_WAIT_L(0); PG8_MMA(1, 0, At, B0); PG8_BAR; PG8_SCHED;
;             PG8_STAGE(PG8_SB(1, 1), b3 + hstep, voffB);
;             PG8_WAIT_V(6); PG8_BAR; PG8_MMA(1, 1, At, B1); PG8_BAR;
	s_waitcnt lgkmcnt(0)
	v_mfma_f32_16x16x32_bf16 v[78:81], v[58:61], v[176:179], v[78:81]
	v_mfma_f32_16x16x32_bf16 v[74:77], v[66:69], v[176:179], v[74:77]
	v_mfma_f32_16x16x32_bf16 v[54:57], v[58:61], v[184:187], v[54:57]
	v_mfma_f32_16x16x32_bf16 v[50:53], v[66:69], v[184:187], v[50:53]
	v_mfma_f32_16x16x32_bf16 v[30:33], v[58:61], v[192:195], v[30:33]
	v_mfma_f32_16x16x32_bf16 v[26:29], v[66:69], v[192:195], v[26:29]
	v_mfma_f32_16x16x32_bf16 v[14:17], v[58:61], v[210:213], v[14:17]
	v_mfma_f32_16x16x32_bf16 v[10:13], v[66:69], v[210:213], v[10:13]
	v_mfma_f32_16x16x32_bf16 v[78:81], v[62:65], v[180:183], v[78:81]
	v_mfma_f32_16x16x32_bf16 v[74:77], v[70:73], v[180:183], v[74:77]
	v_mfma_f32_16x16x32_bf16 v[54:57], v[62:65], v[188:191], v[54:57]
	v_mfma_f32_16x16x32_bf16 v[50:53], v[70:73], v[188:191], v[50:53]
	v_mfma_f32_16x16x32_bf16 v[30:33], v[62:65], v[196:199], v[30:33]
	v_mfma_f32_16x16x32_bf16 v[26:29], v[70:73], v[196:199], v[26:29]
	v_mfma_f32_16x16x32_bf16 v[14:17], v[62:65], v[214:217], v[14:17]
	v_mfma_f32_16x16x32_bf16 v[10:13], v[70:73], v[214:217], v[10:13]
	s_barrier
	s_add_u32 s20, s20, 0x80080
	s_addc_u32 s21, s21, 0
	s_add_i32 s22, s22, s31
	s_mov_b32 m0, s22
	s_nop 0
	global_load_lds_dwordx4 v0, s[20:21]
	s_add_i32 m0, s22, 0x2000
	s_nop 0
	global_load_lds_dwordx4 v164, s[20:21]
	s_waitcnt vmcnt(6)
	s_barrier
	v_mfma_f32_16x16x32_bf16 v[42:45], v[218:221], v[176:179], v[42:45]
	v_mfma_f32_16x16x32_bf16 v[70:73], v[222:225], v[180:183], v[42:45]
	v_mfma_f32_16x16x32_bf16 v[42:45], v[226:229], v[176:179], v[46:49]
	v_mfma_f32_16x16x32_bf16 v[38:41], v[218:221], v[184:187], v[38:41]
	v_mfma_f32_16x16x32_bf16 v[34:37], v[226:229], v[184:187], v[34:37]
	v_mfma_f32_16x16x32_bf16 v[22:25], v[218:221], v[192:195], v[22:25]
	v_mfma_f32_16x16x32_bf16 v[18:21], v[226:229], v[192:195], v[18:21]
	v_mfma_f32_16x16x32_bf16 v[6:9], v[218:221], v[210:213], v[6:9]
	v_mfma_f32_16x16x32_bf16 v[2:5], v[226:229], v[210:213], v[2:5]
	v_mfma_f32_16x16x32_bf16 v[66:69], v[230:233], v[180:183], v[42:45]
	v_mfma_f32_16x16x32_bf16 v[38:41], v[222:225], v[188:191], v[38:41]
	v_mfma_f32_16x16x32_bf16 v[34:37], v[230:233], v[188:191], v[34:37]
	v_mfma_f32_16x16x32_bf16 v[22:25], v[222:225], v[196:199], v[22:25]
	v_mfma_f32_16x16x32_bf16 v[18:21], v[230:233], v[196:199], v[18:21]
	v_mfma_f32_16x16x32_bf16 v[6:9], v[222:225], v[214:217], v[6:9]
	v_mfma_f32_16x16x32_bf16 v[2:5], v[230:233], v[214:217], v[2:5]
	s_add_i32 s49, s49, 2
	s_add_u32 s47, s47, 0x100
	s_addc_u32 s48, s48, 0
	s_add_u32 s18, s18, 0x100
	s_addc_u32 s19, s19, 0
	s_cmp_gt_u32 s49, 29
	s_barrier
	s_cbranch_scc0 .LBB0_119
	s_setprio 0
	s_lshl_b32 s11, s2, 8
	s_lshl_b32 s13, s43, 8
	v_mov_b32_e32 v175, v172
	v_mov_b32_e32 v42, v159
	s_add_i32 s11, s11, s37
	s_or_b32 s13, s13, s38
	s_ashr_i32 s2, s2, 5
	s_mov_b32 s43, s10
	v_lshl_add_u32 v170, v42, 3, s13
	s_mul_hi_i32 s13, s2, 0xc000
	s_mul_i32 s2, s2, 0xc000
	v_add_u32_e32 v176, s11, v175
	s_add_u32 s18, s27, s2
	v_ashrrev_i32_e32 v177, 31, v176
	s_addc_u32 s19, s28, s13
	v_ashrrev_i32_e32 v171, 31, v170
	v_lshlrev_b64 v[176:177], 11, v[176:177]
	v_lshl_add_u64 v[46:47], v[170:171], 2, s[18:19]
	v_lshl_add_u64 v[170:171], v[176:177], 0, v[170:171]
	v_lshlrev_b64 v[170:171], 1, v[170:171]
	v_lshl_add_u64 v[180:181], s[8:9], 0, v[170:171]
	global_load_dwordx4 v[58:61], v[46:47], off offset:16
	global_load_dwordx4 v[62:65], v[46:47], off
	global_load_dwordx4 v[42:45], v[46:47], off offset:528
	s_nop 0
	global_load_dwordx4 v[46:49], v[46:47], off offset:512
	s_mov_b64 s[92:93], s[8:9]
	s_mov_b64 s[94:95], s[6:7]
	global_load_dwordx4 v[184:187], v170, s[92:93]
	global_load_dwordx4 v[188:191], v170, s[92:93] offset:256
	s_add_u32 s92, s92, 0x10000
	s_addc_u32 s93, s93, 0
	global_load_dwordx4 v[192:195], v170, s[92:93]
	global_load_dwordx4 v[196:199], v170, s[92:93] offset:256
	s_add_u32 s92, s92, 0x10000
	s_addc_u32 s93, s93, 0
	global_load_dwordx4 v[210:213], v170, s[92:93]
	global_load_dwordx4 v[214:217], v170, s[92:93] offset:256
	s_add_u32 s92, s92, 0x10000
	s_addc_u32 s93, s93, 0
	global_load_dwordx4 v[218:221], v170, s[92:93]
	global_load_dwordx4 v[222:225], v170, s[92:93] offset:256
	s_add_u32 s92, s92, 0x50000
	s_addc_u32 s93, s93, 0
	global_load_dwordx4 v[226:229], v170, s[92:93]
	global_load_dwordx4 v[230:233], v170, s[92:93] offset:256
	s_add_u32 s92, s92, 0x10000
	s_addc_u32 s93, s93, 0
	global_load_dwordx4 v[234:237], v170, s[92:93]
	s_waitcnt vmcnt(10)
	v_lshlrev_b32_e32 v176, 16, v184
	v_and_b32_e32 v177, 0xffff0000, v184
	v_lshlrev_b32_e32 v178, 16, v185
	v_and_b32_e32 v179, 0xffff0000, v185
	v_lshlrev_b32_e32 v180, 16, v186
	v_and_b32_e32 v181, 0xffff0000, v186
	v_lshlrev_b32_e32 v182, 16, v187
	v_and_b32_e32 v183, 0xffff0000, v187
	v_pk_fma_f32 v[142:143], v[142:143], v[62:63], v[176:177]
	v_pk_fma_f32 v[144:145], v[144:145], v[64:65], v[178:179]
	v_pk_fma_f32 v[138:139], v[138:139], v[58:59], v[180:181]
	v_pk_fma_f32 v[140:141], v[140:141], v[60:61], v[182:183]
	global_load_dwordx4 v[184:187], v170, s[92:93] offset:256
	v_cvt_pk_bf16_f32 v142, v142, v143
	v_cvt_pk_bf16_f32 v143, v144, v145
	v_cvt_pk_bf16_f32 v144, v138, v139
	v_cvt_pk_bf16_f32 v145, v140, v141
	global_store_dwordx4 v170, v[142:145], s[94:95]
	s_waitcnt vmcnt(11)
; __device__ __forceinline__ unsigned pk2(float lo, float hi) { f32x2 v = {lo, hi}; return __builtin_bit_cast(unsigned, __builtin_convertvector(v, bf16x2_t)); }
; __device__ __forceinline__ float bf_lo(unsigned w) { return __uint_as_float(w << 16); }
; __device__ __forceinline__ float bf_hi(unsigned w) { return __uint_as_float(w & 0xffff0000u); }
;     __device__ __forceinline__ void operator()(const f32x4 (&acc)[2][2][4][2], const Unit& u, int wr, int wc, int fr, int fq) const {
;     ...
;                 for (int bj = 0; bj < 2; ++bj) {
;                     f32x4 r0, r1;
;                     if (RB) { const u32x4 rw = *(const u32x4*)((const bf16_t*)resid + ro + bj * HALF);
;                         r0 = (f32x4){bf_lo(rw.x), bf_hi(rw.x), bf_lo(rw.y), bf_hi(rw.y)}; r1 = (f32x4){bf_lo(rw.z), bf_hi(rw.z), bf_lo(rw.w), bf_hi(rw.w)}; }
;                     else { r0 = *(const f32x4*)((const float*)resid + ro + bj * HALF); r1 = *(const f32x4*)((const float*)resid + ro + bj * HALF + 4); }
;                     const f32x4 v0 = r0 + gv[bj][0] * acc[ai][bj][m][0], v1 = r1 + gv[bj][1] * acc[ai][bj][m][1];
;                     if (OB) { u32x4 w; w.x = pk2(v0[0], v0[1]); w.y = pk2(v0[2], v0[3]); w.z = pk2(v1[0], v1[1]); w.w = pk2(v1[2], v1[3]); *(u32x4*)((bf16_t*)out + ro + bj * HALF) = w; }
;                     else { *(f32x4*)((float*)out + ro + bj * HALF) = v0; *(f32x4*)((float*)out + ro + bj * HALF + 4) = v1; }
	v_lshlrev_b32_e32 v176, 16, v188
	v_and_b32_e32 v177, 0xffff0000, v188
	v_lshlrev_b32_e32 v178, 16, v189
	v_and_b32_e32 v179, 0xffff0000, v189
	v_lshlrev_b32_e32 v180, 16, v190
	v_and_b32_e32 v181, 0xffff0000, v190
	v_lshlrev_b32_e32 v182, 16, v191
	v_and_b32_e32 v183, 0xffff0000, v191
	v_pk_fma_f32 v[134:135], v[134:135], v[46:47], v[176:177]
	v_pk_fma_f32 v[136:137], v[136:137], v[48:49], v[178:179]
	v_pk_fma_f32 v[130:131], v[130:131], v[42:43], v[180:181]
	v_pk_fma_f32 v[132:133], v[132:133], v[44:45], v[182:183]
	s_add_u32 s92, s92, 0x10000
	s_addc_u32 s93, s93, 0
	global_load_dwordx4 v[188:191], v170, s[92:93]
	v_cvt_pk_bf16_f32 v134, v134, v135
	v_cvt_pk_bf16_f32 v135, v136, v137
	v_cvt_pk_bf16_f32 v136, v130, v131
	v_cvt_pk_bf16_f32 v137, v132, v133
	global_store_dwordx4 v170, v[134:137], s[94:95] offset:256
	s_waitcnt vmcnt(12)
	v_lshlrev_b32_e32 v176, 16, v192
	v_and_b32_e32 v177, 0xffff0000, v192
	v_lshlrev_b32_e32 v178, 16, v193
	v_and_b32_e32 v179, 0xffff0000, v193
	v_lshlrev_b32_e32 v180, 16, v194
	v_and_b32_e32 v181, 0xffff0000, v194
	v_lshlrev_b32_e32 v182, 16, v195
	v_and_b32_e32 v183, 0xffff0000, v195
	v_pk_fma_f32 v[126:127], v[126:127], v[62:63], v[176:177]
	v_pk_fma_f32 v[128:129], v[128:129], v[64:65], v[178:179]
	v_pk_fma_f32 v[122:123], v[122:123], v[58:59], v[180:181]
	v_pk_fma_f32 v[124:125], v[124:125], v[60:61], v[182:183]
	global_load_dwordx4 v[192:195], v170, s[92:93] offset:256
	s_add_u32 s94, s94, 0x10000
	s_addc_u32 s95, s95, 0
	v_cvt_pk_bf16_f32 v126, v126, v127
	v_cvt_pk_bf16_f32 v127, v128, v129
	v_cvt_pk_bf16_f32 v128, v122, v123
	v_cvt_pk_bf16_f32 v129, v124, v125
	global_store_dwordx4 v170, v[126:129], s[94:95]
	s_waitcnt vmcnt(13)
	v_lshlrev_b32_e32 v176, 16, v196
	v_and_b32_e32 v177, 0xffff0000, v196
	v_lshlrev_b32_e32 v178, 16, v197
	v_and_b32_e32 v179, 0xffff0000, v197
	v_lshlrev_b32_e32 v180, 16, v198
	v_and_b32_e32 v181, 0xffff0000, v198
	v_lshlrev_b32_e32 v182, 16, v199
	v_and_b32_e32 v183, 0xffff0000, v199
	v_pk_fma_f32 v[118:119], v[118:119], v[46:47], v[176:177]
	v_pk_fma_f32 v[120:121], v[120:121], v[48:49], v[178:179]
	v_pk_fma_f32 v[114:115], v[114:115], v[42:43], v[180:181]
	v_pk_fma_f32 v[116:117], v[116:117], v[44:45], v[182:183]
	s_add_u32 s92, s92, 0x10000
	s_addc_u32 s93, s93, 0
	global_load_dwordx4 v[196:199], v170, s[92:93]
	v_cvt_pk_bf16_f32 v118, v118, v119
	v_cvt_pk_bf16_f32 v119, v120, v121
	v_cvt_pk_bf16_f32 v120, v114, v115
	v_cvt_pk_bf16_f32 v121, v116, v117
	global_store_dwordx4 v170, v[118:121], s[94:95] offset:256
	s_waitcnt vmcnt(14)
	v_lshlrev_b32_e32 v176, 16, v210
	v_and_b32_e32 v177, 0xffff0000, v210
	v_lshlrev_b32_e32 v178, 16, v211
	v_and_b32_e32 v179, 0xffff0000, v211
	v_lshlrev_b32_e32 v180, 16, v212
	v_and_b32_e32 v181, 0xffff0000, v212
	v_lshlrev_b32_e32 v182, 16, v213
	v_and_b32_e32 v183, 0xffff0000, v213
	v_pk_fma_f32 v[110:111], v[110:111], v[62:63], v[176:177]
	v_pk_fma_f32 v[112:113], v[112:113], v[64:65], v[178:179]
	v_pk_fma_f32 v[106:107], v[106:107], v[58:59], v[180:181]
	v_pk_fma_f32 v[108:109], v[108:109], v[60:61], v[182:183]
	global_load_dwordx4 v[210:213], v170, s[92:93] offset:256
	s_add_u32 s94, s94, 0x10000
	s_addc_u32 s95, s95, 0
	v_cvt_pk_bf16_f32 v110, v110, v111
	v_cvt_pk_bf16_f32 v111, v112, v113
	v_cvt_pk_bf16_f32 v112, v106, v107
	v_cvt_pk_bf16_f32 v113, v108, v109
	global_store_dwordx4 v170, v[110:113], s[94:95]
	s_waitcnt vmcnt(15)
	v_lshlrev_b32_e32 v176, 16, v214
	v_and_b32_e32 v177, 0xffff0000, v214
	v_lshlrev_b32_e32 v178, 16, v215
	v_and_b32_e32 v179, 0xffff0000, v215
	v_lshlrev_b32_e32 v180, 16, v216
	v_and_b32_e32 v181, 0xffff0000, v216
	v_lshlrev_b32_e32 v182, 16, v217
	v_and_b32_e32 v183, 0xffff0000, v217
	v_pk_fma_f32 v[102:103], v[102:103], v[46:47], v[176:177]
	v_pk_fma_f32 v[104:105], v[104:105], v[48:49], v[178:179]
	v_pk_fma_f32 v[98:99], v[98:99], v[42:43], v[180:181]
	v_pk_fma_f32 v[100:101], v[100:101], v[44:45], v[182:183]
	v_cvt_pk_bf16_f32 v102, v102, v103
	v_cvt_pk_bf16_f32 v103, v104, v105
	v_cvt_pk_bf16_f32 v104, v98, v99
	v_cvt_pk_bf16_f32 v105, v100, v101
	global_store_dwordx4 v170, v[102:105], s[94:95] offset:256
	s_waitcnt vmcnt(15)
	v_lshlrev_b32_e32 v176, 16, v218
	v_and_b32_e32 v177, 0xffff0000, v218
	v_lshlrev_b32_e32 v178, 16, v219
	v_and_b32_e32 v179, 0xffff0000, v219
	v_lshlrev_b32_e32 v180, 16, v220
	v_and_b32_e32 v181, 0xffff0000, v220
	v_lshlrev_b32_e32 v182, 16, v221
	v_and_b32_e32 v183, 0xffff0000, v221
	v_pk_fma_f32 v[94:95], v[94:95], v[62:63], v[176:177]
	v_pk_fma_f32 v[96:97], v[96:97], v[64:65], v[178:179]
	v_pk_fma_f32 v[90:91], v[90:91], v[58:59], v[180:181]
	v_pk_fma_f32 v[92:93], v[92:93], v[60:61], v[182:183]
	s_add_u32 s94, s94, 0x10000
	s_addc_u32 s95, s95, 0
	v_cvt_pk_bf16_f32 v94, v94, v95
	v_cvt_pk_bf16_f32 v95, v96, v97
	v_cvt_pk_bf16_f32 v96, v90, v91
	v_cvt_pk_bf16_f32 v97, v92, v93
	global_store_dwordx4 v170, v[94:97], s[94:95]
	s_waitcnt vmcnt(15)
	v_lshlrev_b32_e32 v176, 16, v222
	v_and_b32_e32 v177, 0xffff0000, v222
	v_lshlrev_b32_e32 v178, 16, v223
	v_and_b32_e32 v179, 0xffff0000, v223
	v_lshlrev_b32_e32 v180, 16, v224
	v_and_b32_e32 v181, 0xffff0000, v224
	v_lshlrev_b32_e32 v182, 16, v225
	v_and_b32_e32 v183, 0xffff0000, v225
	v_pk_fma_f32 v[86:87], v[86:87], v[46:47], v[176:177]
	v_pk_fma_f32 v[88:89], v[88:89], v[48:49], v[178:179]
	v_pk_fma_f32 v[82:83], v[82:83], v[42:43], v[180:181]
	v_pk_fma_f32 v[84:85], v[84:85], v[44:45], v[182:183]
	v_cvt_pk_bf16_f32 v86, v86, v87
	v_cvt_pk_bf16_f32 v87, v88, v89
	v_cvt_pk_bf16_f32 v88, v82, v83
	v_cvt_pk_bf16_f32 v89, v84, v85
	global_store_dwordx4 v170, v[86:89], s[94:95] offset:256
	s_waitcnt vmcnt(15)
; __device__ __forceinline__ unsigned pk2(float lo, float hi) { f32x2 v = {lo, hi}; return __builtin_bit_cast(unsigned, __builtin_convertvector(v, bf16x2_t)); }
; __device__ __forceinline__ float bf_lo(unsigned w) { return __uint_as_float(w << 16); }
; __device__ __forceinline__ float bf_hi(unsigned w) { return __uint_as_float(w & 0xffff0000u); }
; #define PG8_WAIT_V(n) asm volatile("s_waitcnt vmcnt(" #n ")" ::: "memory")
; #define PG8_BAR __builtin_amdgcn_s_barrier()
;     __device__ __forceinline__ void operator()(const f32x4 (&acc)[2][2][4][2], const Unit& u, int wr, int wc, int fr, int fq) const {
;     ...
;                 for (int bj = 0; bj < 2; ++bj) {
;                     f32x4 r0, r1;
;                     if (RB) { const u32x4 rw = *(const u32x4*)((const bf16_t*)resid + ro + bj * HALF);
;                         r0 = (f32x4){bf_lo(rw.x), bf_hi(rw.x), bf_lo(rw.y), bf_hi(rw.y)}; r1 = (f32x4){bf_lo(rw.z), bf_hi(rw.z), bf_lo(rw.w), bf_hi(rw.w)}; }
;                     else { r0 = *(const f32x4*)((const float*)resid + ro + bj * HALF); r1 = *(const f32x4*)((const float*)resid + ro + bj * HALF + 4); }
;                     const f32x4 v0 = r0 + gv[bj][0] * acc[ai][bj][m][0], v1 = r1 + gv[bj][1] * acc[ai][bj][m][1];
;                     if (OB) { u32x4 w; w.x = pk2(v0[0], v0[1]); w.y = pk2(v0[2], v0[3]); w.z = pk2(v1[0], v1[1]); w.w = pk2(v1[2], v1[3]); *(u32x4*)((bf16_t*)out + ro + bj * HALF) = w; }
;                     else { *(f32x4*)((float*)out + ro + bj * HALF) = v0; *(f32x4*)((float*)out + ro + bj * HALF + 4) = v1; }
; template <class Epi>
; __device__ __forceinline__ void gemm_phase(LAS unsigned char* lds, const Gemm g, const StaticOrder& S, const Epi& E, const int tid) {
;     ...
;         E(acc, cur, wr, wc, fr, fq);
;         if (!has_next) break;
; #pragma unroll
;         for (int a = 0; a < 2; ++a)
; #pragma unroll
;             for (int b = 0; b < 2; ++b)
; #pragma unroll
;                 for (int m = 0; m < 4; ++m)
; #pragma unroll
;                     for (int n = 0; n < 2; ++n) acc[a][b][m][n] = (f32x4){0.f, 0.f, 0.f, 0.f};
;         cur = nxt; cA = nA; cB = nB; ++ui;
;     }
;     PG8_WAIT_V(0);
;     if (wr == 0) PG8_BAR;
	v_lshlrev_b32_e32 v176, 16, v226
	v_and_b32_e32 v177, 0xffff0000, v226
	v_lshlrev_b32_e32 v178, 16, v227
	v_and_b32_e32 v179, 0xffff0000, v227
	v_lshlrev_b32_e32 v180, 16, v228
	v_and_b32_e32 v181, 0xffff0000, v228
	v_lshlrev_b32_e32 v182, 16, v229
	v_and_b32_e32 v183, 0xffff0000, v229
	v_pk_fma_f32 v[78:79], v[78:79], v[62:63], v[176:177]
	v_pk_fma_f32 v[80:81], v[80:81], v[64:65], v[178:179]
	v_pk_fma_f32 v[74:75], v[74:75], v[58:59], v[180:181]
	v_pk_fma_f32 v[76:77], v[76:77], v[60:61], v[182:183]
	s_add_u32 s94, s94, 0x50000
	s_addc_u32 s95, s95, 0
	v_cvt_pk_bf16_f32 v78, v78, v79
	v_cvt_pk_bf16_f32 v79, v80, v81
	v_cvt_pk_bf16_f32 v80, v74, v75
	v_cvt_pk_bf16_f32 v81, v76, v77
	global_store_dwordx4 v170, v[78:81], s[94:95]
	s_waitcnt vmcnt(15)
	v_lshlrev_b32_e32 v176, 16, v230
	v_and_b32_e32 v177, 0xffff0000, v230
	v_lshlrev_b32_e32 v178, 16, v231
	v_and_b32_e32 v179, 0xffff0000, v231
	v_lshlrev_b32_e32 v180, 16, v232
	v_and_b32_e32 v181, 0xffff0000, v232
	v_lshlrev_b32_e32 v182, 16, v233
	v_and_b32_e32 v183, 0xffff0000, v233
	v_pk_fma_f32 v[70:71], v[70:71], v[46:47], v[176:177]
	v_pk_fma_f32 v[72:73], v[72:73], v[48:49], v[178:179]
	v_pk_fma_f32 v[66:67], v[66:67], v[42:43], v[180:181]
	v_pk_fma_f32 v[68:69], v[68:69], v[44:45], v[182:183]
	v_cvt_pk_bf16_f32 v70, v70, v71
	v_cvt_pk_bf16_f32 v71, v72, v73
	v_cvt_pk_bf16_f32 v72, v66, v67
	v_cvt_pk_bf16_f32 v73, v68, v69
	global_store_dwordx4 v170, v[70:73], s[94:95] offset:256
	s_waitcnt vmcnt(15)
	v_lshlrev_b32_e32 v176, 16, v234
	v_and_b32_e32 v177, 0xffff0000, v234
	v_lshlrev_b32_e32 v178, 16, v235
	v_and_b32_e32 v179, 0xffff0000, v235
	v_lshlrev_b32_e32 v180, 16, v236
	v_and_b32_e32 v181, 0xffff0000, v236
	v_lshlrev_b32_e32 v182, 16, v237
	v_and_b32_e32 v183, 0xffff0000, v237
	v_pk_fma_f32 v[54:55], v[54:55], v[62:63], v[176:177]
	v_pk_fma_f32 v[56:57], v[56:57], v[64:65], v[178:179]
	v_pk_fma_f32 v[50:51], v[50:51], v[58:59], v[180:181]
	v_pk_fma_f32 v[52:53], v[52:53], v[60:61], v[182:183]
	s_add_u32 s94, s94, 0x10000
	s_addc_u32 s95, s95, 0
	v_cvt_pk_bf16_f32 v54, v54, v55
	v_cvt_pk_bf16_f32 v55, v56, v57
	v_cvt_pk_bf16_f32 v56, v50, v51
	v_cvt_pk_bf16_f32 v57, v52, v53
	global_store_dwordx4 v170, v[54:57], s[94:95]
	s_waitcnt vmcnt(15)
	v_lshlrev_b32_e32 v176, 16, v184
	v_and_b32_e32 v177, 0xffff0000, v184
	v_lshlrev_b32_e32 v178, 16, v185
	v_and_b32_e32 v179, 0xffff0000, v185
	v_lshlrev_b32_e32 v180, 16, v186
	v_and_b32_e32 v181, 0xffff0000, v186
	v_lshlrev_b32_e32 v182, 16, v187
	v_and_b32_e32 v183, 0xffff0000, v187
	v_pk_fma_f32 v[38:39], v[38:39], v[46:47], v[176:177]
	v_pk_fma_f32 v[40:41], v[40:41], v[48:49], v[178:179]
	v_pk_fma_f32 v[34:35], v[34:35], v[42:43], v[180:181]
	v_pk_fma_f32 v[36:37], v[36:37], v[44:45], v[182:183]
	v_cvt_pk_bf16_f32 v38, v38, v39
	v_cvt_pk_bf16_f32 v39, v40, v41
	v_cvt_pk_bf16_f32 v40, v34, v35
	v_cvt_pk_bf16_f32 v41, v36, v37
	global_store_dwordx4 v170, v[38:41], s[94:95] offset:256
	s_waitcnt vmcnt(14)
	v_lshlrev_b32_e32 v176, 16, v188
	v_and_b32_e32 v177, 0xffff0000, v188
	v_lshlrev_b32_e32 v178, 16, v189
	v_and_b32_e32 v179, 0xffff0000, v189
	v_lshlrev_b32_e32 v180, 16, v190
	v_and_b32_e32 v181, 0xffff0000, v190
	v_lshlrev_b32_e32 v182, 16, v191
	v_and_b32_e32 v183, 0xffff0000, v191
	v_pk_fma_f32 v[30:31], v[30:31], v[62:63], v[176:177]
	v_pk_fma_f32 v[32:33], v[32:33], v[64:65], v[178:179]
	v_pk_fma_f32 v[26:27], v[26:27], v[58:59], v[180:181]
	v_pk_fma_f32 v[28:29], v[28:29], v[60:61], v[182:183]
	s_add_u32 s94, s94, 0x10000
	s_addc_u32 s95, s95, 0
	v_cvt_pk_bf16_f32 v30, v30, v31
	v_cvt_pk_bf16_f32 v31, v32, v33
	v_cvt_pk_bf16_f32 v32, v26, v27
	v_cvt_pk_bf16_f32 v33, v28, v29
	global_store_dwordx4 v170, v[30:33], s[94:95]
	s_waitcnt vmcnt(13)
	v_lshlrev_b32_e32 v176, 16, v192
	v_and_b32_e32 v177, 0xffff0000, v192
	v_lshlrev_b32_e32 v178, 16, v193
	v_and_b32_e32 v179, 0xffff0000, v193
	v_lshlrev_b32_e32 v180, 16, v194
	v_and_b32_e32 v181, 0xffff0000, v194
	v_lshlrev_b32_e32 v182, 16, v195
	v_and_b32_e32 v183, 0xffff0000, v195
	v_pk_fma_f32 v[22:23], v[22:23], v[46:47], v[176:177]
	v_pk_fma_f32 v[24:25], v[24:25], v[48:49], v[178:179]
	v_pk_fma_f32 v[18:19], v[18:19], v[42:43], v[180:181]
	v_pk_fma_f32 v[20:21], v[20:21], v[44:45], v[182:183]
	v_cvt_pk_bf16_f32 v22, v22, v23
	v_cvt_pk_bf16_f32 v23, v24, v25
	v_cvt_pk_bf16_f32 v24, v18, v19
	v_cvt_pk_bf16_f32 v25, v20, v21
	global_store_dwordx4 v170, v[22:25], s[94:95] offset:256
	s_waitcnt vmcnt(12)
	v_lshlrev_b32_e32 v176, 16, v196
	v_and_b32_e32 v177, 0xffff0000, v196
	v_lshlrev_b32_e32 v178, 16, v197
	v_and_b32_e32 v179, 0xffff0000, v197
	v_lshlrev_b32_e32 v180, 16, v198
	v_and_b32_e32 v181, 0xffff0000, v198
	v_lshlrev_b32_e32 v182, 16, v199
	v_and_b32_e32 v183, 0xffff0000, v199
	v_pk_fma_f32 v[14:15], v[14:15], v[62:63], v[176:177]
	v_pk_fma_f32 v[16:17], v[16:17], v[64:65], v[178:179]
	v_pk_fma_f32 v[10:11], v[10:11], v[58:59], v[180:181]
	v_pk_fma_f32 v[12:13], v[12:13], v[60:61], v[182:183]
	s_add_u32 s94, s94, 0x10000
	s_addc_u32 s95, s95, 0
	v_cvt_pk_bf16_f32 v14, v14, v15
	v_cvt_pk_bf16_f32 v15, v16, v17
	v_cvt_pk_bf16_f32 v16, v10, v11
	v_cvt_pk_bf16_f32 v17, v12, v13
	global_store_dwordx4 v170, v[14:17], s[94:95]
	s_waitcnt vmcnt(11)
	v_lshlrev_b32_e32 v176, 16, v210
	v_and_b32_e32 v177, 0xffff0000, v210
	v_lshlrev_b32_e32 v178, 16, v211
	v_and_b32_e32 v179, 0xffff0000, v211
	v_lshlrev_b32_e32 v180, 16, v212
	v_and_b32_e32 v181, 0xffff0000, v212
	v_lshlrev_b32_e32 v182, 16, v213
	v_and_b32_e32 v183, 0xffff0000, v213
	v_pk_fma_f32 v[6:7], v[6:7], v[46:47], v[176:177]
	v_pk_fma_f32 v[8:9], v[8:9], v[48:49], v[178:179]
	v_pk_fma_f32 v[2:3], v[2:3], v[42:43], v[180:181]
	v_pk_fma_f32 v[4:5], v[4:5], v[44:45], v[182:183]
	v_cvt_pk_bf16_f32 v6, v6, v7
	v_cvt_pk_bf16_f32 v7, v8, v9
	v_cvt_pk_bf16_f32 v8, v2, v3
	v_cvt_pk_bf16_f32 v9, v4, v5
	global_store_dwordx4 v170, v[6:9], s[94:95] offset:256
	s_mov_b32 s2, s12
	s_mov_b64 s[20:21], s[14:15]
	s_mov_b64 s[18:19], s[16:17]
	s_and_b64 vcc, exec, s[4:5]
	s_nop 1
	s_cbranch_vccz .LBB0_112
	s_waitcnt vmcnt(0)
	s_cmpk_gt_u32 s29, 0xff
	s_cbranch_scc1 .LBB0_123
	s_barrier

; #define PG8_STAGE(bufoff, gbase, voff) do { _Pragma("unroll") for (int _i = 0; _i < 2; ++_i) \
;         __builtin_amdgcn_global_load_lds((const unsigned*)((const char*)(gbase) + (voff)[_i]), (LAS unsigned*)(lds + (bufoff) + ldsw + _i * 8192), 16, 0, 0); } while (0)
; #define PG8_LDA(dst, b, h) do { _Pragma("unroll") for (int m = 0; m < 4; ++m) _Pragma("unroll") for (int k = 0; k < 2; ++k) dst[m][k] = *(const LAS bf16x8*)(lds + PG8_SA(b, h) + aoff + m * 2048 + k * 1024); } while (0)
; #define PG8_LDB(dst, b, h) do { _Pragma("unroll") for (int n = 0; n < 2; ++n) _Pragma("unroll") for (int k = 0; k < 2; ++k) dst[n][k] = *(const LAS bf16x8*)(lds + PG8_SB(b, h) + boff + n * 2048 + k * 1024); } while (0)
; #define PG8_MMA(ai, bj, At, Bt) do { __builtin_amdgcn_s_setprio(1); _Pragma("unroll") for (int m = 0; m < 4; ++m) _Pragma("unroll") for (int n = 0; n < 2; ++n) _Pragma("unroll") for (int k = 0; k < 2; ++k) \
;         acc[ai][bj][m][n] = __builtin_amdgcn_mfma_f32_16x16x32_bf16(Bt[n][k], At[m][k], acc[ai][bj][m][n], 0, 0, 0); __builtin_amdgcn_s_setprio(0); } while (0)
; #define PG8_WAIT_V(n) asm volatile("s_waitcnt vmcnt(" #n ")" ::: "memory")
; #define PG8_WAIT_L(n) asm volatile("s_waitcnt lgkmcnt(" #n ")" ::: "memory")
; #define PG8_BAR __builtin_amdgcn_s_barrier()
; template <class Epi>
; __device__ __forceinline__ void gemm_phase(LAS unsigned char* lds, const Gemm g, const StaticOrder& S, const Epi& E, const int tid) {
;     ...
;             const bool last = (t == nt - 2);
;             const char* a1 = cA + (size_t)(t + 1) * kstep;
;             const char* a2 = last ? nA : cA + (size_t)(t + 2) * kstep; const char* b2 = last ? nB : cB + (size_t)(t + 2) * kstep;
;             const char* a3 = a2 + kstep; const char* b3 = b2 + kstep;
;             PG8_LDB(B0, 0, 0); PG8_SCHED; PG8_LDA(At, 0, 0); PG8_STAGE(PG8_SA(1, 1), a1 + hstep, voffA);
;             PG8_WAIT_L(8); PG8_BAR; PG8_WAIT_L(0); PG8_MMA(0, 0, At, B0); PG8_BAR; PG8_SCHED;
;             PG8_LDB(B1, 0, 1); PG8_STAGE(PG8_SB(0, 0), b2, voffB);
;             PG8_BAR; PG8_WAIT_L(0); PG8_MMA(0, 1, At, B1); PG8_BAR;
;             PG8_LDA(At, 0, 1); PG8_STAGE(PG8_SA(0, 0), a2, voffA);
;             PG8_BAR; PG8_WAIT_L(0); PG8_MMA(1, 0, At, B0); PG8_BAR; PG8_SCHED;
;             PG8_STAGE(PG8_SB(0, 1), b2 + hstep, voffB);
;             PG8_WAIT_V(6); PG8_BAR; PG8_MMA(1, 1, At, B1); PG8_BAR;
.Lgprio4:
.LBB0_141:
	s_add_u32 s20, s18, 0xfff80080
	s_addc_u32 s21, s19, -1
	s_add_i32 s50, 0, 0x10000
	v_add_u32_e32 v86, s50, v173
	ds_read_b128 v[66:69], v86
	ds_read_b128 v[70:73], v86 offset:1024
	ds_read_b128 v[82:85], v86 offset:2048
	ds_read_b128 v[86:89], v86 offset:3072
	s_cmp_eq_u32 s49, 28
	s_cselect_b32 s23, s13, s21
	s_cselect_b32 s22, s44, s20
	s_cselect_b32 s21, s11, s48
	s_cselect_b32 s20, s45, s47
	s_add_i32 m0, s3, 0xc000
	ds_read_b128 v[176:179], v174
	ds_read_b128 v[180:183], v174 offset:1024
	ds_read_b128 v[184:187], v174 offset:2048
	ds_read_b128 v[188:191], v174 offset:3072
	ds_read_b128 v[192:195], v174 offset:4096
	ds_read_b128 v[196:199], v174 offset:5120
	ds_read_b128 v[210:213], v174 offset:6144
	ds_read_b128 v[214:217], v174 offset:7168
	global_load_lds_dwordx4 v168, s[18:19]
	v_lshl_add_u64 v[170:171], s[18:19], 0, v[166:167]
	s_add_i32 m0, s3, 0xe000
	s_nop 0
	global_load_lds_dwordx4 v[170:171], off
	s_waitcnt lgkmcnt(8)
	s_barrier
	s_waitcnt lgkmcnt(0)
	v_mfma_f32_16x16x32_bf16 v[142:145], v[66:69], v[176:179], v[142:145]
	v_mfma_f32_16x16x32_bf16 v[138:141], v[82:85], v[176:179], v[138:141]
	v_mfma_f32_16x16x32_bf16 v[126:129], v[66:69], v[184:187], v[126:129]
	v_mfma_f32_16x16x32_bf16 v[122:125], v[82:85], v[184:187], v[122:125]
	v_mfma_f32_16x16x32_bf16 v[110:113], v[66:69], v[192:195], v[110:113]
	v_mfma_f32_16x16x32_bf16 v[106:109], v[82:85], v[192:195], v[106:109]
	v_mfma_f32_16x16x32_bf16 v[94:97], v[66:69], v[210:213], v[94:97]
	v_mfma_f32_16x16x32_bf16 v[90:93], v[82:85], v[210:213], v[90:93]
	v_mfma_f32_16x16x32_bf16 v[142:145], v[70:73], v[180:183], v[142:145]
	v_mfma_f32_16x16x32_bf16 v[138:141], v[86:89], v[180:183], v[138:141]
	v_mfma_f32_16x16x32_bf16 v[126:129], v[70:73], v[188:191], v[126:129]
	v_mfma_f32_16x16x32_bf16 v[122:125], v[86:89], v[188:191], v[122:125]
	v_mfma_f32_16x16x32_bf16 v[110:113], v[70:73], v[196:199], v[110:113]
	v_mfma_f32_16x16x32_bf16 v[106:109], v[86:89], v[196:199], v[106:109]
	v_mfma_f32_16x16x32_bf16 v[94:97], v[70:73], v[214:217], v[94:97]
	v_mfma_f32_16x16x32_bf16 v[90:93], v[86:89], v[214:217], v[90:93]
	s_barrier
	s_add_i32 s54, 0, 0x14000
	v_add_u32_e32 v170, s54, v173
	s_add_i32 s50, s50, s31
	ds_read_b128 v[218:221], v170
	ds_read_b128 v[222:225], v170 offset:1024
	ds_read_b128 v[226:229], v170 offset:2048
	ds_read_b128 v[230:233], v170 offset:3072
	v_lshl_add_u64 v[170:171], s[20:21], 0, v[0:1]
	s_mov_b32 m0, s50
	v_lshl_add_u64 v[200:201], s[20:21], 0, v[164:165]
	global_load_lds_dwordx4 v[170:171], off
	s_add_i32 m0, s50, 0x2000
	s_nop 0
	global_load_lds_dwordx4 v[200:201], off
	s_barrier
	s_waitcnt lgkmcnt(0)
	v_mfma_f32_16x16x32_bf16 v[134:137], v[218:221], v[176:179], v[134:137]
	v_mfma_f32_16x16x32_bf16 v[130:133], v[226:229], v[176:179], v[130:133]
	v_mfma_f32_16x16x32_bf16 v[118:121], v[218:221], v[184:187], v[118:121]
	v_mfma_f32_16x16x32_bf16 v[114:117], v[226:229], v[184:187], v[114:117]
	v_mfma_f32_16x16x32_bf16 v[102:105], v[218:221], v[192:195], v[102:105]
	v_mfma_f32_16x16x32_bf16 v[98:101], v[226:229], v[192:195], v[98:101]
	v_mfma_f32_16x16x32_bf16 v[78:81], v[218:221], v[210:213], v[78:81]
	v_mfma_f32_16x16x32_bf16 v[74:77], v[226:229], v[210:213], v[74:77]
	v_mfma_f32_16x16x32_bf16 v[134:137], v[222:225], v[180:183], v[134:137]
	v_mfma_f32_16x16x32_bf16 v[130:133], v[230:233], v[180:183], v[130:133]
	v_mfma_f32_16x16x32_bf16 v[118:121], v[222:225], v[188:191], v[118:121]
	v_mfma_f32_16x16x32_bf16 v[114:117], v[230:233], v[188:191], v[114:117]
	v_mfma_f32_16x16x32_bf16 v[102:105], v[222:225], v[196:199], v[102:105]
	v_mfma_f32_16x16x32_bf16 v[98:101], v[230:233], v[196:199], v[98:101]
	v_mfma_f32_16x16x32_bf16 v[78:81], v[222:225], v[214:217], v[78:81]
	v_mfma_f32_16x16x32_bf16 v[74:77], v[230:233], v[214:217], v[74:77]
	s_mov_b32 m0, s3
	v_lshl_add_u64 v[234:235], s[22:23], 0, v[160:161]
	s_barrier
	ds_read_b128 v[176:179], v174 offset:16384
	ds_read_b128 v[180:183], v174 offset:17408
	ds_read_b128 v[184:187], v174 offset:18432
	ds_read_b128 v[188:191], v174 offset:19456
	ds_read_b128 v[192:195], v174 offset:20480
	ds_read_b128 v[196:199], v174 offset:21504
	ds_read_b128 v[210:213], v174 offset:22528
	ds_read_b128 v[214:217], v174 offset:23552
	global_load_lds_dwordx4 v[234:235], off
	v_lshl_add_u64 v[236:237], s[22:23], 0, v[162:163]
	s_mov_b32 m0, s34
	s_nop 0
	global_load_lds_dwordx4 v[236:237], off
	s_barrier
	s_waitcnt lgkmcnt(0)
	v_mfma_f32_16x16x32_bf16 v[62:65], v[66:69], v[176:179], v[62:65]
	v_mfma_f32_16x16x32_bf16 v[58:61], v[82:85], v[176:179], v[58:61]
	v_mfma_f32_16x16x32_bf16 v[46:49], v[66:69], v[184:187], v[46:49]
	v_mfma_f32_16x16x32_bf16 v[42:45], v[82:85], v[184:187], v[42:45]
	v_mfma_f32_16x16x32_bf16 v[30:33], v[66:69], v[192:195], v[30:33]
	v_mfma_f32_16x16x32_bf16 v[26:29], v[82:85], v[192:195], v[26:29]
	v_mfma_f32_16x16x32_bf16 v[14:17], v[66:69], v[210:213], v[14:17]
	v_mfma_f32_16x16x32_bf16 v[10:13], v[82:85], v[210:213], v[10:13]
	v_mfma_f32_16x16x32_bf16 v[62:65], v[70:73], v[180:183], v[62:65]
	v_mfma_f32_16x16x32_bf16 v[58:61], v[86:89], v[180:183], v[58:61]
	v_mfma_f32_16x16x32_bf16 v[46:49], v[70:73], v[188:191], v[46:49]
	v_mfma_f32_16x16x32_bf16 v[42:45], v[86:89], v[188:191], v[42:45]
	v_mfma_f32_16x16x32_bf16 v[30:33], v[70:73], v[196:199], v[30:33]
	v_mfma_f32_16x16x32_bf16 v[26:29], v[86:89], v[196:199], v[26:29]
	v_mfma_f32_16x16x32_bf16 v[14:17], v[70:73], v[214:217], v[14:17]
	v_mfma_f32_16x16x32_bf16 v[10:13], v[86:89], v[214:217], v[10:13]
	s_barrier
	s_add_u32 s52, s20, 0x80000
	s_addc_u32 s53, s21, 0
	s_add_i32 s50, s54, s31
	s_mov_b32 m0, s50
	s_nop 0
	global_load_lds_dwordx4 v0, s[52:53]
	s_add_i32 m0, s50, 0x2000
	s_nop 0
	global_load_lds_dwordx4 v164, s[52:53]
	s_waitcnt vmcnt(6)
	s_barrier
; #define PG8_STAGE(bufoff, gbase, voff) do { _Pragma("unroll") for (int _i = 0; _i < 2; ++_i) \
;         __builtin_amdgcn_global_load_lds((const unsigned*)((const char*)(gbase) + (voff)[_i]), (LAS unsigned*)(lds + (bufoff) + ldsw + _i * 8192), 16, 0, 0); } while (0)
; #define PG8_LDA(dst, b, h) do { _Pragma("unroll") for (int m = 0; m < 4; ++m) _Pragma("unroll") for (int k = 0; k < 2; ++k) dst[m][k] = *(const LAS bf16x8*)(lds + PG8_SA(b, h) + aoff + m * 2048 + k * 1024); } while (0)
; #define PG8_LDB(dst, b, h) do { _Pragma("unroll") for (int n = 0; n < 2; ++n) _Pragma("unroll") for (int k = 0; k < 2; ++k) dst[n][k] = *(const LAS bf16x8*)(lds + PG8_SB(b, h) + boff + n * 2048 + k * 1024); } while (0)
; #define PG8_MMA(ai, bj, At, Bt) do { __builtin_amdgcn_s_setprio(1); _Pragma("unroll") for (int m = 0; m < 4; ++m) _Pragma("unroll") for (int n = 0; n < 2; ++n) _Pragma("unroll") for (int k = 0; k < 2; ++k) \
;         acc[ai][bj][m][n] = __builtin_amdgcn_mfma_f32_16x16x32_bf16(Bt[n][k], At[m][k], acc[ai][bj][m][n], 0, 0, 0); __builtin_amdgcn_s_setprio(0); } while (0)
; #define PG8_WAIT_V(n) asm volatile("s_waitcnt vmcnt(" #n ")" ::: "memory")
; #define PG8_WAIT_L(n) asm volatile("s_waitcnt lgkmcnt(" #n ")" ::: "memory")
; #define PG8_BAR __builtin_amdgcn_s_barrier()
; #define PG8_SCHED __builtin_amdgcn_sched_barrier(0)
; template <class Epi>
; __device__ __forceinline__ void gemm_phase(LAS unsigned char* lds, const Gemm g, const StaticOrder& S, const Epi& E, const int tid) {
;     ...
;             PG8_WAIT_V(6); PG8_BAR; PG8_MMA(1, 1, At, B1); PG8_BAR;
;             PG8_LDB(B0, 1, 0); PG8_SCHED; PG8_LDA(At, 1, 0); PG8_STAGE(PG8_SA(0, 1), a2 + hstep, voffA);
;             PG8_WAIT_L(8); PG8_BAR; PG8_WAIT_L(0); PG8_MMA(0, 0, At, B0); PG8_BAR; PG8_SCHED;
;             PG8_LDB(B1, 1, 1); PG8_STAGE(PG8_SB(1, 0), b3, voffB);
;             PG8_BAR; PG8_WAIT_L(0); PG8_MMA(0, 1, At, B1); PG8_BAR;
;             PG8_LDA(At, 1, 1); PG8_STAGE(PG8_SA(1, 0), a3, voffA);
	v_mfma_f32_16x16x32_bf16 v[54:57], v[218:221], v[176:179], v[54:57]
	v_mfma_f32_16x16x32_bf16 v[50:53], v[226:229], v[176:179], v[50:53]
	v_mfma_f32_16x16x32_bf16 v[38:41], v[218:221], v[184:187], v[38:41]
	v_mfma_f32_16x16x32_bf16 v[34:37], v[226:229], v[184:187], v[34:37]
	v_mfma_f32_16x16x32_bf16 v[22:25], v[218:221], v[192:195], v[22:25]
	v_mfma_f32_16x16x32_bf16 v[18:21], v[226:229], v[192:195], v[18:21]
	v_mfma_f32_16x16x32_bf16 v[6:9], v[218:221], v[210:213], v[6:9]
	v_mfma_f32_16x16x32_bf16 v[2:5], v[226:229], v[210:213], v[2:5]
	v_mfma_f32_16x16x32_bf16 v[54:57], v[222:225], v[180:183], v[54:57]
	v_mfma_f32_16x16x32_bf16 v[50:53], v[230:233], v[180:183], v[50:53]
	v_mfma_f32_16x16x32_bf16 v[38:41], v[222:225], v[188:191], v[38:41]
	v_mfma_f32_16x16x32_bf16 v[34:37], v[230:233], v[188:191], v[34:37]
	v_mfma_f32_16x16x32_bf16 v[22:25], v[222:225], v[196:199], v[22:25]
	v_mfma_f32_16x16x32_bf16 v[18:21], v[230:233], v[196:199], v[18:21]
	v_mfma_f32_16x16x32_bf16 v[6:9], v[222:225], v[214:217], v[6:9]
	v_mfma_f32_16x16x32_bf16 v[2:5], v[230:233], v[214:217], v[2:5]
	s_add_i32 s50, 0, 0x18000
	v_add_u32_e32 v86, s50, v173
	s_barrier
	ds_read_b128 v[66:69], v86
	ds_read_b128 v[70:73], v86 offset:1024
	ds_read_b128 v[82:85], v86 offset:2048
	ds_read_b128 v[86:89], v86 offset:3072
	s_add_u32 s22, s22, 0x80000
	s_addc_u32 s23, s23, 0
	s_mov_b32 m0, s35
	ds_read_b128 v[176:179], v174 offset:32768
	ds_read_b128 v[180:183], v174 offset:33792
	ds_read_b128 v[184:187], v174 offset:34816
	ds_read_b128 v[188:191], v174 offset:35840
	ds_read_b128 v[192:195], v174 offset:36864
	ds_read_b128 v[196:199], v174 offset:37888
	ds_read_b128 v[210:213], v174 offset:38912
	ds_read_b128 v[214:217], v174 offset:39936
	global_load_lds_dwordx4 v160, s[22:23]
	s_mov_b32 m0, s36
	s_nop 0
	global_load_lds_dwordx4 v162, s[22:23]
	s_waitcnt lgkmcnt(8)
	s_barrier
	s_waitcnt lgkmcnt(0)
	v_mfma_f32_16x16x32_bf16 v[142:145], v[66:69], v[176:179], v[142:145]
	v_mfma_f32_16x16x32_bf16 v[138:141], v[82:85], v[176:179], v[138:141]
	v_mfma_f32_16x16x32_bf16 v[126:129], v[66:69], v[184:187], v[126:129]
	v_mfma_f32_16x16x32_bf16 v[122:125], v[82:85], v[184:187], v[122:125]
	v_mfma_f32_16x16x32_bf16 v[110:113], v[66:69], v[192:195], v[110:113]
	v_mfma_f32_16x16x32_bf16 v[106:109], v[82:85], v[192:195], v[106:109]
	v_mfma_f32_16x16x32_bf16 v[94:97], v[66:69], v[210:213], v[94:97]
	v_mfma_f32_16x16x32_bf16 v[90:93], v[82:85], v[210:213], v[90:93]
	v_mfma_f32_16x16x32_bf16 v[142:145], v[70:73], v[180:183], v[142:145]
	v_mfma_f32_16x16x32_bf16 v[138:141], v[86:89], v[180:183], v[138:141]
	v_mfma_f32_16x16x32_bf16 v[126:129], v[70:73], v[188:191], v[126:129]
	v_mfma_f32_16x16x32_bf16 v[122:125], v[86:89], v[188:191], v[122:125]
	v_mfma_f32_16x16x32_bf16 v[110:113], v[70:73], v[196:199], v[110:113]
	v_mfma_f32_16x16x32_bf16 v[106:109], v[86:89], v[196:199], v[106:109]
	v_mfma_f32_16x16x32_bf16 v[94:97], v[70:73], v[214:217], v[94:97]
	v_mfma_f32_16x16x32_bf16 v[90:93], v[86:89], v[214:217], v[90:93]
	s_barrier
	s_add_i32 s22, 0, 0x1c000
	s_add_i32 s23, s50, s31
	v_add_u32_e32 v175, s22, v173
	v_lshl_add_u64 v[170:171], v[170:171], 0, s[56:57]
	s_mov_b32 m0, s23
	ds_read_b128 v[218:221], v175
	ds_read_b128 v[222:225], v175 offset:1024
	ds_read_b128 v[226:229], v175 offset:2048
	ds_read_b128 v[230:233], v175 offset:3072
	global_load_lds_dwordx4 v[170:171], off
	v_lshl_add_u64 v[170:171], v[200:201], 0, s[56:57]
	s_add_i32 m0, s23, 0x2000
	s_nop 0
	global_load_lds_dwordx4 v[170:171], off
	s_barrier
	s_waitcnt lgkmcnt(0)
	v_mfma_f32_16x16x32_bf16 v[134:137], v[218:221], v[176:179], v[134:137]
	v_mfma_f32_16x16x32_bf16 v[130:133], v[226:229], v[176:179], v[130:133]
	v_mfma_f32_16x16x32_bf16 v[118:121], v[218:221], v[184:187], v[118:121]
	v_mfma_f32_16x16x32_bf16 v[114:117], v[226:229], v[184:187], v[114:117]
	v_mfma_f32_16x16x32_bf16 v[102:105], v[218:221], v[192:195], v[102:105]
	v_mfma_f32_16x16x32_bf16 v[98:101], v[226:229], v[192:195], v[98:101]
	v_mfma_f32_16x16x32_bf16 v[78:81], v[218:221], v[210:213], v[78:81]
	v_mfma_f32_16x16x32_bf16 v[74:77], v[226:229], v[210:213], v[74:77]
	v_mfma_f32_16x16x32_bf16 v[134:137], v[222:225], v[180:183], v[134:137]
	v_mfma_f32_16x16x32_bf16 v[130:133], v[230:233], v[180:183], v[130:133]
	v_mfma_f32_16x16x32_bf16 v[118:121], v[222:225], v[188:191], v[118:121]
	v_mfma_f32_16x16x32_bf16 v[114:117], v[230:233], v[188:191], v[114:117]
	v_mfma_f32_16x16x32_bf16 v[102:105], v[222:225], v[196:199], v[102:105]
	v_mfma_f32_16x16x32_bf16 v[98:101], v[230:233], v[196:199], v[98:101]
	v_mfma_f32_16x16x32_bf16 v[78:81], v[222:225], v[214:217], v[78:81]
	v_mfma_f32_16x16x32_bf16 v[74:77], v[230:233], v[214:217], v[74:77]
	s_mov_b32 m0, s39
	v_lshl_add_u64 v[170:171], v[234:235], 0, s[56:57]
	s_barrier
	ds_read_b128 v[176:179], v174 offset:49152
	ds_read_b128 v[180:183], v174 offset:50176
	ds_read_b128 v[184:187], v174 offset:51200
	ds_read_b128 v[188:191], v174 offset:52224
	ds_read_b128 v[192:195], v174 offset:53248
	ds_read_b128 v[196:199], v174 offset:54272
	ds_read_b128 v[210:213], v174 offset:55296
	ds_read_b128 v[214:217], v174 offset:56320
	global_load_lds_dwordx4 v[170:171], off
	v_lshl_add_u64 v[170:171], v[236:237], 0, s[56:57]
	s_mov_b32 m0, s40
	s_nop 0
	global_load_lds_dwordx4 v[170:171], off
	s_barrier
; __device__ __forceinline__ unsigned pk2(float lo, float hi) { f32x2 v = {lo, hi}; return __builtin_bit_cast(unsigned, __builtin_convertvector(v, bf16x2_t)); }
; __device__ __forceinline__ float bf_lo(unsigned w) { return __uint_as_float(w << 16); }
;     __device__ __forceinline__ void operator()(const f32x4 (&acc)[2][2][4][2], const Unit& u, int wr, int wc, int fr, int fq) const {
;         asm volatile("" : "+v"(fr), "+v"(fq));
;         const int row0 = u.pm * BM + wr * 64 + fr, col0 = u.pn * BM + wc * 32 + 8 * fq;
;         const float* gp = gate + (size_t)(u.pm >> 5) * 12288 + col0;
;         f32x4 gv[2][2];
; #pragma unroll
;         for (int bj = 0; bj < 2; ++bj)
; #pragma unroll
;             for (int n = 0; n < 2; ++n) gv[bj][n] = *(const f32x4*)(gp + bj * HALF + 4 * n);
; #pragma unroll
;         for (int ai = 0; ai < 2; ++ai)
; #pragma unroll
;             for (int m = 0; m < 4; ++m) {
;                 const size_t ro = (size_t)(row0 + ai * HALF + m * 16) * DM + col0;
; #pragma unroll
;                 for (int bj = 0; bj < 2; ++bj) {
;                     f32x4 r0, r1;
;                     if (RB) { const u32x4 rw = *(const u32x4*)((const bf16_t*)resid + ro + bj * HALF);
;                         r0 = (f32x4){bf_lo(rw.x), bf_hi(rw.x), bf_lo(rw.y), bf_hi(rw.y)}; r1 = (f32x4){bf_lo(rw.z), bf_hi(rw.z), bf_lo(rw.w), bf_hi(rw.w)}; }
;                     else { r0 = *(const f32x4*)((const float*)resid + ro + bj * HALF); r1 = *(const f32x4*)((const float*)resid + ro + bj * HALF + 4); }
;                     const f32x4 v0 = r0 + gv[bj][0] * acc[ai][bj][m][0], v1 = r1 + gv[bj][1] * acc[ai][bj][m][1];
;                     if (OB) { u32x4 w; w.x = pk2(v0[0], v0[1]); w.y = pk2(v0[2], v0[3]); w.z = pk2(v1[0], v1[1]); w.w = pk2(v1[2], v1[3]); *(u32x4*)((bf16_t*)out + ro + bj * HALF) = w; }
;                     else { *(f32x4*)((float*)out + ro + bj * HALF) = v0; *(f32x4*)((float*)out + ro + bj * HALF + 4) = v1; }
; template <class Epi>
; __device__ __forceinline__ void gemm_phase(LAS unsigned char* lds, const Gemm g, const StaticOrder& S, const Epi& E, const int tid) {
;     ...
;             PG8_BAR; PG8_WAIT_L(0); PG8_MMA(1, 0, At, B0); PG8_BAR; PG8_SCHED;
;             PG8_STAGE(PG8_SB(1, 1), b3 + hstep, voffB);
;             PG8_WAIT_V(6); PG8_BAR; PG8_MMA(1, 1, At, B1); PG8_BAR;
;         }
;         E(acc, cur, wr, wc, fr, fq);
	s_waitcnt lgkmcnt(0)
	v_mfma_f32_16x16x32_bf16 v[62:65], v[66:69], v[176:179], v[62:65]
	v_mfma_f32_16x16x32_bf16 v[58:61], v[82:85], v[176:179], v[58:61]
	v_mfma_f32_16x16x32_bf16 v[46:49], v[66:69], v[184:187], v[46:49]
	v_mfma_f32_16x16x32_bf16 v[42:45], v[82:85], v[184:187], v[42:45]
	v_mfma_f32_16x16x32_bf16 v[30:33], v[66:69], v[192:195], v[30:33]
	v_mfma_f32_16x16x32_bf16 v[26:29], v[82:85], v[192:195], v[26:29]
	v_mfma_f32_16x16x32_bf16 v[14:17], v[66:69], v[210:213], v[14:17]
	v_mfma_f32_16x16x32_bf16 v[10:13], v[82:85], v[210:213], v[10:13]
	v_mfma_f32_16x16x32_bf16 v[62:65], v[70:73], v[180:183], v[62:65]
	v_mfma_f32_16x16x32_bf16 v[58:61], v[86:89], v[180:183], v[58:61]
	v_mfma_f32_16x16x32_bf16 v[46:49], v[70:73], v[188:191], v[46:49]
	v_mfma_f32_16x16x32_bf16 v[42:45], v[86:89], v[188:191], v[42:45]
	v_mfma_f32_16x16x32_bf16 v[30:33], v[70:73], v[196:199], v[30:33]
	v_mfma_f32_16x16x32_bf16 v[26:29], v[86:89], v[196:199], v[26:29]
	v_mfma_f32_16x16x32_bf16 v[14:17], v[70:73], v[214:217], v[14:17]
	v_mfma_f32_16x16x32_bf16 v[10:13], v[86:89], v[214:217], v[10:13]
	s_barrier
	s_add_u32 s20, s20, 0x80080
	s_addc_u32 s21, s21, 0
	s_add_i32 s22, s22, s31
	s_mov_b32 m0, s22
	s_nop 0
	global_load_lds_dwordx4 v0, s[20:21]
	s_add_i32 m0, s22, 0x2000
	s_nop 0
	global_load_lds_dwordx4 v164, s[20:21]
	s_waitcnt vmcnt(6)
	s_barrier
	v_mfma_f32_16x16x32_bf16 v[54:57], v[218:221], v[176:179], v[54:57]
	v_mfma_f32_16x16x32_bf16 v[50:53], v[226:229], v[176:179], v[50:53]
	v_mfma_f32_16x16x32_bf16 v[38:41], v[218:221], v[184:187], v[38:41]
	v_mfma_f32_16x16x32_bf16 v[34:37], v[226:229], v[184:187], v[34:37]
	v_mfma_f32_16x16x32_bf16 v[22:25], v[218:221], v[192:195], v[22:25]
	v_mfma_f32_16x16x32_bf16 v[18:21], v[226:229], v[192:195], v[18:21]
	v_mfma_f32_16x16x32_bf16 v[6:9], v[218:221], v[210:213], v[6:9]
	v_mfma_f32_16x16x32_bf16 v[2:5], v[226:229], v[210:213], v[2:5]
	v_mfma_f32_16x16x32_bf16 v[54:57], v[222:225], v[180:183], v[54:57]
	v_mfma_f32_16x16x32_bf16 v[50:53], v[230:233], v[180:183], v[50:53]
	v_mfma_f32_16x16x32_bf16 v[38:41], v[222:225], v[188:191], v[38:41]
	v_mfma_f32_16x16x32_bf16 v[34:37], v[230:233], v[188:191], v[34:37]
	v_mfma_f32_16x16x32_bf16 v[22:25], v[222:225], v[196:199], v[22:25]
	v_mfma_f32_16x16x32_bf16 v[18:21], v[230:233], v[196:199], v[18:21]
	v_mfma_f32_16x16x32_bf16 v[6:9], v[222:225], v[214:217], v[6:9]
	v_mfma_f32_16x16x32_bf16 v[2:5], v[230:233], v[214:217], v[2:5]
	s_add_i32 s49, s49, 2
	s_add_u32 s47, s47, 0x100
	s_addc_u32 s48, s48, 0
	s_add_u32 s18, s18, 0x100
	s_addc_u32 s19, s19, 0
	s_cmp_gt_u32 s49, 29
	s_barrier
	s_cbranch_scc0 .LBB0_141
	s_setprio 0
	s_lshl_b32 s11, s2, 8
	s_lshl_b32 s13, s43, 8
	v_mov_b32_e32 v66, v172
	v_mov_b32_e32 v175, v159
	s_add_i32 s11, s11, s37
	s_or_b32 s13, s13, s38
	s_ashr_i32 s2, s2, 5
	s_mov_b32 s43, s10
	v_lshl_add_u32 v170, v66, 3, s13
	s_mul_hi_i32 s13, s2, 0xc000
	s_mul_i32 s2, s2, 0xc000
	v_add_u32_e32 v176, s11, v175
	s_add_u32 s18, s27, s2
	v_ashrrev_i32_e32 v177, 31, v176
	s_addc_u32 s19, s28, s13
	v_ashrrev_i32_e32 v171, 31, v170
	v_lshlrev_b64 v[176:177], 11, v[176:177]
	v_lshl_add_u64 v[70:71], v[170:171], 2, s[18:19]
	v_lshl_add_u64 v[170:171], v[176:177], 0, v[170:171]
	v_lshl_add_u64 v[184:185], v[170:171], 2, s[8:9]
	global_load_dwordx4 v[82:85], v[70:71], off offset:16
	global_load_dwordx4 v[86:89], v[70:71], off
	global_load_dwordx4 v[66:69], v[70:71], off offset:528
	s_nop 0
	global_load_dwordx4 v[70:73], v[70:71], off offset:512
	v_lshlrev_b32_e32 v175, 2, v170
	v_lshlrev_b32_e32 v200, 1, v170
	s_mov_b64 s[92:93], s[8:9]
	s_mov_b64 s[94:95], s[6:7]
	global_load_dwordx4 v[176:179], v175, s[92:93]
	global_load_dwordx4 v[180:183], v175, s[92:93] offset:16
	global_load_dwordx4 v[184:187], v175, s[92:93] offset:512
	global_load_dwordx4 v[188:191], v175, s[92:93] offset:528
	s_add_u32 s92, s92, 0x20000
	s_addc_u32 s93, s93, 0
	global_load_dwordx4 v[192:195], v175, s[92:93]
	global_load_dwordx4 v[196:199], v175, s[92:93] offset:16
	global_load_dwordx4 v[210:213], v175, s[92:93] offset:512
	global_load_dwordx4 v[214:217], v175, s[92:93] offset:528
	s_add_u32 s92, s92, 0x20000
	s_addc_u32 s93, s93, 0
	global_load_dwordx4 v[218:221], v175, s[92:93]
	global_load_dwordx4 v[222:225], v175, s[92:93] offset:16
	global_load_dwordx4 v[226:229], v175, s[92:93] offset:512
	global_load_dwordx4 v[230:233], v175, s[92:93] offset:528
	s_waitcnt vmcnt(10)
	v_pk_fma_f32 v[142:143], v[142:143], v[86:87], v[176:177]
	v_pk_fma_f32 v[144:145], v[144:145], v[88:89], v[178:179]
	v_pk_fma_f32 v[138:139], v[138:139], v[82:83], v[180:181]
	v_pk_fma_f32 v[140:141], v[140:141], v[84:85], v[182:183]
	s_add_u32 s92, s92, 0x20000
	s_addc_u32 s93, s93, 0
	global_load_dwordx4 v[176:179], v175, s[92:93]
	global_load_dwordx4 v[180:183], v175, s[92:93] offset:16
	v_cvt_pk_bf16_f32 v142, v142, v143
	v_cvt_pk_bf16_f32 v143, v144, v145
	v_cvt_pk_bf16_f32 v144, v138, v139
	v_cvt_pk_bf16_f32 v145, v140, v141
	global_store_dwordx4 v200, v[142:145], s[94:95]
	s_waitcnt vmcnt(11)
	v_pk_fma_f32 v[134:135], v[134:135], v[70:71], v[184:185]
	v_pk_fma_f32 v[136:137], v[136:137], v[72:73], v[186:187]
	v_pk_fma_f32 v[130:131], v[130:131], v[66:67], v[188:189]
	v_pk_fma_f32 v[132:133], v[132:133], v[68:69], v[190:191]
	global_load_dwordx4 v[184:187], v175, s[92:93] offset:512
	global_load_dwordx4 v[188:191], v175, s[92:93] offset:528
	v_cvt_pk_bf16_f32 v134, v134, v135
	v_cvt_pk_bf16_f32 v135, v136, v137
	v_cvt_pk_bf16_f32 v136, v130, v131
	v_cvt_pk_bf16_f32 v137, v132, v133
	global_store_dwordx4 v200, v[134:137], s[94:95] offset:256
	s_waitcnt vmcnt(12)
; __device__ __forceinline__ unsigned pk2(float lo, float hi) { f32x2 v = {lo, hi}; return __builtin_bit_cast(unsigned, __builtin_convertvector(v, bf16x2_t)); }
; __device__ __forceinline__ float bf_lo(unsigned w) { return __uint_as_float(w << 16); }
; __device__ __forceinline__ float bf_hi(unsigned w) { return __uint_as_float(w & 0xffff0000u); }
;     __device__ __forceinline__ void operator()(const f32x4 (&acc)[2][2][4][2], const Unit& u, int wr, int wc, int fr, int fq) const {
;     ...
;         for (int ai = 0; ai < 2; ++ai)
; #pragma unroll
;             for (int m = 0; m < 4; ++m) {
;                 const size_t ro = (size_t)(row0 + ai * HALF + m * 16) * DM + col0;
; #pragma unroll
;                 for (int bj = 0; bj < 2; ++bj) {
;                     f32x4 r0, r1;
;                     if (RB) { const u32x4 rw = *(const u32x4*)((const bf16_t*)resid + ro + bj * HALF);
;                         r0 = (f32x4){bf_lo(rw.x), bf_hi(rw.x), bf_lo(rw.y), bf_hi(rw.y)}; r1 = (f32x4){bf_lo(rw.z), bf_hi(rw.z), bf_lo(rw.w), bf_hi(rw.w)}; }
;                     else { r0 = *(const f32x4*)((const float*)resid + ro + bj * HALF); r1 = *(const f32x4*)((const float*)resid + ro + bj * HALF + 4); }
;                     const f32x4 v0 = r0 + gv[bj][0] * acc[ai][bj][m][0], v1 = r1 + gv[bj][1] * acc[ai][bj][m][1];
;                     if (OB) { u32x4 w; w.x = pk2(v0[0], v0[1]); w.y = pk2(v0[2], v0[3]); w.z = pk2(v1[0], v1[1]); w.w = pk2(v1[2], v1[3]); *(u32x4*)((bf16_t*)out + ro + bj * HALF) = w; }
;                     else { *(f32x4*)((float*)out + ro + bj * HALF) = v0; *(f32x4*)((float*)out + ro + bj * HALF + 4) = v1; }
;                 }
	v_pk_fma_f32 v[126:127], v[126:127], v[86:87], v[192:193]
	v_pk_fma_f32 v[128:129], v[128:129], v[88:89], v[194:195]
	v_pk_fma_f32 v[122:123], v[122:123], v[82:83], v[196:197]
	v_pk_fma_f32 v[124:125], v[124:125], v[84:85], v[198:199]
	s_add_u32 s92, s92, 0xa0000
	s_addc_u32 s93, s93, 0
	global_load_dwordx4 v[192:195], v175, s[92:93]
	global_load_dwordx4 v[196:199], v175, s[92:93] offset:16
	s_add_u32 s94, s94, 0x10000
	s_addc_u32 s95, s95, 0
	v_cvt_pk_bf16_f32 v126, v126, v127
	v_cvt_pk_bf16_f32 v127, v128, v129
	v_cvt_pk_bf16_f32 v128, v122, v123
	v_cvt_pk_bf16_f32 v129, v124, v125
	global_store_dwordx4 v200, v[126:129], s[94:95]
	s_waitcnt vmcnt(13)
	v_pk_fma_f32 v[118:119], v[118:119], v[70:71], v[210:211]
	v_pk_fma_f32 v[120:121], v[120:121], v[72:73], v[212:213]
	v_pk_fma_f32 v[114:115], v[114:115], v[66:67], v[214:215]
	v_pk_fma_f32 v[116:117], v[116:117], v[68:69], v[216:217]
	global_load_dwordx4 v[210:213], v175, s[92:93] offset:512
	global_load_dwordx4 v[214:217], v175, s[92:93] offset:528
	v_cvt_pk_bf16_f32 v118, v118, v119
	v_cvt_pk_bf16_f32 v119, v120, v121
	v_cvt_pk_bf16_f32 v120, v114, v115
	v_cvt_pk_bf16_f32 v121, v116, v117
	global_store_dwordx4 v200, v[118:121], s[94:95] offset:256
	s_waitcnt vmcnt(14)
	v_pk_fma_f32 v[110:111], v[110:111], v[86:87], v[218:219]
	v_pk_fma_f32 v[112:113], v[112:113], v[88:89], v[220:221]
	v_pk_fma_f32 v[106:107], v[106:107], v[82:83], v[222:223]
	v_pk_fma_f32 v[108:109], v[108:109], v[84:85], v[224:225]
	s_add_u32 s92, s92, 0x20000
	s_addc_u32 s93, s93, 0
	global_load_dwordx4 v[218:221], v175, s[92:93]
	global_load_dwordx4 v[222:225], v175, s[92:93] offset:16
	s_add_u32 s94, s94, 0x10000
	s_addc_u32 s95, s95, 0
	v_cvt_pk_bf16_f32 v110, v110, v111
	v_cvt_pk_bf16_f32 v111, v112, v113
	v_cvt_pk_bf16_f32 v112, v106, v107
	v_cvt_pk_bf16_f32 v113, v108, v109
	global_store_dwordx4 v200, v[110:113], s[94:95]
	s_waitcnt vmcnt(15)
	v_pk_fma_f32 v[102:103], v[102:103], v[70:71], v[226:227]
	v_pk_fma_f32 v[104:105], v[104:105], v[72:73], v[228:229]
	v_pk_fma_f32 v[98:99], v[98:99], v[66:67], v[230:231]
	v_pk_fma_f32 v[100:101], v[100:101], v[68:69], v[232:233]
	global_load_dwordx4 v[226:229], v175, s[92:93] offset:512
	global_load_dwordx4 v[230:233], v175, s[92:93] offset:528
	v_cvt_pk_bf16_f32 v102, v102, v103
	v_cvt_pk_bf16_f32 v103, v104, v105
	v_cvt_pk_bf16_f32 v104, v98, v99
	v_cvt_pk_bf16_f32 v105, v100, v101
	global_store_dwordx4 v200, v[102:105], s[94:95] offset:256
	s_waitcnt vmcnt(16)
	v_pk_fma_f32 v[94:95], v[94:95], v[86:87], v[176:177]
	v_pk_fma_f32 v[96:97], v[96:97], v[88:89], v[178:179]
	v_pk_fma_f32 v[90:91], v[90:91], v[82:83], v[180:181]
	v_pk_fma_f32 v[92:93], v[92:93], v[84:85], v[182:183]
	s_add_u32 s92, s92, 0x20000
	s_addc_u32 s93, s93, 0
	global_load_dwordx4 v[176:179], v175, s[92:93]
	global_load_dwordx4 v[180:183], v175, s[92:93] offset:16
	s_add_u32 s94, s94, 0x10000
	s_addc_u32 s95, s95, 0
	v_cvt_pk_bf16_f32 v94, v94, v95
	v_cvt_pk_bf16_f32 v95, v96, v97
	v_cvt_pk_bf16_f32 v96, v90, v91
	v_cvt_pk_bf16_f32 v97, v92, v93
	global_store_dwordx4 v200, v[94:97], s[94:95]
	s_waitcnt vmcnt(16)
	v_pk_fma_f32 v[78:79], v[78:79], v[70:71], v[184:185]
	v_pk_fma_f32 v[80:81], v[80:81], v[72:73], v[186:187]
	v_pk_fma_f32 v[74:75], v[74:75], v[66:67], v[188:189]
	v_pk_fma_f32 v[76:77], v[76:77], v[68:69], v[190:191]
	global_load_dwordx4 v[184:187], v175, s[92:93] offset:512
	global_load_dwordx4 v[188:191], v175, s[92:93] offset:528
	v_cvt_pk_bf16_f32 v78, v78, v79
	v_cvt_pk_bf16_f32 v79, v80, v81
	v_cvt_pk_bf16_f32 v80, v74, v75
	v_cvt_pk_bf16_f32 v81, v76, v77
	global_store_dwordx4 v200, v[78:81], s[94:95] offset:256
	s_waitcnt vmcnt(16)
; __device__ __forceinline__ unsigned pk2(float lo, float hi) { f32x2 v = {lo, hi}; return __builtin_bit_cast(unsigned, __builtin_convertvector(v, bf16x2_t)); }
; __device__ __forceinline__ float bf_lo(unsigned w) { return __uint_as_float(w << 16); }
; __device__ __forceinline__ float bf_hi(unsigned w) { return __uint_as_float(w & 0xffff0000u); }
; #define PG8_WAIT_V(n) asm volatile("s_waitcnt vmcnt(" #n ")" ::: "memory")
;     __device__ __forceinline__ void operator()(const f32x4 (&acc)[2][2][4][2], const Unit& u, int wr, int wc, int fr, int fq) const {
;     ...
;         for (int ai = 0; ai < 2; ++ai)
; #pragma unroll
;             for (int m = 0; m < 4; ++m) {
;                 const size_t ro = (size_t)(row0 + ai * HALF + m * 16) * DM + col0;
; #pragma unroll
;                 for (int bj = 0; bj < 2; ++bj) {
;                     f32x4 r0, r1;
;                     if (RB) { const u32x4 rw = *(const u32x4*)((const bf16_t*)resid + ro + bj * HALF);
;                         r0 = (f32x4){bf_lo(rw.x), bf_hi(rw.x), bf_lo(rw.y), bf_hi(rw.y)}; r1 = (f32x4){bf_lo(rw.z), bf_hi(rw.z), bf_lo(rw.w), bf_hi(rw.w)}; }
;                     else { r0 = *(const f32x4*)((const float*)resid + ro + bj * HALF); r1 = *(const f32x4*)((const float*)resid + ro + bj * HALF + 4); }
;                     const f32x4 v0 = r0 + gv[bj][0] * acc[ai][bj][m][0], v1 = r1 + gv[bj][1] * acc[ai][bj][m][1];
;                     if (OB) { u32x4 w; w.x = pk2(v0[0], v0[1]); w.y = pk2(v0[2], v0[3]); w.z = pk2(v1[0], v1[1]); w.w = pk2(v1[2], v1[3]); *(u32x4*)((bf16_t*)out + ro + bj * HALF) = w; }
;                     else { *(f32x4*)((float*)out + ro + bj * HALF) = v0; *(f32x4*)((float*)out + ro + bj * HALF + 4) = v1; }
;                 }
; template <class Epi>
; __device__ __forceinline__ void gemm_phase(LAS unsigned char* lds, const Gemm g, const StaticOrder& S, const Epi& E, const int tid) {
;     ...
;         E(acc, cur, wr, wc, fr, fq);
;         if (!has_next) break;
; #pragma unroll
;         for (int a = 0; a < 2; ++a)
; #pragma unroll
;             for (int b = 0; b < 2; ++b)
; #pragma unroll
;                 for (int m = 0; m < 4; ++m)
; #pragma unroll
;                     for (int n = 0; n < 2; ++n) acc[a][b][m][n] = (f32x4){0.f, 0.f, 0.f, 0.f};
;         cur = nxt; cA = nA; cB = nB; ++ui;
;     }
;     PG8_WAIT_V(0);
;     if (wr == 0) PG8_BAR;
;     PG8_BAR;
	v_pk_fma_f32 v[62:63], v[62:63], v[86:87], v[192:193]
	v_pk_fma_f32 v[64:65], v[64:65], v[88:89], v[194:195]
	v_pk_fma_f32 v[58:59], v[58:59], v[82:83], v[196:197]
	v_pk_fma_f32 v[60:61], v[60:61], v[84:85], v[198:199]
	s_add_u32 s92, s92, 0x20000
	s_addc_u32 s93, s93, 0
	global_load_dwordx4 v[192:195], v175, s[92:93]
	global_load_dwordx4 v[196:199], v175, s[92:93] offset:16
	s_add_u32 s94, s94, 0x50000
	s_addc_u32 s95, s95, 0
	v_cvt_pk_bf16_f32 v62, v62, v63
	v_cvt_pk_bf16_f32 v63, v64, v65
	v_cvt_pk_bf16_f32 v64, v58, v59
	v_cvt_pk_bf16_f32 v65, v60, v61
	global_store_dwordx4 v200, v[62:65], s[94:95]
	s_waitcnt vmcnt(16)
	v_pk_fma_f32 v[54:55], v[54:55], v[70:71], v[210:211]
	v_pk_fma_f32 v[56:57], v[56:57], v[72:73], v[212:213]
	v_pk_fma_f32 v[50:51], v[50:51], v[66:67], v[214:215]
	v_pk_fma_f32 v[52:53], v[52:53], v[68:69], v[216:217]
	global_load_dwordx4 v[210:213], v175, s[92:93] offset:512
	global_load_dwordx4 v[214:217], v175, s[92:93] offset:528
	v_cvt_pk_bf16_f32 v54, v54, v55
	v_cvt_pk_bf16_f32 v55, v56, v57
	v_cvt_pk_bf16_f32 v56, v50, v51
	v_cvt_pk_bf16_f32 v57, v52, v53
	global_store_dwordx4 v200, v[54:57], s[94:95] offset:256
	s_waitcnt vmcnt(16)
	v_pk_fma_f32 v[46:47], v[46:47], v[86:87], v[218:219]
	v_pk_fma_f32 v[48:49], v[48:49], v[88:89], v[220:221]
	v_pk_fma_f32 v[42:43], v[42:43], v[82:83], v[222:223]
	v_pk_fma_f32 v[44:45], v[44:45], v[84:85], v[224:225]
	s_add_u32 s94, s94, 0x10000
	s_addc_u32 s95, s95, 0
	v_cvt_pk_bf16_f32 v46, v46, v47
	v_cvt_pk_bf16_f32 v47, v48, v49
	v_cvt_pk_bf16_f32 v48, v42, v43
	v_cvt_pk_bf16_f32 v49, v44, v45
	global_store_dwordx4 v200, v[46:49], s[94:95]
	s_waitcnt vmcnt(14)
	v_pk_fma_f32 v[38:39], v[38:39], v[70:71], v[226:227]
	v_pk_fma_f32 v[40:41], v[40:41], v[72:73], v[228:229]
	v_pk_fma_f32 v[34:35], v[34:35], v[66:67], v[230:231]
	v_pk_fma_f32 v[36:37], v[36:37], v[68:69], v[232:233]
	v_cvt_pk_bf16_f32 v38, v38, v39
	v_cvt_pk_bf16_f32 v39, v40, v41
	v_cvt_pk_bf16_f32 v40, v34, v35
	v_cvt_pk_bf16_f32 v41, v36, v37
	global_store_dwordx4 v200, v[38:41], s[94:95] offset:256
	s_waitcnt vmcnt(12)
	v_pk_fma_f32 v[30:31], v[30:31], v[86:87], v[176:177]
	v_pk_fma_f32 v[32:33], v[32:33], v[88:89], v[178:179]
	v_pk_fma_f32 v[26:27], v[26:27], v[82:83], v[180:181]
	v_pk_fma_f32 v[28:29], v[28:29], v[84:85], v[182:183]
	s_add_u32 s94, s94, 0x10000
	s_addc_u32 s95, s95, 0
	v_cvt_pk_bf16_f32 v30, v30, v31
	v_cvt_pk_bf16_f32 v31, v32, v33
	v_cvt_pk_bf16_f32 v32, v26, v27
	v_cvt_pk_bf16_f32 v33, v28, v29
	global_store_dwordx4 v200, v[30:33], s[94:95]
	s_waitcnt vmcnt(10)
	v_pk_fma_f32 v[22:23], v[22:23], v[70:71], v[184:185]
	v_pk_fma_f32 v[24:25], v[24:25], v[72:73], v[186:187]
	v_pk_fma_f32 v[18:19], v[18:19], v[66:67], v[188:189]
	v_pk_fma_f32 v[20:21], v[20:21], v[68:69], v[190:191]
	v_cvt_pk_bf16_f32 v22, v22, v23
	v_cvt_pk_bf16_f32 v23, v24, v25
	v_cvt_pk_bf16_f32 v24, v18, v19
	v_cvt_pk_bf16_f32 v25, v20, v21
	global_store_dwordx4 v200, v[22:25], s[94:95] offset:256
	s_waitcnt vmcnt(8)
	v_pk_fma_f32 v[14:15], v[14:15], v[86:87], v[192:193]
	v_pk_fma_f32 v[16:17], v[16:17], v[88:89], v[194:195]
	v_pk_fma_f32 v[10:11], v[10:11], v[82:83], v[196:197]
	v_pk_fma_f32 v[12:13], v[12:13], v[84:85], v[198:199]
	s_add_u32 s94, s94, 0x10000
	s_addc_u32 s95, s95, 0
	v_cvt_pk_bf16_f32 v14, v14, v15
	v_cvt_pk_bf16_f32 v15, v16, v17
	v_cvt_pk_bf16_f32 v16, v10, v11
	v_cvt_pk_bf16_f32 v17, v12, v13
	global_store_dwordx4 v200, v[14:17], s[94:95]
	s_waitcnt vmcnt(6)
	v_pk_fma_f32 v[6:7], v[6:7], v[70:71], v[210:211]
	v_pk_fma_f32 v[8:9], v[8:9], v[72:73], v[212:213]
	v_pk_fma_f32 v[2:3], v[2:3], v[66:67], v[214:215]
	v_pk_fma_f32 v[4:5], v[4:5], v[68:69], v[216:217]
	v_cvt_pk_bf16_f32 v6, v6, v7
	v_cvt_pk_bf16_f32 v7, v8, v9
	v_cvt_pk_bf16_f32 v8, v2, v3
	v_cvt_pk_bf16_f32 v9, v4, v5
	global_store_dwordx4 v200, v[6:9], s[94:95] offset:256
	s_mov_b32 s2, s12
	s_mov_b64 s[20:21], s[14:15]
	s_mov_b64 s[18:19], s[16:17]
	s_and_b64 vcc, exec, s[4:5]
	s_nop 1
	s_cbranch_vccz .LBB0_134
	s_waitcnt vmcnt(0)
	s_cmpk_gt_u32 s29, 0xff
	s_cbranch_scc1 .LBB0_145
	s_barrier

; #define PG8_STAGE(bufoff, gbase, voff) do { _Pragma("unroll") for (int _i = 0; _i < 2; ++_i) \
;         __builtin_amdgcn_global_load_lds((const unsigned*)((const char*)(gbase) + (voff)[_i]), (LAS unsigned*)(lds + (bufoff) + ldsw + _i * 8192), 16, 0, 0); } while (0)
; #define PG8_LDA(dst, b, h) do { _Pragma("unroll") for (int m = 0; m < 4; ++m) _Pragma("unroll") for (int k = 0; k < 2; ++k) dst[m][k] = *(const LAS bf16x8*)(lds + PG8_SA(b, h) + aoff + m * 2048 + k * 1024); } while (0)
; #define PG8_LDB(dst, b, h) do { _Pragma("unroll") for (int n = 0; n < 2; ++n) _Pragma("unroll") for (int k = 0; k < 2; ++k) dst[n][k] = *(const LAS bf16x8*)(lds + PG8_SB(b, h) + boff + n * 2048 + k * 1024); } while (0)
; #define PG8_WAIT_V(n) asm volatile("s_waitcnt vmcnt(" #n ")" ::: "memory")
; #define PG8_WAIT_L(n) asm volatile("s_waitcnt lgkmcnt(" #n ")" ::: "memory")
; #define PG8_BAR __builtin_amdgcn_s_barrier()
; #define PG8_SCHED __builtin_amdgcn_sched_barrier(0)
; template <class Epi>
; __device__ __forceinline__ void gemm_phase(LAS unsigned char* lds, const Gemm g, const StaticOrder& S, const Epi& E, const int tid) {
;     ...
;         const bool has_next = S.next(ui + 1, nxt);
;         const char* nA = has_next ? (const char*)g.A + (size_t)nxt.pm * tstep : cA; const char* nB = has_next ? (const char*)g.Bt + (size_t)nxt.pn * tstep : cB;
;         for (int t = 0; t < nt; t += 2) {
;             const bool last = (t == nt - 2);
;             const char* a1 = cA + (size_t)(t + 1) * kstep;
;             const char* a2 = last ? nA : cA + (size_t)(t + 2) * kstep; const char* b2 = last ? nB : cB + (size_t)(t + 2) * kstep;
;             const char* a3 = a2 + kstep; const char* b3 = b2 + kstep;
;             PG8_LDB(B0, 0, 0); PG8_SCHED; PG8_LDA(At, 0, 0); PG8_STAGE(PG8_SA(1, 1), a1 + hstep, voffA);
;             PG8_WAIT_L(8); PG8_BAR; PG8_WAIT_L(0); PG8_MMA(0, 0, At, B0); PG8_BAR; PG8_SCHED;
;             PG8_LDB(B1, 0, 1); PG8_STAGE(PG8_SB(0, 0), b2, voffB);
;             PG8_BAR; PG8_WAIT_L(0); PG8_MMA(0, 1, At, B1); PG8_BAR;
;             PG8_LDA(At, 0, 1); PG8_STAGE(PG8_SA(0, 0), a2, voffA);
;             PG8_BAR; PG8_WAIT_L(0); PG8_MMA(1, 0, At, B0); PG8_BAR; PG8_SCHED;
;             PG8_STAGE(PG8_SB(0, 1), b2 + hstep, voffB);
;             PG8_WAIT_V(6); PG8_BAR; PG8_MMA(1, 1, At, B1); PG8_BAR;
.Lgprio5:
.LBB0_286:
	s_add_u32 s8, s6, 0xfff80080
	s_addc_u32 s9, s7, -1
	s_add_i32 s37, 0, 0x10000
	v_add_u32_e32 v0, s37, v210
	ds_read_b128 v[130:133], v0
	ds_read_b128 v[134:137], v0 offset:1024
	ds_read_b128 v[138:141], v0 offset:2048
	ds_read_b128 v[142:145], v0 offset:3072
	s_cmp_eq_u32 s36, 28
	s_cselect_b32 s35, s3, s9
	s_cselect_b32 s34, s27, s8
	s_cselect_b32 s9, s25, s72
	s_cselect_b32 s8, s50, s66
	s_add_i32 m0, s21, 0xc000
	ds_read_b128 v[172:175], v211
	ds_read_b128 v[176:179], v211 offset:1024
	ds_read_b128 v[180:183], v211 offset:2048
	ds_read_b128 v[184:187], v211 offset:3072
	ds_read_b128 v[188:191], v211 offset:4096
	ds_read_b128 v[192:195], v211 offset:5120
	ds_read_b128 v[196:199], v211 offset:6144
	ds_read_b128 v[212:215], v211 offset:7168
	global_load_lds_dwordx4 v170, s[6:7]
	s_add_i32 m0, s21, 0xe000
	s_nop 0
	global_load_lds_dwordx4 v168, s[6:7]
	s_waitcnt lgkmcnt(8)
	s_barrier
	s_waitcnt lgkmcnt(0)
	v_mfma_f32_16x16x32_bf16 v[126:129], v[130:133], v[172:175], v[126:129]
	v_mfma_f32_16x16x32_bf16 v[122:125], v[138:141], v[172:175], v[122:125]
	v_mfma_f32_16x16x32_bf16 v[118:121], v[130:133], v[180:183], v[118:121]
	v_mfma_f32_16x16x32_bf16 v[114:117], v[138:141], v[180:183], v[114:117]
	v_mfma_f32_16x16x32_bf16 v[102:105], v[130:133], v[188:191], v[102:105]
	v_mfma_f32_16x16x32_bf16 v[98:101], v[138:141], v[188:191], v[98:101]
	v_mfma_f32_16x16x32_bf16 v[86:89], v[130:133], v[196:199], v[86:89]
	v_mfma_f32_16x16x32_bf16 v[82:85], v[138:141], v[196:199], v[82:85]
	v_mfma_f32_16x16x32_bf16 v[126:129], v[134:137], v[176:179], v[126:129]
	v_mfma_f32_16x16x32_bf16 v[122:125], v[142:145], v[176:179], v[122:125]
	v_mfma_f32_16x16x32_bf16 v[118:121], v[134:137], v[184:187], v[118:121]
	v_mfma_f32_16x16x32_bf16 v[114:117], v[142:145], v[184:187], v[114:117]
	v_mfma_f32_16x16x32_bf16 v[102:105], v[134:137], v[192:195], v[102:105]
	v_mfma_f32_16x16x32_bf16 v[98:101], v[142:145], v[192:195], v[98:101]
	v_mfma_f32_16x16x32_bf16 v[86:89], v[134:137], v[212:215], v[86:89]
	v_mfma_f32_16x16x32_bf16 v[82:85], v[142:145], v[212:215], v[82:85]
	s_barrier
	s_add_i32 s73, 0, 0x14000
	s_add_i32 s37, s37, s39
	v_add_u32_e32 v0, s73, v210
	v_lshl_add_u64 v[200:201], s[8:9], 0, v[162:163]
	s_mov_b32 m0, s37
	ds_read_b128 v[216:219], v0
	ds_read_b128 v[220:223], v0 offset:1024
	ds_read_b128 v[224:227], v0 offset:2048
	ds_read_b128 v[228:231], v0 offset:3072
	global_load_lds_dwordx4 v[200:201], off
	v_lshl_add_u64 v[232:233], s[8:9], 0, v[166:167]
	s_add_i32 m0, s37, 0x2000
	s_nop 0
	global_load_lds_dwordx4 v[232:233], off
	s_barrier
	s_waitcnt lgkmcnt(0)
	v_mfma_f32_16x16x32_bf16 v[110:113], v[216:219], v[172:175], v[110:113]
	v_mfma_f32_16x16x32_bf16 v[106:109], v[224:227], v[172:175], v[106:109]
	v_mfma_f32_16x16x32_bf16 v[94:97], v[216:219], v[180:183], v[94:97]
	v_mfma_f32_16x16x32_bf16 v[90:93], v[224:227], v[180:183], v[90:93]
	v_mfma_f32_16x16x32_bf16 v[78:81], v[216:219], v[188:191], v[78:81]
	v_mfma_f32_16x16x32_bf16 v[74:77], v[224:227], v[188:191], v[74:77]
	v_mfma_f32_16x16x32_bf16 v[70:73], v[216:219], v[196:199], v[70:73]
	v_mfma_f32_16x16x32_bf16 v[66:69], v[224:227], v[196:199], v[66:69]
	v_mfma_f32_16x16x32_bf16 v[110:113], v[220:223], v[176:179], v[110:113]
	v_mfma_f32_16x16x32_bf16 v[106:109], v[228:231], v[176:179], v[106:109]
	v_mfma_f32_16x16x32_bf16 v[94:97], v[220:223], v[184:187], v[94:97]
	v_mfma_f32_16x16x32_bf16 v[90:93], v[228:231], v[184:187], v[90:93]
	v_mfma_f32_16x16x32_bf16 v[78:81], v[220:223], v[192:195], v[78:81]
	v_mfma_f32_16x16x32_bf16 v[74:77], v[228:231], v[192:195], v[74:77]
	v_mfma_f32_16x16x32_bf16 v[70:73], v[220:223], v[212:215], v[70:73]
	v_mfma_f32_16x16x32_bf16 v[66:69], v[228:231], v[212:215], v[66:69]
	s_mov_b32 m0, s21
	v_lshl_add_u64 v[234:235], s[34:35], 0, v[160:161]
	s_barrier
	ds_read_b128 v[172:175], v211 offset:16384
	ds_read_b128 v[176:179], v211 offset:17408
	ds_read_b128 v[180:183], v211 offset:18432
	ds_read_b128 v[184:187], v211 offset:19456
	ds_read_b128 v[188:191], v211 offset:20480
	ds_read_b128 v[192:195], v211 offset:21504
	ds_read_b128 v[196:199], v211 offset:22528
	ds_read_b128 v[212:215], v211 offset:23552
	global_load_lds_dwordx4 v[234:235], off
	v_lshl_add_u64 v[236:237], s[34:35], 0, v[164:165]
	s_mov_b32 m0, s40
	s_nop 0
	global_load_lds_dwordx4 v[236:237], off
	s_barrier
	s_waitcnt lgkmcnt(0)
	v_mfma_f32_16x16x32_bf16 v[62:65], v[130:133], v[172:175], v[62:65]
	v_mfma_f32_16x16x32_bf16 v[58:61], v[138:141], v[172:175], v[58:61]
	v_mfma_f32_16x16x32_bf16 v[54:57], v[130:133], v[180:183], v[54:57]
	v_mfma_f32_16x16x32_bf16 v[50:53], v[138:141], v[180:183], v[50:53]
	v_mfma_f32_16x16x32_bf16 v[38:41], v[130:133], v[188:191], v[38:41]
	v_mfma_f32_16x16x32_bf16 v[34:37], v[138:141], v[188:191], v[34:37]
	v_mfma_f32_16x16x32_bf16 v[22:25], v[130:133], v[196:199], v[22:25]
	v_mfma_f32_16x16x32_bf16 v[18:21], v[138:141], v[196:199], v[18:21]
	v_mfma_f32_16x16x32_bf16 v[62:65], v[134:137], v[176:179], v[62:65]
	v_mfma_f32_16x16x32_bf16 v[58:61], v[142:145], v[176:179], v[58:61]
	v_mfma_f32_16x16x32_bf16 v[54:57], v[134:137], v[184:187], v[54:57]
	v_mfma_f32_16x16x32_bf16 v[50:53], v[142:145], v[184:187], v[50:53]
	v_mfma_f32_16x16x32_bf16 v[38:41], v[134:137], v[192:195], v[38:41]
	v_mfma_f32_16x16x32_bf16 v[34:37], v[142:145], v[192:195], v[34:37]
	v_mfma_f32_16x16x32_bf16 v[22:25], v[134:137], v[212:215], v[22:25]
	v_mfma_f32_16x16x32_bf16 v[18:21], v[142:145], v[212:215], v[18:21]
	s_barrier
	s_add_u32 s74, s8, 0x80000
	s_addc_u32 s75, s9, 0
	s_add_i32 s37, s73, s39
	s_mov_b32 m0, s37
	s_nop 0
	global_load_lds_dwordx4 v162, s[74:75]
	s_add_i32 m0, s37, 0x2000
	s_nop 0
	global_load_lds_dwordx4 v166, s[74:75]
	s_waitcnt vmcnt(6)
	s_barrier
; #define PG8_STAGE(bufoff, gbase, voff) do { _Pragma("unroll") for (int _i = 0; _i < 2; ++_i) \
;         __builtin_amdgcn_global_load_lds((const unsigned*)((const char*)(gbase) + (voff)[_i]), (LAS unsigned*)(lds + (bufoff) + ldsw + _i * 8192), 16, 0, 0); } while (0)
; #define PG8_LDA(dst, b, h) do { _Pragma("unroll") for (int m = 0; m < 4; ++m) _Pragma("unroll") for (int k = 0; k < 2; ++k) dst[m][k] = *(const LAS bf16x8*)(lds + PG8_SA(b, h) + aoff + m * 2048 + k * 1024); } while (0)
; #define PG8_LDB(dst, b, h) do { _Pragma("unroll") for (int n = 0; n < 2; ++n) _Pragma("unroll") for (int k = 0; k < 2; ++k) dst[n][k] = *(const LAS bf16x8*)(lds + PG8_SB(b, h) + boff + n * 2048 + k * 1024); } while (0)
; #define PG8_MMA(ai, bj, At, Bt) do { __builtin_amdgcn_s_setprio(1); _Pragma("unroll") for (int m = 0; m < 4; ++m) _Pragma("unroll") for (int n = 0; n < 2; ++n) _Pragma("unroll") for (int k = 0; k < 2; ++k) \
;         acc[ai][bj][m][n] = __builtin_amdgcn_mfma_f32_16x16x32_bf16(Bt[n][k], At[m][k], acc[ai][bj][m][n], 0, 0, 0); __builtin_amdgcn_s_setprio(0); } while (0)
; #define PG8_WAIT_V(n) asm volatile("s_waitcnt vmcnt(" #n ")" ::: "memory")
; #define PG8_WAIT_L(n) asm volatile("s_waitcnt lgkmcnt(" #n ")" ::: "memory")
; #define PG8_BAR __builtin_amdgcn_s_barrier()
; #define PG8_SCHED __builtin_amdgcn_sched_barrier(0)
; template <class Epi>
; __device__ __forceinline__ void gemm_phase(LAS unsigned char* lds, const Gemm g, const StaticOrder& S, const Epi& E, const int tid) {
;     ...
;             PG8_WAIT_V(6); PG8_BAR; PG8_MMA(1, 1, At, B1); PG8_BAR;
;             PG8_LDB(B0, 1, 0); PG8_SCHED; PG8_LDA(At, 1, 0); PG8_STAGE(PG8_SA(0, 1), a2 + hstep, voffA);
;             PG8_WAIT_L(8); PG8_BAR; PG8_WAIT_L(0); PG8_MMA(0, 0, At, B0); PG8_BAR; PG8_SCHED;
;             PG8_LDB(B1, 1, 1); PG8_STAGE(PG8_SB(1, 0), b3, voffB);
;             PG8_BAR; PG8_WAIT_L(0); PG8_MMA(0, 1, At, B1); PG8_BAR;
;             PG8_LDA(At, 1, 1); PG8_STAGE(PG8_SA(1, 0), a3, voffA);
	v_mfma_f32_16x16x32_bf16 v[46:49], v[216:219], v[172:175], v[46:49]
	v_mfma_f32_16x16x32_bf16 v[42:45], v[224:227], v[172:175], v[42:45]
	v_mfma_f32_16x16x32_bf16 v[30:33], v[216:219], v[180:183], v[30:33]
	v_mfma_f32_16x16x32_bf16 v[26:29], v[224:227], v[180:183], v[26:29]
	v_mfma_f32_16x16x32_bf16 v[14:17], v[216:219], v[188:191], v[14:17]
	v_mfma_f32_16x16x32_bf16 v[10:13], v[224:227], v[188:191], v[10:13]
	v_mfma_f32_16x16x32_bf16 v[6:9], v[216:219], v[196:199], v[6:9]
	v_mfma_f32_16x16x32_bf16 v[2:5], v[224:227], v[196:199], v[2:5]
	v_mfma_f32_16x16x32_bf16 v[46:49], v[220:223], v[176:179], v[46:49]
	v_mfma_f32_16x16x32_bf16 v[42:45], v[228:231], v[176:179], v[42:45]
	v_mfma_f32_16x16x32_bf16 v[30:33], v[220:223], v[184:187], v[30:33]
	v_mfma_f32_16x16x32_bf16 v[26:29], v[228:231], v[184:187], v[26:29]
	v_mfma_f32_16x16x32_bf16 v[14:17], v[220:223], v[192:195], v[14:17]
	v_mfma_f32_16x16x32_bf16 v[10:13], v[228:231], v[192:195], v[10:13]
	v_mfma_f32_16x16x32_bf16 v[6:9], v[220:223], v[212:215], v[6:9]
	v_mfma_f32_16x16x32_bf16 v[2:5], v[228:231], v[212:215], v[2:5]
	s_add_i32 s37, 0, 0x18000
	v_add_u32_e32 v0, s37, v210
	s_barrier
	ds_read_b128 v[130:133], v0
	ds_read_b128 v[134:137], v0 offset:1024
	ds_read_b128 v[138:141], v0 offset:2048
	ds_read_b128 v[142:145], v0 offset:3072
	s_add_u32 s34, s34, 0x80000
	s_addc_u32 s35, s35, 0
	s_mov_b32 m0, s41
	ds_read_b128 v[172:175], v211 offset:32768
	ds_read_b128 v[176:179], v211 offset:33792
	ds_read_b128 v[180:183], v211 offset:34816
	ds_read_b128 v[184:187], v211 offset:35840
	ds_read_b128 v[188:191], v211 offset:36864
	ds_read_b128 v[192:195], v211 offset:37888
	ds_read_b128 v[196:199], v211 offset:38912
	ds_read_b128 v[212:215], v211 offset:39936
	global_load_lds_dwordx4 v160, s[34:35]
	s_mov_b32 m0, s42
	s_nop 0
	global_load_lds_dwordx4 v164, s[34:35]
	s_waitcnt lgkmcnt(8)
	s_barrier
	s_waitcnt lgkmcnt(0)
	v_mfma_f32_16x16x32_bf16 v[126:129], v[130:133], v[172:175], v[126:129]
	v_mfma_f32_16x16x32_bf16 v[122:125], v[138:141], v[172:175], v[122:125]
	v_mfma_f32_16x16x32_bf16 v[118:121], v[130:133], v[180:183], v[118:121]
	v_mfma_f32_16x16x32_bf16 v[114:117], v[138:141], v[180:183], v[114:117]
	v_mfma_f32_16x16x32_bf16 v[102:105], v[130:133], v[188:191], v[102:105]
	v_mfma_f32_16x16x32_bf16 v[98:101], v[138:141], v[188:191], v[98:101]
	v_mfma_f32_16x16x32_bf16 v[86:89], v[130:133], v[196:199], v[86:89]
	v_mfma_f32_16x16x32_bf16 v[82:85], v[138:141], v[196:199], v[82:85]
	v_mfma_f32_16x16x32_bf16 v[126:129], v[134:137], v[176:179], v[126:129]
	v_mfma_f32_16x16x32_bf16 v[122:125], v[142:145], v[176:179], v[122:125]
	v_mfma_f32_16x16x32_bf16 v[118:121], v[134:137], v[184:187], v[118:121]
	v_mfma_f32_16x16x32_bf16 v[114:117], v[142:145], v[184:187], v[114:117]
	v_mfma_f32_16x16x32_bf16 v[102:105], v[134:137], v[192:195], v[102:105]
	v_mfma_f32_16x16x32_bf16 v[98:101], v[142:145], v[192:195], v[98:101]
	v_mfma_f32_16x16x32_bf16 v[86:89], v[134:137], v[212:215], v[86:89]
	v_mfma_f32_16x16x32_bf16 v[82:85], v[142:145], v[212:215], v[82:85]
	s_barrier
	s_add_i32 s34, 0, 0x1c000
	s_add_i32 s35, s37, s39
	v_add_u32_e32 v0, s34, v210
	v_lshl_add_u64 v[200:201], v[200:201], 0, s[56:57]
	s_mov_b32 m0, s35
	ds_read_b128 v[216:219], v0
	ds_read_b128 v[220:223], v0 offset:1024
	ds_read_b128 v[224:227], v0 offset:2048
	ds_read_b128 v[228:231], v0 offset:3072
	global_load_lds_dwordx4 v[200:201], off
	v_lshl_add_u64 v[200:201], v[232:233], 0, s[56:57]
	s_add_i32 m0, s35, 0x2000
	s_nop 0
	global_load_lds_dwordx4 v[200:201], off
	s_barrier
	s_waitcnt lgkmcnt(0)
	v_mfma_f32_16x16x32_bf16 v[110:113], v[216:219], v[172:175], v[110:113]
	v_mfma_f32_16x16x32_bf16 v[106:109], v[224:227], v[172:175], v[106:109]
	v_mfma_f32_16x16x32_bf16 v[94:97], v[216:219], v[180:183], v[94:97]
	v_mfma_f32_16x16x32_bf16 v[90:93], v[224:227], v[180:183], v[90:93]
	v_mfma_f32_16x16x32_bf16 v[78:81], v[216:219], v[188:191], v[78:81]
	v_mfma_f32_16x16x32_bf16 v[74:77], v[224:227], v[188:191], v[74:77]
	v_mfma_f32_16x16x32_bf16 v[70:73], v[216:219], v[196:199], v[70:73]
	v_mfma_f32_16x16x32_bf16 v[66:69], v[224:227], v[196:199], v[66:69]
	v_mfma_f32_16x16x32_bf16 v[110:113], v[220:223], v[176:179], v[110:113]
	v_mfma_f32_16x16x32_bf16 v[106:109], v[228:231], v[176:179], v[106:109]
	v_mfma_f32_16x16x32_bf16 v[94:97], v[220:223], v[184:187], v[94:97]
	v_mfma_f32_16x16x32_bf16 v[90:93], v[228:231], v[184:187], v[90:93]
	v_mfma_f32_16x16x32_bf16 v[78:81], v[220:223], v[192:195], v[78:81]
	v_mfma_f32_16x16x32_bf16 v[74:77], v[228:231], v[192:195], v[74:77]
	v_mfma_f32_16x16x32_bf16 v[70:73], v[220:223], v[212:215], v[70:73]
	v_mfma_f32_16x16x32_bf16 v[66:69], v[228:231], v[212:215], v[66:69]
	s_mov_b32 m0, s49
	v_lshl_add_u64 v[200:201], v[234:235], 0, s[56:57]
	s_barrier
; __device__ __forceinline__ unsigned pk2(float lo, float hi) { f32x2 v = {lo, hi}; return __builtin_bit_cast(unsigned, __builtin_convertvector(v, bf16x2_t)); }
; #define PG8_STAGE(bufoff, gbase, voff) do { _Pragma("unroll") for (int _i = 0; _i < 2; ++_i) \
;         __builtin_amdgcn_global_load_lds((const unsigned*)((const char*)(gbase) + (voff)[_i]), (LAS unsigned*)(lds + (bufoff) + ldsw + _i * 8192), 16, 0, 0); } while (0)
;     __device__ __forceinline__ void operator()(const f32x4 (&acc)[2][2][4][2], const Unit& u, int wr, int wc, int fr, int fq) const {
;     ...
;         const int type = (u.pn >> 2) % 3, grp = u.pn / 12;
;         const int row0 = u.pm * BM + wr * 64 + fr, col0 = u.pn * BM + wc * 32 + 8 * fq;
;         if (type == 2) {
; #pragma unroll
;             for (int ai = 0; ai < 2; ++ai)
; #pragma unroll
;                 for (int m = 0; m < 4; ++m) {
;                     bf16_t* rowp = O + ((size_t)(2 * u.pn) * MTOK + (row0 + ai * HALF + m * 16)) * 128 + wc * 32 + 8 * fq;
; #pragma unroll
;                     for (int bj = 0; bj < 2; ++bj) { const f32x4 v0 = acc[ai][bj][m][0], v1 = acc[ai][bj][m][1];
;                         u32x4 w; w.x = pk2(v0[0], v0[1]); w.y = pk2(v0[2], v0[3]); w.z = pk2(v1[0], v1[1]); w.w = pk2(v1[2], v1[3]); *(u32x4*)(rowp + (size_t)bj * MTOK * 128) = w; }
;                 }
;             return;
;         }
; #pragma unroll
;         for (int ai = 0; ai < 2; ++ai)
; #pragma unroll
;             for (int m = 0; m < 4; ++m)
; #pragma unroll
;                 for (int bj = 0; bj < 2; ++bj) {
;                     const f32x4 a = acc[ai][bj][m][0], b = acc[ai][bj][m][1];
;                     float s = (a[0] * a[0] + a[1] * a[1]) + (a[2] * a[2] + a[3] * a[3]) + (b[0] * b[0] + b[1] * b[1]) + (b[2] * b[2] + b[3] * b[3]);
;                     s += __shfl_xor(s, 16); s += __shfl_xor(s, 32);
;                     if (fq == 0) T[((wr * 128 + ai * 64 + m * 16 + fr) * 2 + bj) * 4 + wc] = s;
; template <class Epi>
; __device__ __forceinline__ void gemm_phase(LAS unsigned char* lds, const Gemm g, const StaticOrder& S, const Epi& E, const int tid) {
;     ...
;             PG8_LDA(At, 1, 1); PG8_STAGE(PG8_SA(1, 0), a3, voffA);
;             PG8_BAR; PG8_WAIT_L(0); PG8_MMA(1, 0, At, B0); PG8_BAR; PG8_SCHED;
;             PG8_STAGE(PG8_SB(1, 1), b3 + hstep, voffB);
;             PG8_WAIT_V(6); PG8_BAR; PG8_MMA(1, 1, At, B1); PG8_BAR;
	ds_read_b128 v[172:175], v211 offset:49152
	ds_read_b128 v[176:179], v211 offset:50176
	ds_read_b128 v[180:183], v211 offset:51200
	ds_read_b128 v[184:187], v211 offset:52224
	ds_read_b128 v[188:191], v211 offset:53248
	ds_read_b128 v[192:195], v211 offset:54272
	ds_read_b128 v[196:199], v211 offset:55296
	ds_read_b128 v[212:215], v211 offset:56320
	global_load_lds_dwordx4 v[200:201], off
	v_lshl_add_u64 v[200:201], v[236:237], 0, s[56:57]
	s_mov_b32 m0, s52
	s_nop 0
	global_load_lds_dwordx4 v[200:201], off
	s_barrier
	s_waitcnt lgkmcnt(0)
	v_mfma_f32_16x16x32_bf16 v[62:65], v[130:133], v[172:175], v[62:65]
	v_mfma_f32_16x16x32_bf16 v[58:61], v[138:141], v[172:175], v[58:61]
	v_mfma_f32_16x16x32_bf16 v[54:57], v[130:133], v[180:183], v[54:57]
	v_mfma_f32_16x16x32_bf16 v[50:53], v[138:141], v[180:183], v[50:53]
	v_mfma_f32_16x16x32_bf16 v[38:41], v[130:133], v[188:191], v[38:41]
	v_mfma_f32_16x16x32_bf16 v[34:37], v[138:141], v[188:191], v[34:37]
	v_mfma_f32_16x16x32_bf16 v[22:25], v[130:133], v[196:199], v[22:25]
	v_mfma_f32_16x16x32_bf16 v[18:21], v[138:141], v[196:199], v[18:21]
	v_mfma_f32_16x16x32_bf16 v[62:65], v[134:137], v[176:179], v[62:65]
	v_mfma_f32_16x16x32_bf16 v[58:61], v[142:145], v[176:179], v[58:61]
	v_mfma_f32_16x16x32_bf16 v[54:57], v[134:137], v[184:187], v[54:57]
	v_mfma_f32_16x16x32_bf16 v[50:53], v[142:145], v[184:187], v[50:53]
	v_mfma_f32_16x16x32_bf16 v[38:41], v[134:137], v[192:195], v[38:41]
	v_mfma_f32_16x16x32_bf16 v[34:37], v[142:145], v[192:195], v[34:37]
	v_mfma_f32_16x16x32_bf16 v[22:25], v[134:137], v[212:215], v[22:25]
	v_mfma_f32_16x16x32_bf16 v[18:21], v[142:145], v[212:215], v[18:21]
	s_barrier
	s_add_u32 s8, s8, 0x80080
	s_addc_u32 s9, s9, 0
	s_add_i32 s34, s34, s39
	s_mov_b32 m0, s34
	s_nop 0
	global_load_lds_dwordx4 v162, s[8:9]
	s_add_i32 m0, s34, 0x2000
	s_nop 0
	global_load_lds_dwordx4 v166, s[8:9]
	s_waitcnt vmcnt(6)
	s_barrier
	v_mfma_f32_16x16x32_bf16 v[46:49], v[216:219], v[172:175], v[46:49]
	v_mfma_f32_16x16x32_bf16 v[42:45], v[224:227], v[172:175], v[42:45]
	v_mfma_f32_16x16x32_bf16 v[30:33], v[216:219], v[180:183], v[30:33]
	v_mfma_f32_16x16x32_bf16 v[26:29], v[224:227], v[180:183], v[26:29]
	v_mfma_f32_16x16x32_bf16 v[14:17], v[216:219], v[188:191], v[14:17]
	v_mfma_f32_16x16x32_bf16 v[10:13], v[224:227], v[188:191], v[10:13]
	v_mfma_f32_16x16x32_bf16 v[6:9], v[216:219], v[196:199], v[6:9]
	v_mfma_f32_16x16x32_bf16 v[2:5], v[224:227], v[196:199], v[2:5]
	v_mfma_f32_16x16x32_bf16 v[46:49], v[220:223], v[176:179], v[46:49]
	v_mfma_f32_16x16x32_bf16 v[42:45], v[228:231], v[176:179], v[42:45]
	v_mfma_f32_16x16x32_bf16 v[30:33], v[220:223], v[184:187], v[30:33]
	v_mfma_f32_16x16x32_bf16 v[26:29], v[228:231], v[184:187], v[26:29]
	v_mfma_f32_16x16x32_bf16 v[14:17], v[220:223], v[192:195], v[14:17]
	v_mfma_f32_16x16x32_bf16 v[10:13], v[228:231], v[192:195], v[10:13]
	v_mfma_f32_16x16x32_bf16 v[6:9], v[220:223], v[212:215], v[6:9]
	v_mfma_f32_16x16x32_bf16 v[2:5], v[228:231], v[212:215], v[2:5]
	s_add_i32 s36, s36, 2
	s_add_u32 s66, s66, 0x100
	s_addc_u32 s72, s72, 0
	s_add_u32 s6, s6, 0x100
	s_addc_u32 s7, s7, 0
	s_cmp_gt_u32 s36, 29
	s_barrier
	s_cbranch_scc0 .LBB0_286
	s_setprio 0
	s_ashr_i32 s3, s20, 2
	s_mul_hi_i32 s6, s3, 0x55555556
	s_lshr_b32 s7, s6, 31
	s_add_i32 s6, s6, s7
	s_mul_i32 s6, s6, 3
	s_lshl_b32 s2, s2, 8
	v_mov_b32_e32 v138, v159
	v_mov_b32_e32 v0, v209
	s_sub_i32 s6, s3, s6
	s_add_i32 s2, s2, s47
	s_cmp_eq_u32 s6, 2
	v_add_u32_e32 v174, s2, v138
	v_lshlrev_b32_e32 v172, 3, v0
	s_mov_b64 s[2:3], -1
	s_cbranch_scc1 .LBB0_376
	v_mul_f32_e32 v132, v127, v127
	v_mul_f32_e32 v133, v129, v129
	v_fmac_f32_e32 v132, v126, v126
	v_fmac_f32_e32 v133, v128, v128
	v_and_b32_e32 v131, 64, v204
	v_add_f32_e32 v132, v132, v133
	v_mul_f32_e32 v133, v123, v123
	v_xor_b32_e32 v130, 16, v204
	v_add_u32_e32 v131, 64, v131
	v_fmac_f32_e32 v133, v122, v122
	v_cmp_lt_i32_e32 vcc, v130, v131
	v_add_f32_e32 v132, v132, v133
	v_mul_f32_e32 v133, v125, v125
	v_cndmask_b32_e32 v130, v204, v130, vcc
	v_fmac_f32_e32 v133, v124, v124
	v_lshlrev_b32_e32 v130, 2, v130
	v_add_f32_e32 v132, v133, v132
	ds_bpermute_b32 v133, v130, v132
	v_xor_b32_e32 v134, 32, v204
	v_cmp_lt_i32_e32 vcc, v134, v131
	v_lshlrev_b32_e32 v175, 5, v138
	s_waitcnt lgkmcnt(0)
	v_add_f32_e32 v132, v132, v133
	v_cndmask_b32_e32 v131, v204, v134, vcc
	v_lshlrev_b32_e32 v212, 2, v131
	ds_bpermute_b32 v133, v212, v132
	v_cmp_eq_u32_e32 vcc, 0, v0
	v_add_u32_e32 v131, s63, v175
	s_and_saveexec_b64 s[2:3], vcc
	s_cbranch_execz .LBB0_290
	s_waitcnt lgkmcnt(0)
	v_add_f32_e32 v132, v132, v133
	ds_write_b32 v131, v132
